# v27 + residual/base loads of the P3, P7, P9 epilogues hoisted into a counted-vmcnt prefetch ring (global_ loads, 6-16 in flight per wave)
# speedup vs baseline: 1.0074x; 1.0074x over previous
; #define PG8_STAGE(bufoff, gbase, voff) do { _Pragma("unroll") for (int _i = 0; _i < 2; ++_i) \
;         __builtin_amdgcn_global_load_lds((const unsigned*)((const char*)(gbase) + (voff)[_i]), (PG8_LAS unsigned*)(lds + (bufoff) + ldsw + _i * 8192), 16, 0, 0); } while (0)
; #define PG8_LDA(dst, b, h) do { _Pragma("unroll") for (int m = 0; m < 4; ++m) _Pragma("unroll") for (int k = 0; k < 2; ++k) dst[m][k] = *(const PG8_LAS bf16x8*)(lds + PG8_SA(b, h) + aoff + m * 2048 + k * 1024); } while (0)
; #define PG8_LDB(dst, b, h) do { _Pragma("unroll") for (int n = 0; n < 2; ++n) _Pragma("unroll") for (int k = 0; k < 2; ++k) dst[n][k] = *(const PG8_LAS bf16x8*)(lds + PG8_SB(b, h) + boff + n * 2048 + k * 1024); } while (0)
; #define PG8_MMA(ai, bj, At, Bt) do { __builtin_amdgcn_s_setprio(1); _Pragma("unroll") for (int m = 0; m < 4; ++m) _Pragma("unroll") for (int n = 0; n < 2; ++n) _Pragma("unroll") for (int k = 0; k < 2; ++k) \
;         acc[ai][bj][m][n] = __builtin_amdgcn_mfma_f32_16x16x32_bf16(Bt[n][k], At[m][k], acc[ai][bj][m][n], 0, 0, 0); __builtin_amdgcn_s_setprio(0); } while (0)
; #define PG8_WAIT_V(n) asm volatile("s_waitcnt vmcnt(" #n ")" ::: "memory")
; #define PG8_WAIT_L(n) asm volatile("s_waitcnt lgkmcnt(" #n ")" ::: "memory")
; #define PG8_BAR __builtin_amdgcn_s_barrier()
; #define PG8_SCHED __builtin_amdgcn_sched_barrier(0)
; template <class Epi, class Sched>
; __device__ __forceinline__ void gemm_phase(PG8_LAS unsigned char* lds, PG8_LAS unsigned char* xl, const Gemm g, const Sched& S, const Epi& E) {
;     ...
;             PG8_LDB(B0, 0, 0); PG8_LDB(B1, 0, 1); PG8_SCHED; PG8_LDA(At, 0, 0); PG8_STAGE(PG8_SA(1, 1), a1 + hsA, voffA);
;             PG8_WAIT_V(8); PG8_WAIT_L(0); PG8_BAR; PG8_MMA(0, 0, At, B0); PG8_MMA(0, 1, At, B1); PG8_BAR; PG8_SCHED;
;             PG8_LDA(At, 0, 1); PG8_STAGE(PG8_SB(0, 0), b2, voffB); PG8_STAGE(PG8_SB(0, 1), b2 + hsB, voffB); PG8_STAGE(PG8_SA(0, 0), a2, voffA);
;             PG8_WAIT_V(8); PG8_WAIT_L(0); PG8_BAR; PG8_MMA(1, 0, At, B0); PG8_MMA(1, 1, At, B1); PG8_BAR; PG8_SCHED;
.LBB0_471:
	ds_read_b128 v[168:171], v156
	ds_read_b128 v[172:175], v156 offset:1024
	ds_read_b128 v[180:183], v156 offset:2048
	ds_read_b128 v[184:187], v156 offset:3072
	ds_read_b128 v[188:191], v157
	ds_read_b128 v[192:195], v157 offset:1024
	ds_read_b128 v[196:199], v157 offset:2048
	ds_read_b128 v[200:203], v157 offset:3072
	s_add_u32 s34, s30, 0xfffc0080
	s_addc_u32 s35, s31, -1
	s_cmp_eq_u32 s74, 12
	s_cselect_b32 s37, s33, s35
	s_cselect_b32 s36, s46, s34
	s_cselect_b32 s35, s47, s73
	s_cselect_b32 s34, s70, s72
	v_lshl_add_u64 v[144:145], s[30:31], 0, v[138:139]
	s_add_i32 m0, s56, 0xc000
	ds_read_b128 v[204:207], v158
	ds_read_b128 v[208:211], v158 offset:1024
	ds_read_b128 v[212:215], v158 offset:2048
	ds_read_b128 v[216:219], v158 offset:3072
	ds_read_b128 v[222:225], v158 offset:4096
	ds_read_b128 v[226:229], v158 offset:5120
	ds_read_b128 v[230:233], v158 offset:6144
	ds_read_b128 v[234:237], v158 offset:7168
	global_load_lds_dwordx4 v[144:145], off
	v_lshl_add_u64 v[144:145], s[30:31], 0, v[136:137]
	s_add_i32 m0, s56, 0xe000
	s_nop 0
	global_load_lds_dwordx4 v[144:145], off
	s_waitcnt vmcnt(8)
	s_waitcnt lgkmcnt(0)
	s_barrier
	s_setprio 1
	s_waitcnt lgkmcnt(0)
	v_mfma_f32_16x16x32_bf16 v[124:127], v[168:171], v[204:207], v[124:127]
	v_mfma_f32_16x16x32_bf16 v[120:123], v[180:183], v[204:207], v[120:123]
	v_mfma_f32_16x16x32_bf16 v[108:111], v[168:171], v[212:215], v[108:111]
	v_mfma_f32_16x16x32_bf16 v[104:107], v[180:183], v[212:215], v[104:107]
	v_mfma_f32_16x16x32_bf16 v[92:95], v[168:171], v[222:225], v[92:95]
	v_mfma_f32_16x16x32_bf16 v[88:91], v[180:183], v[222:225], v[88:91]
	v_mfma_f32_16x16x32_bf16 v[76:79], v[168:171], v[230:233], v[76:79]
	v_mfma_f32_16x16x32_bf16 v[72:75], v[180:183], v[230:233], v[72:75]
	v_mfma_f32_16x16x32_bf16 v[124:127], v[172:175], v[208:211], v[124:127]
	v_mfma_f32_16x16x32_bf16 v[120:123], v[184:187], v[208:211], v[120:123]
	v_mfma_f32_16x16x32_bf16 v[108:111], v[172:175], v[216:219], v[108:111]
	v_mfma_f32_16x16x32_bf16 v[104:107], v[184:187], v[216:219], v[104:107]
	v_mfma_f32_16x16x32_bf16 v[92:95], v[172:175], v[226:229], v[92:95]
	v_mfma_f32_16x16x32_bf16 v[88:91], v[184:187], v[226:229], v[88:91]
	v_mfma_f32_16x16x32_bf16 v[76:79], v[172:175], v[234:237], v[76:79]
	v_mfma_f32_16x16x32_bf16 v[72:75], v[184:187], v[234:237], v[72:75]
	s_setprio 0
	s_setprio 1
	v_mfma_f32_16x16x32_bf16 v[116:119], v[188:191], v[204:207], v[116:119]
	v_mfma_f32_16x16x32_bf16 v[112:115], v[196:199], v[204:207], v[112:115]
	v_mfma_f32_16x16x32_bf16 v[100:103], v[188:191], v[212:215], v[100:103]
	v_mfma_f32_16x16x32_bf16 v[96:99], v[196:199], v[212:215], v[96:99]
	v_mfma_f32_16x16x32_bf16 v[84:87], v[188:191], v[222:225], v[84:87]
	v_mfma_f32_16x16x32_bf16 v[80:83], v[196:199], v[222:225], v[80:83]
	v_mfma_f32_16x16x32_bf16 v[68:71], v[188:191], v[230:233], v[68:71]
	v_mfma_f32_16x16x32_bf16 v[64:67], v[196:199], v[230:233], v[64:67]
	v_mfma_f32_16x16x32_bf16 v[116:119], v[192:195], v[208:211], v[116:119]
	v_mfma_f32_16x16x32_bf16 v[112:115], v[200:203], v[208:211], v[112:115]
	v_mfma_f32_16x16x32_bf16 v[100:103], v[192:195], v[216:219], v[100:103]
	v_mfma_f32_16x16x32_bf16 v[96:99], v[200:203], v[216:219], v[96:99]
	v_mfma_f32_16x16x32_bf16 v[84:87], v[192:195], v[226:229], v[84:87]
	v_mfma_f32_16x16x32_bf16 v[80:83], v[200:203], v[226:229], v[80:83]
	v_mfma_f32_16x16x32_bf16 v[68:71], v[192:195], v[234:237], v[68:71]
	v_mfma_f32_16x16x32_bf16 v[64:67], v[200:203], v[234:237], v[64:67]
	s_setprio 0
	s_barrier
	s_add_i32 s68, s64, s55
	v_lshl_add_u64 v[144:145], s[34:35], 0, v[130:131]
	s_mov_b32 m0, s68
	ds_read_b128 v[204:207], v158 offset:16384
	ds_read_b128 v[208:211], v158 offset:17408
	ds_read_b128 v[212:215], v158 offset:18432
	ds_read_b128 v[216:219], v158 offset:19456
	ds_read_b128 v[222:225], v158 offset:20480
	ds_read_b128 v[226:229], v158 offset:21504
	ds_read_b128 v[230:233], v158 offset:22528
	ds_read_b128 v[234:237], v158 offset:23552
	global_load_lds_dwordx4 v[144:145], off
	s_add_i32 m0, s68, 0x2000
	s_add_u32 s76, s34, 0x40000
	v_lshl_add_u64 v[176:177], s[34:35], 0, v[134:135]
	s_addc_u32 s77, s35, 0
	s_add_i32 s68, s65, s55
	global_load_lds_dwordx4 v[176:177], off
	v_lshl_add_u64 v[238:239], s[76:77], 0, v[130:131]
	s_mov_b32 m0, s68
	v_lshl_add_u64 v[240:241], s[36:37], 0, v[132:133]
	global_load_lds_dwordx4 v[238:239], off
	v_lshl_add_u64 v[238:239], s[76:77], 0, v[134:135]
	s_add_i32 m0, s68, 0x2000
	s_nop 0
	global_load_lds_dwordx4 v[238:239], off
	v_lshl_add_u64 v[238:239], s[36:37], 0, v[128:129]
	s_mov_b32 m0, s56
	s_nop 0
	global_load_lds_dwordx4 v[238:239], off
	s_mov_b32 m0, s57
	s_nop 0
	global_load_lds_dwordx4 v[240:241], off
	s_waitcnt vmcnt(8)
	s_waitcnt lgkmcnt(0)
	s_barrier
; #define PG8_STAGE(bufoff, gbase, voff) do { _Pragma("unroll") for (int _i = 0; _i < 2; ++_i) \
;         __builtin_amdgcn_global_load_lds((const unsigned*)((const char*)(gbase) + (voff)[_i]), (PG8_LAS unsigned*)(lds + (bufoff) + ldsw + _i * 8192), 16, 0, 0); } while (0)
; #define PG8_LDA(dst, b, h) do { _Pragma("unroll") for (int m = 0; m < 4; ++m) _Pragma("unroll") for (int k = 0; k < 2; ++k) dst[m][k] = *(const PG8_LAS bf16x8*)(lds + PG8_SA(b, h) + aoff + m * 2048 + k * 1024); } while (0)
; #define PG8_LDB(dst, b, h) do { _Pragma("unroll") for (int n = 0; n < 2; ++n) _Pragma("unroll") for (int k = 0; k < 2; ++k) dst[n][k] = *(const PG8_LAS bf16x8*)(lds + PG8_SB(b, h) + boff + n * 2048 + k * 1024); } while (0)
; #define PG8_MMA(ai, bj, At, Bt) do { __builtin_amdgcn_s_setprio(1); _Pragma("unroll") for (int m = 0; m < 4; ++m) _Pragma("unroll") for (int n = 0; n < 2; ++n) _Pragma("unroll") for (int k = 0; k < 2; ++k) \
;         acc[ai][bj][m][n] = __builtin_amdgcn_mfma_f32_16x16x32_bf16(Bt[n][k], At[m][k], acc[ai][bj][m][n], 0, 0, 0); __builtin_amdgcn_s_setprio(0); } while (0)
; #define PG8_WAIT_V(n) asm volatile("s_waitcnt vmcnt(" #n ")" ::: "memory")
; #define PG8_WAIT_L(n) asm volatile("s_waitcnt lgkmcnt(" #n ")" ::: "memory")
; #define PG8_BAR __builtin_amdgcn_s_barrier()
; #define PG8_SCHED __builtin_amdgcn_sched_barrier(0)
; template <class Epi, class Sched>
; __device__ __forceinline__ void gemm_phase(PG8_LAS unsigned char* lds, PG8_LAS unsigned char* xl, const Gemm g, const Sched& S, const Epi& E) {
;     ...
;             PG8_WAIT_V(8); PG8_WAIT_L(0); PG8_BAR; PG8_MMA(1, 0, At, B0); PG8_MMA(1, 1, At, B1); PG8_BAR; PG8_SCHED;
;             PG8_LDB(B0, 1, 0); PG8_LDB(B1, 1, 1); PG8_SCHED; PG8_LDA(At, 1, 0); PG8_STAGE(PG8_SA(0, 1), a2 + hsA, voffA);
;             PG8_WAIT_V(8); PG8_WAIT_L(0); PG8_BAR; PG8_MMA(0, 0, At, B0); PG8_MMA(0, 1, At, B1); PG8_BAR; PG8_SCHED;
	s_setprio 1
	s_waitcnt lgkmcnt(0)
	v_mfma_f32_16x16x32_bf16 v[60:63], v[168:171], v[204:207], v[60:63]
	v_mfma_f32_16x16x32_bf16 v[56:59], v[180:183], v[204:207], v[56:59]
	v_mfma_f32_16x16x32_bf16 v[44:47], v[168:171], v[212:215], v[44:47]
	v_mfma_f32_16x16x32_bf16 v[40:43], v[180:183], v[212:215], v[40:43]
	v_mfma_f32_16x16x32_bf16 v[28:31], v[168:171], v[222:225], v[28:31]
	v_mfma_f32_16x16x32_bf16 v[24:27], v[180:183], v[222:225], v[24:27]
	v_mfma_f32_16x16x32_bf16 v[12:15], v[168:171], v[230:233], v[12:15]
	v_mfma_f32_16x16x32_bf16 v[8:11], v[180:183], v[230:233], v[8:11]
	v_mfma_f32_16x16x32_bf16 v[60:63], v[172:175], v[208:211], v[60:63]
	v_mfma_f32_16x16x32_bf16 v[56:59], v[184:187], v[208:211], v[56:59]
	v_mfma_f32_16x16x32_bf16 v[44:47], v[172:175], v[216:219], v[44:47]
	v_mfma_f32_16x16x32_bf16 v[40:43], v[184:187], v[216:219], v[40:43]
	v_mfma_f32_16x16x32_bf16 v[28:31], v[172:175], v[226:229], v[28:31]
	v_mfma_f32_16x16x32_bf16 v[24:27], v[184:187], v[226:229], v[24:27]
	v_mfma_f32_16x16x32_bf16 v[12:15], v[172:175], v[234:237], v[12:15]
	v_mfma_f32_16x16x32_bf16 v[8:11], v[184:187], v[234:237], v[8:11]
	s_setprio 0
	s_setprio 1
	v_mfma_f32_16x16x32_bf16 v[52:55], v[188:191], v[204:207], v[52:55]
	v_mfma_f32_16x16x32_bf16 v[48:51], v[196:199], v[204:207], v[48:51]
	v_mfma_f32_16x16x32_bf16 v[36:39], v[188:191], v[212:215], v[36:39]
	v_mfma_f32_16x16x32_bf16 v[32:35], v[196:199], v[212:215], v[32:35]
	v_mfma_f32_16x16x32_bf16 v[20:23], v[188:191], v[222:225], v[20:23]
	v_mfma_f32_16x16x32_bf16 v[16:19], v[196:199], v[222:225], v[16:19]
	v_mfma_f32_16x16x32_bf16 v[4:7], v[188:191], v[230:233], v[4:7]
	v_mfma_f32_16x16x32_bf16 v[0:3], v[196:199], v[230:233], v[0:3]
	v_mfma_f32_16x16x32_bf16 v[52:55], v[192:195], v[208:211], v[52:55]
	v_mfma_f32_16x16x32_bf16 v[48:51], v[200:203], v[208:211], v[48:51]
	v_mfma_f32_16x16x32_bf16 v[36:39], v[192:195], v[216:219], v[36:39]
	v_mfma_f32_16x16x32_bf16 v[32:35], v[200:203], v[216:219], v[32:35]
	v_mfma_f32_16x16x32_bf16 v[20:23], v[192:195], v[226:229], v[20:23]
	v_mfma_f32_16x16x32_bf16 v[16:19], v[200:203], v[226:229], v[16:19]
	v_mfma_f32_16x16x32_bf16 v[4:7], v[192:195], v[234:237], v[4:7]
	v_mfma_f32_16x16x32_bf16 v[0:3], v[200:203], v[234:237], v[0:3]
	s_setprio 0
	s_barrier
	s_add_i32 s68, 0, 0x18000
	v_add_u32_e32 v179, s68, v147
	s_add_i32 s75, 0, 0x1c000
	ds_read_b128 v[168:171], v179
	ds_read_b128 v[172:175], v179 offset:1024
	ds_read_b128 v[180:183], v179 offset:2048
	ds_read_b128 v[184:187], v179 offset:3072
	v_add_u32_e32 v179, s75, v147
	ds_read_b128 v[188:191], v179
	ds_read_b128 v[192:195], v179 offset:1024
	ds_read_b128 v[196:199], v179 offset:2048
	ds_read_b128 v[200:203], v179 offset:3072
	s_add_u32 s36, s36, 0x40000
	s_addc_u32 s37, s37, 0
	s_mov_b32 m0, s58
	v_lshl_add_u64 v[242:243], s[36:37], 0, v[128:129]
	ds_read_b128 v[204:207], v158 offset:32768
	ds_read_b128 v[208:211], v158 offset:33792
	ds_read_b128 v[212:215], v158 offset:34816
	ds_read_b128 v[216:219], v158 offset:35840
	ds_read_b128 v[222:225], v158 offset:36864
	ds_read_b128 v[226:229], v158 offset:37888
	ds_read_b128 v[230:233], v158 offset:38912
	ds_read_b128 v[234:237], v158 offset:39936
	global_load_lds_dwordx4 v[242:243], off
	v_lshl_add_u64 v[242:243], s[36:37], 0, v[132:133]
	s_mov_b32 m0, s59
	s_nop 0
	global_load_lds_dwordx4 v[242:243], off
	s_waitcnt vmcnt(8)
	s_waitcnt lgkmcnt(0)
	s_barrier
	s_setprio 1
	s_waitcnt lgkmcnt(0)
	v_mfma_f32_16x16x32_bf16 v[124:127], v[168:171], v[204:207], v[124:127]
	v_mfma_f32_16x16x32_bf16 v[120:123], v[180:183], v[204:207], v[120:123]
	v_mfma_f32_16x16x32_bf16 v[108:111], v[168:171], v[212:215], v[108:111]
	v_mfma_f32_16x16x32_bf16 v[104:107], v[180:183], v[212:215], v[104:107]
	v_mfma_f32_16x16x32_bf16 v[92:95], v[168:171], v[222:225], v[92:95]
	v_mfma_f32_16x16x32_bf16 v[88:91], v[180:183], v[222:225], v[88:91]
	v_mfma_f32_16x16x32_bf16 v[76:79], v[168:171], v[230:233], v[76:79]
	v_mfma_f32_16x16x32_bf16 v[72:75], v[180:183], v[230:233], v[72:75]
	v_mfma_f32_16x16x32_bf16 v[124:127], v[172:175], v[208:211], v[124:127]
	v_mfma_f32_16x16x32_bf16 v[120:123], v[184:187], v[208:211], v[120:123]
	v_mfma_f32_16x16x32_bf16 v[108:111], v[172:175], v[216:219], v[108:111]
	v_mfma_f32_16x16x32_bf16 v[104:107], v[184:187], v[216:219], v[104:107]
	v_mfma_f32_16x16x32_bf16 v[92:95], v[172:175], v[226:229], v[92:95]
	v_mfma_f32_16x16x32_bf16 v[88:91], v[184:187], v[226:229], v[88:91]
	v_mfma_f32_16x16x32_bf16 v[76:79], v[172:175], v[234:237], v[76:79]
	v_mfma_f32_16x16x32_bf16 v[72:75], v[184:187], v[234:237], v[72:75]
	s_setprio 0
	s_setprio 1
	v_mfma_f32_16x16x32_bf16 v[116:119], v[188:191], v[204:207], v[116:119]
	v_mfma_f32_16x16x32_bf16 v[112:115], v[196:199], v[204:207], v[112:115]
	v_mfma_f32_16x16x32_bf16 v[100:103], v[188:191], v[212:215], v[100:103]
	v_mfma_f32_16x16x32_bf16 v[96:99], v[196:199], v[212:215], v[96:99]
	v_mfma_f32_16x16x32_bf16 v[84:87], v[188:191], v[222:225], v[84:87]
	v_mfma_f32_16x16x32_bf16 v[80:83], v[196:199], v[222:225], v[80:83]
	v_mfma_f32_16x16x32_bf16 v[68:71], v[188:191], v[230:233], v[68:71]
	v_mfma_f32_16x16x32_bf16 v[64:67], v[196:199], v[230:233], v[64:67]
	v_mfma_f32_16x16x32_bf16 v[116:119], v[192:195], v[208:211], v[116:119]
	v_mfma_f32_16x16x32_bf16 v[112:115], v[200:203], v[208:211], v[112:115]
	v_mfma_f32_16x16x32_bf16 v[100:103], v[192:195], v[216:219], v[100:103]
	v_mfma_f32_16x16x32_bf16 v[96:99], v[200:203], v[216:219], v[96:99]
	v_mfma_f32_16x16x32_bf16 v[84:87], v[192:195], v[226:229], v[84:87]
	v_mfma_f32_16x16x32_bf16 v[80:83], v[200:203], v[226:229], v[80:83]
	v_mfma_f32_16x16x32_bf16 v[68:71], v[192:195], v[234:237], v[68:71]
	v_mfma_f32_16x16x32_bf16 v[64:67], v[200:203], v[234:237], v[64:67]
	s_setprio 0
	s_barrier
; #define PG8_STAGE(bufoff, gbase, voff) do { _Pragma("unroll") for (int _i = 0; _i < 2; ++_i) \
;         __builtin_amdgcn_global_load_lds((const unsigned*)((const char*)(gbase) + (voff)[_i]), (PG8_LAS unsigned*)(lds + (bufoff) + ldsw + _i * 8192), 16, 0, 0); } while (0)
; #define PG8_LDA(dst, b, h) do { _Pragma("unroll") for (int m = 0; m < 4; ++m) _Pragma("unroll") for (int k = 0; k < 2; ++k) dst[m][k] = *(const PG8_LAS bf16x8*)(lds + PG8_SA(b, h) + aoff + m * 2048 + k * 1024); } while (0)
; #define PG8_MMA(ai, bj, At, Bt) do { __builtin_amdgcn_s_setprio(1); _Pragma("unroll") for (int m = 0; m < 4; ++m) _Pragma("unroll") for (int n = 0; n < 2; ++n) _Pragma("unroll") for (int k = 0; k < 2; ++k) \
;         acc[ai][bj][m][n] = __builtin_amdgcn_mfma_f32_16x16x32_bf16(Bt[n][k], At[m][k], acc[ai][bj][m][n], 0, 0, 0); __builtin_amdgcn_s_setprio(0); } while (0)
; #define PG8_WAIT_V(n) asm volatile("s_waitcnt vmcnt(" #n ")" ::: "memory")
; #define PG8_WAIT_L(n) asm volatile("s_waitcnt lgkmcnt(" #n ")" ::: "memory")
; #define PG8_BAR __builtin_amdgcn_s_barrier()
; #define PG8_SCHED __builtin_amdgcn_sched_barrier(0)
;     __device__ __forceinline__ void operator()(Acc& acc, const Unit& u, int wr, int wc, int fr, int fq, PG8_LAS unsigned char* xl) const {
;     ...
;             for (int m = 0; m < 4; ++m) { const int rl = ai * HALF + wr * 64 + m * 16 + fr; const int row = u.r0 + rl; const size_t off = (size_t)row * DM + col; float s = 0.f;
; #pragma unroll
;                 for (int bj = 0; bj < 2; ++bj) {
;                     f32x4 b0, b1;
;                     if (BASE_BF16) unpack8(*(const u32x4*)((const bf16_t*)base + off + bj * HALF), b0, b1);
;                     else { b0 = *(const f32x4*)((const float*)base + off + bj * HALF); b1 = *(const f32x4*)((const float*)base + off + bj * HALF + 4); }
; template <class Epi, class Sched>
; __device__ __forceinline__ void gemm_phase(PG8_LAS unsigned char* lds, PG8_LAS unsigned char* xl, const Gemm g, const Sched& S, const Epi& E) {
;     ...
;             PG8_LDA(At, 1, 1); PG8_STAGE(PG8_SB(1, 0), b3, voffB); PG8_STAGE(PG8_SB(1, 1), b3 + hsB, voffB); PG8_STAGE(PG8_SA(1, 0), a3, voffA);
;             PG8_WAIT_V(8); PG8_WAIT_L(0); PG8_BAR; PG8_MMA(1, 0, At, B0); PG8_MMA(1, 1, At, B1); PG8_BAR; PG8_SCHED;
;         }
;         if (wr == 0) PG8_BAR;
	s_add_i32 s36, s68, s55
	v_lshl_add_u64 v[144:145], v[144:145], 0, s[16:17]
	s_mov_b32 m0, s36
	ds_read_b128 v[204:207], v158 offset:49152
	ds_read_b128 v[208:211], v158 offset:50176
	ds_read_b128 v[212:215], v158 offset:51200
	ds_read_b128 v[216:219], v158 offset:52224
	ds_read_b128 v[222:225], v158 offset:53248
	ds_read_b128 v[226:229], v158 offset:54272
	ds_read_b128 v[230:233], v158 offset:55296
	ds_read_b128 v[234:237], v158 offset:56320
	global_load_lds_dwordx4 v[144:145], off
	s_add_i32 m0, s36, 0x2000
	s_add_u32 s34, s34, 0x40080
	v_lshl_add_u64 v[144:145], v[176:177], 0, s[16:17]
	s_addc_u32 s35, s35, 0
	s_add_i32 s36, s75, s55
	global_load_lds_dwordx4 v[144:145], off
	v_lshl_add_u64 v[144:145], s[34:35], 0, v[130:131]
	s_mov_b32 m0, s36
	s_nop 0
	global_load_lds_dwordx4 v[144:145], off
	v_lshl_add_u64 v[144:145], s[34:35], 0, v[134:135]
	s_add_i32 m0, s36, 0x2000
	s_nop 0
	global_load_lds_dwordx4 v[144:145], off
	v_lshl_add_u64 v[144:145], v[238:239], 0, s[16:17]
	s_mov_b32 m0, s61
	s_nop 0
	global_load_lds_dwordx4 v[144:145], off
	v_lshl_add_u64 v[144:145], v[240:241], 0, s[16:17]
	s_mov_b32 m0, s62
	s_nop 0
	global_load_lds_dwordx4 v[144:145], off
	s_waitcnt vmcnt(8)
	s_waitcnt lgkmcnt(0)
	s_barrier
	s_setprio 1
	s_waitcnt lgkmcnt(0)
	v_mfma_f32_16x16x32_bf16 v[60:63], v[168:171], v[204:207], v[60:63]
	v_mfma_f32_16x16x32_bf16 v[56:59], v[180:183], v[204:207], v[56:59]
	v_mfma_f32_16x16x32_bf16 v[44:47], v[168:171], v[212:215], v[44:47]
	v_mfma_f32_16x16x32_bf16 v[40:43], v[180:183], v[212:215], v[40:43]
	v_mfma_f32_16x16x32_bf16 v[28:31], v[168:171], v[222:225], v[28:31]
	v_mfma_f32_16x16x32_bf16 v[24:27], v[180:183], v[222:225], v[24:27]
	v_mfma_f32_16x16x32_bf16 v[12:15], v[168:171], v[230:233], v[12:15]
	v_mfma_f32_16x16x32_bf16 v[8:11], v[180:183], v[230:233], v[8:11]
	v_mfma_f32_16x16x32_bf16 v[60:63], v[172:175], v[208:211], v[60:63]
	v_mfma_f32_16x16x32_bf16 v[56:59], v[184:187], v[208:211], v[56:59]
	v_mfma_f32_16x16x32_bf16 v[44:47], v[172:175], v[216:219], v[44:47]
	v_mfma_f32_16x16x32_bf16 v[40:43], v[184:187], v[216:219], v[40:43]
	v_mfma_f32_16x16x32_bf16 v[28:31], v[172:175], v[226:229], v[28:31]
	v_mfma_f32_16x16x32_bf16 v[24:27], v[184:187], v[226:229], v[24:27]
	v_mfma_f32_16x16x32_bf16 v[12:15], v[172:175], v[234:237], v[12:15]
	v_mfma_f32_16x16x32_bf16 v[8:11], v[184:187], v[234:237], v[8:11]
	s_setprio 0
	s_setprio 1
	v_mfma_f32_16x16x32_bf16 v[52:55], v[188:191], v[204:207], v[52:55]
	v_mfma_f32_16x16x32_bf16 v[48:51], v[196:199], v[204:207], v[48:51]
	v_mfma_f32_16x16x32_bf16 v[36:39], v[188:191], v[212:215], v[36:39]
	v_mfma_f32_16x16x32_bf16 v[32:35], v[196:199], v[212:215], v[32:35]
	v_mfma_f32_16x16x32_bf16 v[20:23], v[188:191], v[222:225], v[20:23]
	v_mfma_f32_16x16x32_bf16 v[16:19], v[196:199], v[222:225], v[16:19]
	v_mfma_f32_16x16x32_bf16 v[4:7], v[188:191], v[230:233], v[4:7]
	v_mfma_f32_16x16x32_bf16 v[0:3], v[196:199], v[230:233], v[0:3]
	v_mfma_f32_16x16x32_bf16 v[52:55], v[192:195], v[208:211], v[52:55]
	v_mfma_f32_16x16x32_bf16 v[48:51], v[200:203], v[208:211], v[48:51]
	v_mfma_f32_16x16x32_bf16 v[36:39], v[192:195], v[216:219], v[36:39]
	v_mfma_f32_16x16x32_bf16 v[32:35], v[200:203], v[216:219], v[32:35]
	v_mfma_f32_16x16x32_bf16 v[20:23], v[192:195], v[226:229], v[20:23]
	v_mfma_f32_16x16x32_bf16 v[16:19], v[200:203], v[226:229], v[16:19]
	v_mfma_f32_16x16x32_bf16 v[4:7], v[192:195], v[234:237], v[4:7]
	v_mfma_f32_16x16x32_bf16 v[0:3], v[200:203], v[234:237], v[0:3]
	s_setprio 0
	s_barrier
	s_add_i32 s74, s74, 2
	s_add_u32 s72, s72, 0x100
	s_addc_u32 s73, s73, 0
	s_add_u32 s30, s30, 0x100
	s_addc_u32 s31, s31, 0
	s_cmp_gt_u32 s74, 13
	s_cbranch_scc0 .LBB0_471
	v_add_u32_e32 v252, s53, v148
	v_ashrrev_i32_e32 v253, 31, v252
	v_add_u32_e32 v222, s54, v146
	v_ashrrev_i32_e32 v223, 31, v222
	v_lshlrev_b64 v[222:223], 10, v[222:223]
	v_lshl_add_u64 v[222:223], v[222:223], 0, v[252:253]
	v_lshl_add_u64 v[222:223], v[222:223], 2, s[2:3]
	global_load_dwordx4 v[184:187], v[222:223], off
	global_load_dwordx4 v[188:191], v[222:223], off offset:16
	global_load_dwordx4 v[192:195], v[222:223], off offset:512
	global_load_dwordx4 v[196:199], v[222:223], off offset:528
	v_add_u32_e32 v222, s54, v149
	v_ashrrev_i32_e32 v223, 31, v222
	v_lshlrev_b64 v[222:223], 10, v[222:223]
	v_lshl_add_u64 v[222:223], v[222:223], 0, v[252:253]
	v_lshl_add_u64 v[222:223], v[222:223], 2, s[2:3]
	global_load_dwordx4 v[200:203], v[222:223], off
	global_load_dwordx4 v[204:207], v[222:223], off offset:16
	global_load_dwordx4 v[208:211], v[222:223], off offset:512
	global_load_dwordx4 v[212:215], v[222:223], off offset:528
	v_add_u32_e32 v222, s54, v150
	v_ashrrev_i32_e32 v223, 31, v222
	v_lshlrev_b64 v[222:223], 10, v[222:223]
	v_lshl_add_u64 v[222:223], v[222:223], 0, v[252:253]
	v_lshl_add_u64 v[222:223], v[222:223], 2, s[2:3]
	global_load_dwordx4 v[216:219], v[222:223], off
	global_load_dwordx4 v[224:227], v[222:223], off offset:16
	global_load_dwordx4 v[228:231], v[222:223], off offset:512
	global_load_dwordx4 v[232:235], v[222:223], off offset:528
	v_add_u32_e32 v222, s54, v151
	v_ashrrev_i32_e32 v223, 31, v222
	v_lshlrev_b64 v[222:223], 10, v[222:223]
	v_lshl_add_u64 v[222:223], v[222:223], 0, v[252:253]
	v_lshl_add_u64 v[222:223], v[222:223], 2, s[2:3]
	global_load_dwordx4 v[236:239], v[222:223], off
	global_load_dwordx4 v[240:243], v[222:223], off offset:16
	global_load_dwordx4 v[244:247], v[222:223], off offset:512
	global_load_dwordx4 v[248:251], v[222:223], off offset:528
	s_and_b64 vcc, exec, s[18:19]
	s_cbranch_vccz .LBB0_474
	s_barrier
; __device__ __forceinline__ u32x4 pack8(f32x4 v0, f32x4 v1) { u32x4 w; w.x = cvt_pk_bf16(v0[0], v0[1]); w.y = cvt_pk_bf16(v0[2], v0[3]); w.z = cvt_pk_bf16(v1[0], v1[1]); w.w = cvt_pk_bf16(v1[2], v1[3]); return w; }
;     __device__ __forceinline__ void operator()(Acc& acc, const Unit& u, int wr, int wc, int fr, int fq, PG8_LAS unsigned char* xl) const {
;     ...
;             for (int m = 0; m < 4; ++m) { const int rl = ai * HALF + wr * 64 + m * 16 + fr; const int row = u.r0 + rl; const size_t off = (size_t)row * DM + col; float s = 0.f;
; #pragma unroll
;                 for (int bj = 0; bj < 2; ++bj) {
;                     f32x4 b0, b1;
;                     if (BASE_BF16) unpack8(*(const u32x4*)((const bf16_t*)base + off + bj * HALF), b0, b1);
;                     else { b0 = *(const f32x4*)((const float*)base + off + bj * HALF); b1 = *(const f32x4*)((const float*)base + off + bj * HALF + 4); }
;                     const u32x4 w = pack8(acc[ai][bj][m][0] + b0, acc[ai][bj][m][1] + b1);
;                     *(u32x4*)(outB + off + bj * HALF) = w;
;                     f32x4 v0, v1; unpack8(w, v0, v1);
;                     s += (v0[0] * v0[0] + v0[1] * v0[1]) + (v0[2] * v0[2] + v0[3] * v0[3]) + (v1[0] * v1[0] + v1[1] * v1[1]) + (v1[2] * v1[2] + v1[3] * v1[3]); }
;                 s += __shfl_xor(s, 16); s += __shfl_xor(s, 32);
;                 if (fq == 0) X[rl * 4 + wc] = s; }
.LBB0_474:
	v_add_u32_e32 v168, s54, v146
	v_add_u32_e32 v144, s53, v148
	v_ashrrev_i32_e32 v169, 31, v168
	v_ashrrev_i32_e32 v145, 31, v144
	v_lshlrev_b64 v[168:169], 10, v[168:169]
	v_lshl_add_u64 v[176:177], v[168:169], 0, v[144:145]
	v_lshl_add_u64 v[180:181], v[176:177], 2, s[2:3]
	s_nop 0
	s_nop 0
	v_lshl_add_u64 v[176:177], v[176:177], 1, s[12:13]
	s_waitcnt vmcnt(14) lgkmcnt(0)
	v_pk_add_f32 v[124:125], v[124:125], v[184:185]
	v_pk_add_f32 v[126:127], v[126:127], v[186:187]
	v_pk_add_f32 v[168:169], v[122:123], v[190:191]
	v_pk_add_f32 v[120:121], v[120:121], v[188:189]
	v_cvt_pk_bf16_f32 v122, v124, v125
	v_cvt_pk_bf16_f32 v123, v126, v127
	s_nop 0
	v_cvt_pk_bf16_f32 v124, v120, v121
	v_cvt_pk_bf16_f32 v125, v168, v169
	global_store_dwordx4 v[176:177], v[122:125], off
	s_nop 0
	s_nop 0
	v_lshlrev_b32_e32 v126, 16, v122
	v_and_b32_e32 v122, 0xffff0000, v122
	v_lshlrev_b32_e32 v127, 16, v123
	v_and_b32_e32 v123, 0xffff0000, v123
	v_lshlrev_b32_e32 v179, 16, v124
	v_and_b32_e32 v124, 0xffff0000, v124
	v_mul_f32_e32 v122, v122, v122
	v_mul_f32_e32 v123, v123, v123
	v_mul_f32_e32 v124, v124, v124
	v_fmac_f32_e32 v122, v126, v126
	v_fmac_f32_e32 v123, v127, v127
	v_lshlrev_b32_e32 v180, 16, v125
	v_and_b32_e32 v125, 0xffff0000, v125
	v_fmac_f32_e32 v124, v179, v179
	v_add_f32_e32 v122, v122, v123
	v_mul_f32_e32 v125, v125, v125
	v_add_f32_e32 v122, v122, v124
	v_and_b32_e32 v121, 64, v159
	v_fmac_f32_e32 v125, v180, v180
	v_xor_b32_e32 v120, 16, v159
	v_add_u32_e32 v121, 64, v121
	v_add_f32_e32 v122, v122, v125
	v_cmp_lt_i32_e32 vcc, v120, v121
	s_waitcnt vmcnt(13) lgkmcnt(0)
	v_pk_add_f32 v[118:119], v[118:119], v[194:195]
	v_pk_add_f32 v[116:117], v[116:117], v[192:193]
	v_pk_add_f32 v[114:115], v[114:115], v[198:199]
	v_pk_add_f32 v[112:113], v[112:113], v[196:197]
	v_add_u32_e32 v222, s54, v152
	v_ashrrev_i32_e32 v223, 31, v222
	v_lshlrev_b64 v[222:223], 10, v[222:223]
	v_lshl_add_u64 v[222:223], v[222:223], 0, v[252:253]
	v_lshl_add_u64 v[222:223], v[222:223], 2, s[2:3]
	global_load_dwordx4 v[184:187], v[222:223], off
	global_load_dwordx4 v[188:191], v[222:223], off offset:16
	global_load_dwordx4 v[192:195], v[222:223], off offset:512
	global_load_dwordx4 v[196:199], v[222:223], off offset:528
	v_cvt_pk_bf16_f32 v116, v116, v117
	v_cvt_pk_bf16_f32 v117, v118, v119
	v_cndmask_b32_e32 v120, v159, v120, vcc
	v_cvt_pk_bf16_f32 v118, v112, v113
	v_cvt_pk_bf16_f32 v119, v114, v115
	v_and_b32_e32 v113, 0xffff0000, v116
	v_and_b32_e32 v115, 0xffff0000, v117
	v_lshlrev_b32_e32 v112, 16, v116
	v_lshlrev_b32_e32 v114, 16, v117
	v_and_b32_e32 v124, 0xffff0000, v118
	v_mul_f32_e32 v113, v113, v113
	v_mul_f32_e32 v115, v115, v115
	v_lshlrev_b32_e32 v123, 16, v118
	v_and_b32_e32 v126, 0xffff0000, v119
	v_mul_f32_e32 v124, v124, v124
	v_fmac_f32_e32 v113, v112, v112
	v_fmac_f32_e32 v115, v114, v114
	v_lshlrev_b32_e32 v125, 16, v119
	v_mul_f32_e32 v126, v126, v126
	v_fmac_f32_e32 v124, v123, v123
	v_add_f32_e32 v112, v113, v115
	v_fmac_f32_e32 v126, v125, v125
	v_add_f32_e32 v112, v112, v124
	v_add_f32_e32 v112, v112, v126
	v_lshlrev_b32_e32 v120, 2, v120
	v_add_f32_e32 v112, v122, v112
	ds_bpermute_b32 v113, v120, v112
	v_xor_b32_e32 v114, 32, v159
	v_cmp_lt_i32_e32 vcc, v114, v121
	global_store_dwordx4 v[176:177], v[116:119], off offset:256
	s_waitcnt lgkmcnt(0)
	v_add_f32_e32 v113, v112, v113
	v_cndmask_b32_e32 v114, v159, v114, vcc
	v_lshlrev_b32_e32 v112, 2, v114
	ds_bpermute_b32 v114, v112, v113
	s_and_saveexec_b64 s[30:31], s[6:7]
	s_cbranch_execz .LBB0_476
	s_waitcnt lgkmcnt(0)
	v_add_f32_e32 v113, v113, v114
	ds_write_b32 v160, v113
.LBB0_476:
	s_or_b64 exec, exec, s[30:31]
	s_waitcnt lgkmcnt(0)
	v_add_u32_e32 v114, s54, v149
	v_ashrrev_i32_e32 v115, 31, v114
	v_lshlrev_b64 v[114:115], 10, v[114:115]
	v_lshl_add_u64 v[118:119], v[114:115], 0, v[144:145]
	v_lshl_add_u64 v[126:127], v[118:119], 2, s[2:3]
	s_nop 0
	s_nop 0
	v_lshl_add_u64 v[118:119], v[118:119], 1, s[12:13]
	s_waitcnt vmcnt(16) lgkmcnt(0)
	v_pk_add_f32 v[108:109], v[108:109], v[200:201]
	v_pk_add_f32 v[114:115], v[106:107], v[206:207]
	v_pk_add_f32 v[106:107], v[104:105], v[204:205]
	v_pk_add_f32 v[110:111], v[110:111], v[202:203]
	v_cvt_pk_bf16_f32 v104, v108, v109
	s_nop 0
	v_cvt_pk_bf16_f32 v105, v110, v111
	v_cvt_pk_bf16_f32 v106, v106, v107
	v_cvt_pk_bf16_f32 v107, v114, v115
	global_store_dwordx4 v[118:119], v[104:107], off
	s_nop 0
	s_nop 0
	v_lshlrev_b32_e32 v113, 16, v104
	v_and_b32_e32 v104, 0xffff0000, v104
	v_lshlrev_b32_e32 v121, 16, v105
	v_and_b32_e32 v105, 0xffff0000, v105
	v_lshlrev_b32_e32 v122, 16, v106
	v_and_b32_e32 v106, 0xffff0000, v106
	v_mul_f32_e32 v104, v104, v104
	v_mul_f32_e32 v105, v105, v105
	v_lshlrev_b32_e32 v123, 16, v107
	v_and_b32_e32 v107, 0xffff0000, v107
	v_mul_f32_e32 v106, v106, v106
	v_fmac_f32_e32 v104, v113, v113
	v_fmac_f32_e32 v105, v121, v121
	v_mul_f32_e32 v107, v107, v107
	v_fmac_f32_e32 v106, v122, v122
	v_add_f32_e32 v104, v104, v105
	v_fmac_f32_e32 v107, v123, v123
	v_add_f32_e32 v104, v104, v106
	v_add_f32_e32 v106, v104, v107
	s_waitcnt vmcnt(15) lgkmcnt(0)
	v_pk_add_f32 v[102:103], v[102:103], v[210:211]
	v_pk_add_f32 v[100:101], v[100:101], v[208:209]
	v_pk_add_f32 v[96:97], v[96:97], v[212:213]
	v_pk_add_f32 v[104:105], v[98:99], v[214:215]
	v_add_u32_e32 v222, s54, v153
	v_ashrrev_i32_e32 v223, 31, v222
	v_lshlrev_b64 v[222:223], 10, v[222:223]
	v_lshl_add_u64 v[222:223], v[222:223], 0, v[252:253]
	v_lshl_add_u64 v[222:223], v[222:223], 2, s[2:3]
	global_load_dwordx4 v[200:203], v[222:223], off
	global_load_dwordx4 v[204:207], v[222:223], off offset:16
	global_load_dwordx4 v[208:211], v[222:223], off offset:512
	global_load_dwordx4 v[212:215], v[222:223], off offset:528
	v_cvt_pk_bf16_f32 v98, v100, v101
	v_cvt_pk_bf16_f32 v99, v102, v103
	v_cvt_pk_bf16_f32 v100, v96, v97
	s_nop 0
	v_and_b32_e32 v97, 0xffff0000, v98
	v_and_b32_e32 v103, 0xffff0000, v99
	v_cvt_pk_bf16_f32 v101, v104, v105
	v_lshlrev_b32_e32 v96, 16, v98
	v_lshlrev_b32_e32 v102, 16, v99
	v_and_b32_e32 v105, 0xffff0000, v100
	v_mul_f32_e32 v97, v97, v97
	v_mul_f32_e32 v103, v103, v103
	v_lshlrev_b32_e32 v104, 16, v100
	v_and_b32_e32 v108, 0xffff0000, v101
	v_mul_f32_e32 v105, v105, v105
	v_fmac_f32_e32 v97, v96, v96
	v_fmac_f32_e32 v103, v102, v102
	v_lshlrev_b32_e32 v107, 16, v101
	v_mul_f32_e32 v108, v108, v108
	v_fmac_f32_e32 v105, v104, v104
	v_add_f32_e32 v96, v97, v103
	v_add_f32_e32 v96, v96, v105
	v_fmac_f32_e32 v108, v107, v107
	v_add_f32_e32 v96, v96, v108
	v_add_f32_e32 v96, v106, v96
	ds_bpermute_b32 v97, v120, v96
	global_store_dwordx4 v[118:119], v[98:101], off offset:256
	s_waitcnt lgkmcnt(0)
	v_add_f32_e32 v96, v96, v97
	ds_bpermute_b32 v97, v112, v96
	s_and_saveexec_b64 s[30:31], s[6:7]
	s_cbranch_execz .LBB0_478
	s_waitcnt lgkmcnt(0)
	v_add_f32_e32 v96, v96, v97
	ds_write_b32 v161, v96
; __device__ __forceinline__ u32x4 pack8(f32x4 v0, f32x4 v1) { u32x4 w; w.x = cvt_pk_bf16(v0[0], v0[1]); w.y = cvt_pk_bf16(v0[2], v0[3]); w.z = cvt_pk_bf16(v1[0], v1[1]); w.w = cvt_pk_bf16(v1[2], v1[3]); return w; }
;     __device__ __forceinline__ void operator()(Acc& acc, const Unit& u, int wr, int wc, int fr, int fq, PG8_LAS unsigned char* xl) const {
;     ...
;             for (int m = 0; m < 4; ++m) { const int rl = ai * HALF + wr * 64 + m * 16 + fr; const int row = u.r0 + rl; const size_t off = (size_t)row * DM + col; float s = 0.f;
; #pragma unroll
;                 for (int bj = 0; bj < 2; ++bj) {
;                     f32x4 b0, b1;
;                     if (BASE_BF16) unpack8(*(const u32x4*)((const bf16_t*)base + off + bj * HALF), b0, b1);
;                     else { b0 = *(const f32x4*)((const float*)base + off + bj * HALF); b1 = *(const f32x4*)((const float*)base + off + bj * HALF + 4); }
;                     const u32x4 w = pack8(acc[ai][bj][m][0] + b0, acc[ai][bj][m][1] + b1);
;                     *(u32x4*)(outB + off + bj * HALF) = w;
;                     f32x4 v0, v1; unpack8(w, v0, v1);
;                     s += (v0[0] * v0[0] + v0[1] * v0[1]) + (v0[2] * v0[2] + v0[3] * v0[3]) + (v1[0] * v1[0] + v1[1] * v1[1]) + (v1[2] * v1[2] + v1[3] * v1[3]); }
;                 s += __shfl_xor(s, 16); s += __shfl_xor(s, 32);
;                 if (fq == 0) X[rl * 4 + wc] = s; }
.LBB0_478:
	s_or_b64 exec, exec, s[30:31]
	v_add_u32_e32 v96, s54, v150
	s_waitcnt lgkmcnt(0)
	v_ashrrev_i32_e32 v97, 31, v96
	v_lshlrev_b64 v[96:97], 10, v[96:97]
	v_lshl_add_u64 v[104:105], v[96:97], 0, v[144:145]
	v_lshl_add_u64 v[106:107], v[104:105], 2, s[2:3]
	s_nop 0
	s_nop 0
	v_lshl_add_u64 v[104:105], v[104:105], 1, s[12:13]
	s_waitcnt vmcnt(18) lgkmcnt(0)
	v_pk_add_f32 v[92:93], v[92:93], v[216:217]
	v_pk_add_f32 v[96:97], v[90:91], v[226:227]
	v_pk_add_f32 v[90:91], v[88:89], v[224:225]
	v_pk_add_f32 v[94:95], v[94:95], v[218:219]
	v_cvt_pk_bf16_f32 v88, v92, v93
	s_nop 0
	v_cvt_pk_bf16_f32 v89, v94, v95
	v_cvt_pk_bf16_f32 v90, v90, v91
	v_cvt_pk_bf16_f32 v91, v96, v97
	global_store_dwordx4 v[104:105], v[88:91], off
	s_nop 0
	s_nop 0
	v_lshlrev_b32_e32 v100, 16, v88
	v_and_b32_e32 v88, 0xffff0000, v88
	v_lshlrev_b32_e32 v101, 16, v89
	v_and_b32_e32 v89, 0xffff0000, v89
	v_lshlrev_b32_e32 v102, 16, v90
	v_and_b32_e32 v90, 0xffff0000, v90
	v_mul_f32_e32 v88, v88, v88
	v_mul_f32_e32 v89, v89, v89
	v_lshlrev_b32_e32 v103, 16, v91
	v_and_b32_e32 v91, 0xffff0000, v91
	v_mul_f32_e32 v90, v90, v90
	v_fmac_f32_e32 v88, v100, v100
	v_fmac_f32_e32 v89, v101, v101
	v_mul_f32_e32 v91, v91, v91
	v_fmac_f32_e32 v90, v102, v102
	v_add_f32_e32 v88, v88, v89
	v_fmac_f32_e32 v91, v103, v103
	v_add_f32_e32 v88, v88, v90
	v_add_f32_e32 v90, v88, v91
	s_waitcnt vmcnt(17) lgkmcnt(0)
	v_pk_add_f32 v[86:87], v[86:87], v[230:231]
	v_pk_add_f32 v[84:85], v[84:85], v[228:229]
	v_pk_add_f32 v[80:81], v[80:81], v[232:233]
	v_pk_add_f32 v[88:89], v[82:83], v[234:235]
	v_add_u32_e32 v222, s54, v154
	v_ashrrev_i32_e32 v223, 31, v222
	v_lshlrev_b64 v[222:223], 10, v[222:223]
	v_lshl_add_u64 v[222:223], v[222:223], 0, v[252:253]
	v_lshl_add_u64 v[222:223], v[222:223], 2, s[2:3]
	global_load_dwordx4 v[216:219], v[222:223], off
	global_load_dwordx4 v[224:227], v[222:223], off offset:16
	global_load_dwordx4 v[228:231], v[222:223], off offset:512
	global_load_dwordx4 v[232:235], v[222:223], off offset:528
	v_cvt_pk_bf16_f32 v82, v84, v85
	v_cvt_pk_bf16_f32 v83, v86, v87
	v_cvt_pk_bf16_f32 v84, v80, v81
	s_nop 0
	v_and_b32_e32 v81, 0xffff0000, v82
	v_and_b32_e32 v87, 0xffff0000, v83
	v_cvt_pk_bf16_f32 v85, v88, v89
	v_lshlrev_b32_e32 v80, 16, v82
	v_lshlrev_b32_e32 v86, 16, v83
	v_and_b32_e32 v89, 0xffff0000, v84
	v_mul_f32_e32 v81, v81, v81
	v_mul_f32_e32 v87, v87, v87
	v_lshlrev_b32_e32 v88, 16, v84
	v_and_b32_e32 v92, 0xffff0000, v85
	v_mul_f32_e32 v89, v89, v89
	v_fmac_f32_e32 v81, v80, v80
	v_fmac_f32_e32 v87, v86, v86
	v_lshlrev_b32_e32 v91, 16, v85
	v_mul_f32_e32 v92, v92, v92
	v_fmac_f32_e32 v89, v88, v88
	v_add_f32_e32 v80, v81, v87
	v_add_f32_e32 v80, v80, v89
	v_fmac_f32_e32 v92, v91, v91
	v_add_f32_e32 v80, v80, v92
	v_add_f32_e32 v80, v90, v80
	ds_bpermute_b32 v81, v120, v80
	global_store_dwordx4 v[104:105], v[82:85], off offset:256
	s_waitcnt lgkmcnt(0)
	v_add_f32_e32 v80, v80, v81
	ds_bpermute_b32 v81, v112, v80
	s_and_saveexec_b64 s[30:31], s[6:7]
	s_cbranch_execz .LBB0_480
	s_waitcnt lgkmcnt(0)
	v_add_f32_e32 v80, v80, v81
	ds_write_b32 v162, v80
.LBB0_480:
	s_or_b64 exec, exec, s[30:31]
	v_add_u32_e32 v80, s54, v151
	s_waitcnt lgkmcnt(0)
	v_ashrrev_i32_e32 v81, 31, v80
	v_lshlrev_b64 v[80:81], 10, v[80:81]
	v_lshl_add_u64 v[88:89], v[80:81], 0, v[144:145]
	v_lshl_add_u64 v[90:91], v[88:89], 2, s[2:3]
	s_nop 0
	s_nop 0
	v_lshl_add_u64 v[88:89], v[88:89], 1, s[12:13]
	s_waitcnt vmcnt(20) lgkmcnt(0)
	v_pk_add_f32 v[76:77], v[76:77], v[236:237]
	v_pk_add_f32 v[80:81], v[74:75], v[242:243]
	v_pk_add_f32 v[74:75], v[72:73], v[240:241]
	v_pk_add_f32 v[78:79], v[78:79], v[238:239]
	v_cvt_pk_bf16_f32 v72, v76, v77
	s_nop 0
	v_cvt_pk_bf16_f32 v73, v78, v79
	v_cvt_pk_bf16_f32 v74, v74, v75
	v_cvt_pk_bf16_f32 v75, v80, v81
	global_store_dwordx4 v[88:89], v[72:75], off
	s_nop 0
	s_nop 0
	v_lshlrev_b32_e32 v84, 16, v72
	v_and_b32_e32 v72, 0xffff0000, v72
	v_lshlrev_b32_e32 v85, 16, v73
	v_and_b32_e32 v73, 0xffff0000, v73
	v_lshlrev_b32_e32 v86, 16, v74
	v_and_b32_e32 v74, 0xffff0000, v74
	v_mul_f32_e32 v72, v72, v72
	v_mul_f32_e32 v73, v73, v73
	v_lshlrev_b32_e32 v87, 16, v75
	v_and_b32_e32 v75, 0xffff0000, v75
	v_mul_f32_e32 v74, v74, v74
	v_fmac_f32_e32 v72, v84, v84
	v_fmac_f32_e32 v73, v85, v85
	v_mul_f32_e32 v75, v75, v75
	v_fmac_f32_e32 v74, v86, v86
	v_add_f32_e32 v72, v72, v73
	v_fmac_f32_e32 v75, v87, v87
	v_add_f32_e32 v72, v72, v74
	v_add_f32_e32 v74, v72, v75
	s_waitcnt vmcnt(19) lgkmcnt(0)
	v_pk_add_f32 v[70:71], v[70:71], v[246:247]
	v_pk_add_f32 v[68:69], v[68:69], v[244:245]
	v_pk_add_f32 v[64:65], v[64:65], v[248:249]
	v_pk_add_f32 v[72:73], v[66:67], v[250:251]
	v_add_u32_e32 v222, s54, v155
	v_ashrrev_i32_e32 v223, 31, v222
	v_lshlrev_b64 v[222:223], 10, v[222:223]
	v_lshl_add_u64 v[222:223], v[222:223], 0, v[252:253]
	v_lshl_add_u64 v[222:223], v[222:223], 2, s[2:3]
	global_load_dwordx4 v[236:239], v[222:223], off
	global_load_dwordx4 v[240:243], v[222:223], off offset:16
	global_load_dwordx4 v[244:247], v[222:223], off offset:512
	global_load_dwordx4 v[248:251], v[222:223], off offset:528
	v_cvt_pk_bf16_f32 v66, v68, v69
	v_cvt_pk_bf16_f32 v67, v70, v71
	v_cvt_pk_bf16_f32 v68, v64, v65
	s_nop 0
	v_and_b32_e32 v65, 0xffff0000, v66
	v_and_b32_e32 v71, 0xffff0000, v67
	v_cvt_pk_bf16_f32 v69, v72, v73
	v_lshlrev_b32_e32 v64, 16, v66
	v_lshlrev_b32_e32 v70, 16, v67
	v_and_b32_e32 v73, 0xffff0000, v68
	v_mul_f32_e32 v65, v65, v65
	v_mul_f32_e32 v71, v71, v71
	v_lshlrev_b32_e32 v72, 16, v68
	v_and_b32_e32 v76, 0xffff0000, v69
	v_mul_f32_e32 v73, v73, v73
	v_fmac_f32_e32 v65, v64, v64
	v_fmac_f32_e32 v71, v70, v70
	v_lshlrev_b32_e32 v75, 16, v69
	v_mul_f32_e32 v76, v76, v76
	v_fmac_f32_e32 v73, v72, v72
	v_add_f32_e32 v64, v65, v71
	v_add_f32_e32 v64, v64, v73
	v_fmac_f32_e32 v76, v75, v75
	v_add_f32_e32 v64, v64, v76
	v_add_f32_e32 v64, v74, v64
	ds_bpermute_b32 v65, v120, v64
	global_store_dwordx4 v[88:89], v[66:69], off offset:256
	s_waitcnt lgkmcnt(0)
	v_add_f32_e32 v64, v64, v65
	ds_bpermute_b32 v65, v112, v64
	s_and_saveexec_b64 s[30:31], s[6:7]
	s_cbranch_execz .LBB0_482
	s_waitcnt lgkmcnt(0)
	v_add_f32_e32 v64, v64, v65
	ds_write_b32 v163, v64
; __device__ __forceinline__ u32x4 pack8(f32x4 v0, f32x4 v1) { u32x4 w; w.x = cvt_pk_bf16(v0[0], v0[1]); w.y = cvt_pk_bf16(v0[2], v0[3]); w.z = cvt_pk_bf16(v1[0], v1[1]); w.w = cvt_pk_bf16(v1[2], v1[3]); return w; }
;     __device__ __forceinline__ void operator()(Acc& acc, const Unit& u, int wr, int wc, int fr, int fq, PG8_LAS unsigned char* xl) const {
;     ...
;             for (int m = 0; m < 4; ++m) { const int rl = ai * HALF + wr * 64 + m * 16 + fr; const int row = u.r0 + rl; const size_t off = (size_t)row * DM + col; float s = 0.f;
; #pragma unroll
;                 for (int bj = 0; bj < 2; ++bj) {
;                     f32x4 b0, b1;
;                     if (BASE_BF16) unpack8(*(const u32x4*)((const bf16_t*)base + off + bj * HALF), b0, b1);
;                     else { b0 = *(const f32x4*)((const float*)base + off + bj * HALF); b1 = *(const f32x4*)((const float*)base + off + bj * HALF + 4); }
;                     const u32x4 w = pack8(acc[ai][bj][m][0] + b0, acc[ai][bj][m][1] + b1);
;                     *(u32x4*)(outB + off + bj * HALF) = w;
;                     f32x4 v0, v1; unpack8(w, v0, v1);
;                     s += (v0[0] * v0[0] + v0[1] * v0[1]) + (v0[2] * v0[2] + v0[3] * v0[3]) + (v1[0] * v1[0] + v1[1] * v1[1]) + (v1[2] * v1[2] + v1[3] * v1[3]); }
;                 s += __shfl_xor(s, 16); s += __shfl_xor(s, 32);
;                 if (fq == 0) X[rl * 4 + wc] = s; }
.LBB0_482:
	s_or_b64 exec, exec, s[30:31]
	v_add_u32_e32 v64, s54, v152
	s_waitcnt lgkmcnt(0)
	v_ashrrev_i32_e32 v65, 31, v64
	v_lshlrev_b64 v[64:65], 10, v[64:65]
	v_lshl_add_u64 v[72:73], v[64:65], 0, v[144:145]
	v_lshl_add_u64 v[74:75], v[72:73], 2, s[2:3]
	s_nop 0
	s_nop 0
	v_lshl_add_u64 v[72:73], v[72:73], 1, s[12:13]
	s_waitcnt vmcnt(21) lgkmcnt(0)
	v_pk_add_f32 v[60:61], v[60:61], v[184:185]
	v_pk_add_f32 v[64:65], v[58:59], v[190:191]
	v_pk_add_f32 v[58:59], v[56:57], v[188:189]
	v_pk_add_f32 v[62:63], v[62:63], v[186:187]
	v_cvt_pk_bf16_f32 v56, v60, v61
	s_nop 0
	v_cvt_pk_bf16_f32 v57, v62, v63
	v_cvt_pk_bf16_f32 v58, v58, v59
	v_cvt_pk_bf16_f32 v59, v64, v65
	global_store_dwordx4 v[72:73], v[56:59], off
	s_nop 0
	s_nop 0
	v_lshlrev_b32_e32 v68, 16, v56
	v_and_b32_e32 v56, 0xffff0000, v56
	v_lshlrev_b32_e32 v69, 16, v57
	v_and_b32_e32 v57, 0xffff0000, v57
	v_lshlrev_b32_e32 v70, 16, v58
	v_and_b32_e32 v58, 0xffff0000, v58
	v_mul_f32_e32 v56, v56, v56
	v_mul_f32_e32 v57, v57, v57
	v_lshlrev_b32_e32 v71, 16, v59
	v_and_b32_e32 v59, 0xffff0000, v59
	v_mul_f32_e32 v58, v58, v58
	v_fmac_f32_e32 v56, v68, v68
	v_fmac_f32_e32 v57, v69, v69
	v_mul_f32_e32 v59, v59, v59
	v_fmac_f32_e32 v58, v70, v70
	v_add_f32_e32 v56, v56, v57
	v_fmac_f32_e32 v59, v71, v71
	v_add_f32_e32 v56, v56, v58
	v_add_f32_e32 v58, v56, v59
	s_waitcnt vmcnt(20) lgkmcnt(0)
	v_pk_add_f32 v[54:55], v[54:55], v[194:195]
	v_pk_add_f32 v[52:53], v[52:53], v[192:193]
	v_pk_add_f32 v[48:49], v[48:49], v[196:197]
	v_pk_add_f32 v[56:57], v[50:51], v[198:199]
	v_cvt_pk_bf16_f32 v50, v52, v53
	v_cvt_pk_bf16_f32 v51, v54, v55
	v_cvt_pk_bf16_f32 v52, v48, v49
	s_nop 0
	v_and_b32_e32 v49, 0xffff0000, v50
	v_and_b32_e32 v55, 0xffff0000, v51
	v_cvt_pk_bf16_f32 v53, v56, v57
	v_lshlrev_b32_e32 v48, 16, v50
	v_lshlrev_b32_e32 v54, 16, v51
	v_and_b32_e32 v57, 0xffff0000, v52
	v_mul_f32_e32 v49, v49, v49
	v_mul_f32_e32 v55, v55, v55
	v_lshlrev_b32_e32 v56, 16, v52
	v_and_b32_e32 v60, 0xffff0000, v53
	v_mul_f32_e32 v57, v57, v57
	v_fmac_f32_e32 v49, v48, v48
	v_fmac_f32_e32 v55, v54, v54
	v_lshlrev_b32_e32 v59, 16, v53
	v_mul_f32_e32 v60, v60, v60
	v_fmac_f32_e32 v57, v56, v56
	v_add_f32_e32 v48, v49, v55
	v_add_f32_e32 v48, v48, v57
	v_fmac_f32_e32 v60, v59, v59
	v_add_f32_e32 v48, v48, v60
	v_add_f32_e32 v48, v58, v48
	ds_bpermute_b32 v49, v120, v48
	global_store_dwordx4 v[72:73], v[50:53], off offset:256
	s_waitcnt lgkmcnt(0)
	v_add_f32_e32 v48, v48, v49
	ds_bpermute_b32 v49, v112, v48
	s_and_saveexec_b64 s[30:31], s[6:7]
	s_cbranch_execz .LBB0_484
	s_waitcnt lgkmcnt(0)
	v_add_f32_e32 v48, v48, v49
	ds_write_b32 v164, v48
.LBB0_484:
	s_or_b64 exec, exec, s[30:31]
	v_add_u32_e32 v48, s54, v153
	s_waitcnt lgkmcnt(0)
	v_ashrrev_i32_e32 v49, 31, v48
	v_lshlrev_b64 v[48:49], 10, v[48:49]
	v_lshl_add_u64 v[56:57], v[48:49], 0, v[144:145]
	v_lshl_add_u64 v[58:59], v[56:57], 2, s[2:3]
	s_nop 0
	s_nop 0
	v_lshl_add_u64 v[56:57], v[56:57], 1, s[12:13]
	s_waitcnt vmcnt(17) lgkmcnt(0)
	v_pk_add_f32 v[44:45], v[44:45], v[200:201]
	v_pk_add_f32 v[48:49], v[42:43], v[206:207]
	v_pk_add_f32 v[42:43], v[40:41], v[204:205]
	v_pk_add_f32 v[46:47], v[46:47], v[202:203]
	v_cvt_pk_bf16_f32 v40, v44, v45
	s_nop 0
	v_cvt_pk_bf16_f32 v41, v46, v47
	v_cvt_pk_bf16_f32 v42, v42, v43
	v_cvt_pk_bf16_f32 v43, v48, v49
	global_store_dwordx4 v[56:57], v[40:43], off
	s_nop 0
	s_nop 0
	v_lshlrev_b32_e32 v52, 16, v40
	v_and_b32_e32 v40, 0xffff0000, v40
	v_lshlrev_b32_e32 v53, 16, v41
	v_and_b32_e32 v41, 0xffff0000, v41
	v_lshlrev_b32_e32 v54, 16, v42
	v_and_b32_e32 v42, 0xffff0000, v42
	v_mul_f32_e32 v40, v40, v40
	v_mul_f32_e32 v41, v41, v41
	v_lshlrev_b32_e32 v55, 16, v43
	v_and_b32_e32 v43, 0xffff0000, v43
	v_mul_f32_e32 v42, v42, v42
	v_fmac_f32_e32 v40, v52, v52
	v_fmac_f32_e32 v41, v53, v53
	v_mul_f32_e32 v43, v43, v43
	v_fmac_f32_e32 v42, v54, v54
	v_add_f32_e32 v40, v40, v41
	v_fmac_f32_e32 v43, v55, v55
	v_add_f32_e32 v40, v40, v42
	v_add_f32_e32 v42, v40, v43
	s_waitcnt vmcnt(16) lgkmcnt(0)
	v_pk_add_f32 v[38:39], v[38:39], v[210:211]
	v_pk_add_f32 v[36:37], v[36:37], v[208:209]
	v_pk_add_f32 v[32:33], v[32:33], v[212:213]
	v_pk_add_f32 v[40:41], v[34:35], v[214:215]
	v_cvt_pk_bf16_f32 v34, v36, v37
	v_cvt_pk_bf16_f32 v35, v38, v39
	v_cvt_pk_bf16_f32 v36, v32, v33
	s_nop 0
	v_and_b32_e32 v33, 0xffff0000, v34
	v_and_b32_e32 v39, 0xffff0000, v35
	v_cvt_pk_bf16_f32 v37, v40, v41
	v_lshlrev_b32_e32 v32, 16, v34
	v_lshlrev_b32_e32 v38, 16, v35
	v_and_b32_e32 v41, 0xffff0000, v36
	v_mul_f32_e32 v33, v33, v33
	v_mul_f32_e32 v39, v39, v39
	v_lshlrev_b32_e32 v40, 16, v36
	v_and_b32_e32 v44, 0xffff0000, v37
	v_mul_f32_e32 v41, v41, v41
	v_fmac_f32_e32 v33, v32, v32
	v_fmac_f32_e32 v39, v38, v38
	v_lshlrev_b32_e32 v43, 16, v37
	v_mul_f32_e32 v44, v44, v44
	v_fmac_f32_e32 v41, v40, v40
	v_add_f32_e32 v32, v33, v39
	v_add_f32_e32 v32, v32, v41
	v_fmac_f32_e32 v44, v43, v43
	v_add_f32_e32 v32, v32, v44
	v_add_f32_e32 v32, v42, v32
	ds_bpermute_b32 v33, v120, v32
	global_store_dwordx4 v[56:57], v[34:37], off offset:256
	s_waitcnt lgkmcnt(0)
	v_add_f32_e32 v32, v32, v33
	ds_bpermute_b32 v33, v112, v32
	s_and_saveexec_b64 s[30:31], s[6:7]
	s_cbranch_execz .LBB0_486
	s_waitcnt lgkmcnt(0)
	v_add_f32_e32 v32, v32, v33
	ds_write_b32 v165, v32
; __device__ __forceinline__ u32x4 pack8(f32x4 v0, f32x4 v1) { u32x4 w; w.x = cvt_pk_bf16(v0[0], v0[1]); w.y = cvt_pk_bf16(v0[2], v0[3]); w.z = cvt_pk_bf16(v1[0], v1[1]); w.w = cvt_pk_bf16(v1[2], v1[3]); return w; }
;     __device__ __forceinline__ void operator()(Acc& acc, const Unit& u, int wr, int wc, int fr, int fq, PG8_LAS unsigned char* xl) const {
;     ...
;             for (int m = 0; m < 4; ++m) { const int rl = ai * HALF + wr * 64 + m * 16 + fr; const int row = u.r0 + rl; const size_t off = (size_t)row * DM + col; float s = 0.f;
; #pragma unroll
;                 for (int bj = 0; bj < 2; ++bj) {
;                     f32x4 b0, b1;
;                     if (BASE_BF16) unpack8(*(const u32x4*)((const bf16_t*)base + off + bj * HALF), b0, b1);
;                     else { b0 = *(const f32x4*)((const float*)base + off + bj * HALF); b1 = *(const f32x4*)((const float*)base + off + bj * HALF + 4); }
;                     const u32x4 w = pack8(acc[ai][bj][m][0] + b0, acc[ai][bj][m][1] + b1);
;                     *(u32x4*)(outB + off + bj * HALF) = w;
;                     f32x4 v0, v1; unpack8(w, v0, v1);
;                     s += (v0[0] * v0[0] + v0[1] * v0[1]) + (v0[2] * v0[2] + v0[3] * v0[3]) + (v1[0] * v1[0] + v1[1] * v1[1]) + (v1[2] * v1[2] + v1[3] * v1[3]); }
;                 s += __shfl_xor(s, 16); s += __shfl_xor(s, 32);
;                 if (fq == 0) X[rl * 4 + wc] = s; }
.LBB0_486:
	s_or_b64 exec, exec, s[30:31]
	v_add_u32_e32 v32, s54, v154
	s_waitcnt lgkmcnt(0)
	v_ashrrev_i32_e32 v33, 31, v32
	v_lshlrev_b64 v[32:33], 10, v[32:33]
	v_lshl_add_u64 v[40:41], v[32:33], 0, v[144:145]
	v_lshl_add_u64 v[42:43], v[40:41], 2, s[2:3]
	s_nop 0
	s_nop 0
	v_lshl_add_u64 v[40:41], v[40:41], 1, s[12:13]
	s_waitcnt vmcnt(13) lgkmcnt(0)
	v_pk_add_f32 v[28:29], v[28:29], v[216:217]
	v_pk_add_f32 v[32:33], v[26:27], v[226:227]
	v_pk_add_f32 v[26:27], v[24:25], v[224:225]
	v_pk_add_f32 v[30:31], v[30:31], v[218:219]
	v_cvt_pk_bf16_f32 v24, v28, v29
	s_nop 0
	v_cvt_pk_bf16_f32 v25, v30, v31
	v_cvt_pk_bf16_f32 v26, v26, v27
	v_cvt_pk_bf16_f32 v27, v32, v33
	global_store_dwordx4 v[40:41], v[24:27], off
	s_nop 0
	s_nop 0
	v_lshlrev_b32_e32 v36, 16, v24
	v_and_b32_e32 v24, 0xffff0000, v24
	v_lshlrev_b32_e32 v37, 16, v25
	v_and_b32_e32 v25, 0xffff0000, v25
	v_lshlrev_b32_e32 v38, 16, v26
	v_and_b32_e32 v26, 0xffff0000, v26
	v_mul_f32_e32 v24, v24, v24
	v_mul_f32_e32 v25, v25, v25
	v_lshlrev_b32_e32 v39, 16, v27
	v_and_b32_e32 v27, 0xffff0000, v27
	v_mul_f32_e32 v26, v26, v26
	v_fmac_f32_e32 v24, v36, v36
	v_fmac_f32_e32 v25, v37, v37
	v_mul_f32_e32 v27, v27, v27
	v_fmac_f32_e32 v26, v38, v38
	v_add_f32_e32 v24, v24, v25
	v_fmac_f32_e32 v27, v39, v39
	v_add_f32_e32 v24, v24, v26
	v_add_f32_e32 v26, v24, v27
	s_waitcnt vmcnt(12) lgkmcnt(0)
	v_pk_add_f32 v[22:23], v[22:23], v[230:231]
	v_pk_add_f32 v[20:21], v[20:21], v[228:229]
	v_pk_add_f32 v[16:17], v[16:17], v[232:233]
	v_pk_add_f32 v[24:25], v[18:19], v[234:235]
	v_cvt_pk_bf16_f32 v18, v20, v21
	v_cvt_pk_bf16_f32 v19, v22, v23
	v_cvt_pk_bf16_f32 v20, v16, v17
	s_nop 0
	v_and_b32_e32 v17, 0xffff0000, v18
	v_and_b32_e32 v23, 0xffff0000, v19
	v_cvt_pk_bf16_f32 v21, v24, v25
	v_lshlrev_b32_e32 v16, 16, v18
	v_lshlrev_b32_e32 v22, 16, v19
	v_and_b32_e32 v25, 0xffff0000, v20
	v_mul_f32_e32 v17, v17, v17
	v_mul_f32_e32 v23, v23, v23
	v_lshlrev_b32_e32 v24, 16, v20
	v_and_b32_e32 v28, 0xffff0000, v21
	v_mul_f32_e32 v25, v25, v25
	v_fmac_f32_e32 v17, v16, v16
	v_fmac_f32_e32 v23, v22, v22
	v_lshlrev_b32_e32 v27, 16, v21
	v_mul_f32_e32 v28, v28, v28
	v_fmac_f32_e32 v25, v24, v24
	v_add_f32_e32 v16, v17, v23
	v_add_f32_e32 v16, v16, v25
	v_fmac_f32_e32 v28, v27, v27
	v_add_f32_e32 v16, v16, v28
	v_add_f32_e32 v16, v26, v16
	ds_bpermute_b32 v17, v120, v16
	global_store_dwordx4 v[40:41], v[18:21], off offset:256
	s_waitcnt lgkmcnt(0)
	v_add_f32_e32 v16, v16, v17
	ds_bpermute_b32 v17, v112, v16
	s_and_saveexec_b64 s[30:31], s[6:7]
	s_cbranch_execz .LBB0_488
	s_waitcnt lgkmcnt(0)
	v_add_f32_e32 v16, v16, v17
	ds_write_b32 v166, v16
.LBB0_488:
	s_or_b64 exec, exec, s[30:31]
	v_add_u32_e32 v16, s54, v155
	s_waitcnt lgkmcnt(0)
	v_ashrrev_i32_e32 v17, 31, v16
	v_lshlrev_b64 v[16:17], 10, v[16:17]
	v_lshl_add_u64 v[24:25], v[16:17], 0, v[144:145]
	v_lshl_add_u64 v[26:27], v[24:25], 2, s[2:3]
	s_nop 0
	s_nop 0
	v_lshl_add_u64 v[24:25], v[24:25], 1, s[12:13]
	s_waitcnt vmcnt(9) lgkmcnt(0)
	v_pk_add_f32 v[12:13], v[12:13], v[236:237]
	v_pk_add_f32 v[16:17], v[10:11], v[242:243]
	v_pk_add_f32 v[10:11], v[8:9], v[240:241]
	v_pk_add_f32 v[14:15], v[14:15], v[238:239]
	v_cvt_pk_bf16_f32 v8, v12, v13
	s_nop 0
	v_cvt_pk_bf16_f32 v9, v14, v15
	v_cvt_pk_bf16_f32 v10, v10, v11
	v_cvt_pk_bf16_f32 v11, v16, v17
	global_store_dwordx4 v[24:25], v[8:11], off
	s_nop 0
	s_nop 0
	v_lshlrev_b32_e32 v20, 16, v8
	v_and_b32_e32 v8, 0xffff0000, v8
	v_lshlrev_b32_e32 v21, 16, v9
	v_and_b32_e32 v9, 0xffff0000, v9
	v_lshlrev_b32_e32 v22, 16, v10
	v_and_b32_e32 v10, 0xffff0000, v10
	v_mul_f32_e32 v8, v8, v8
	v_mul_f32_e32 v9, v9, v9
	v_lshlrev_b32_e32 v23, 16, v11
	v_and_b32_e32 v11, 0xffff0000, v11
	v_mul_f32_e32 v10, v10, v10
	v_fmac_f32_e32 v8, v20, v20
	v_fmac_f32_e32 v9, v21, v21
	v_mul_f32_e32 v11, v11, v11
	v_fmac_f32_e32 v10, v22, v22
	v_add_f32_e32 v8, v8, v9
	v_fmac_f32_e32 v11, v23, v23
	v_add_f32_e32 v8, v8, v10
	v_add_f32_e32 v10, v8, v11
	s_waitcnt vmcnt(8) lgkmcnt(0)
	v_pk_add_f32 v[6:7], v[6:7], v[246:247]
	v_pk_add_f32 v[4:5], v[4:5], v[244:245]
	v_pk_add_f32 v[0:1], v[0:1], v[248:249]
	v_pk_add_f32 v[8:9], v[2:3], v[250:251]
	v_cvt_pk_bf16_f32 v2, v4, v5
	v_cvt_pk_bf16_f32 v3, v6, v7
	v_cvt_pk_bf16_f32 v4, v0, v1
	s_nop 0
	v_and_b32_e32 v1, 0xffff0000, v2
	v_and_b32_e32 v7, 0xffff0000, v3
	v_cvt_pk_bf16_f32 v5, v8, v9
	v_lshlrev_b32_e32 v0, 16, v2
	v_lshlrev_b32_e32 v6, 16, v3
	v_and_b32_e32 v9, 0xffff0000, v4
	v_mul_f32_e32 v1, v1, v1
	v_mul_f32_e32 v7, v7, v7
	v_lshlrev_b32_e32 v8, 16, v4
	v_and_b32_e32 v12, 0xffff0000, v5
	v_mul_f32_e32 v9, v9, v9
	v_fmac_f32_e32 v1, v0, v0
	v_fmac_f32_e32 v7, v6, v6
	v_lshlrev_b32_e32 v11, 16, v5
	v_mul_f32_e32 v12, v12, v12
	v_fmac_f32_e32 v9, v8, v8
	v_add_f32_e32 v0, v1, v7
	v_add_f32_e32 v0, v0, v9
	v_fmac_f32_e32 v12, v11, v11
	v_add_f32_e32 v0, v0, v12
	v_add_f32_e32 v0, v10, v0
	ds_bpermute_b32 v1, v120, v0
	global_store_dwordx4 v[24:25], v[2:5], off offset:256
	s_waitcnt lgkmcnt(0)
	v_add_f32_e32 v0, v0, v1
	ds_bpermute_b32 v1, v112, v0
	s_and_saveexec_b64 s[30:31], s[6:7]
	s_cbranch_execz .LBB0_490
	s_waitcnt lgkmcnt(0)
	v_add_f32_e32 v0, v0, v1
	ds_write_b32 v167, v0

; #define PG8_STAGE(bufoff, gbase, voff) do { _Pragma("unroll") for (int _i = 0; _i < 2; ++_i) \
;         __builtin_amdgcn_global_load_lds((const unsigned*)((const char*)(gbase) + (voff)[_i]), (PG8_LAS unsigned*)(lds + (bufoff) + ldsw + _i * 8192), 16, 0, 0); } while (0)
; #define PG8_LDA(dst, b, h) do { _Pragma("unroll") for (int m = 0; m < 4; ++m) _Pragma("unroll") for (int k = 0; k < 2; ++k) dst[m][k] = *(const PG8_LAS bf16x8*)(lds + PG8_SA(b, h) + aoff + m * 2048 + k * 1024); } while (0)
; #define PG8_LDB(dst, b, h) do { _Pragma("unroll") for (int n = 0; n < 2; ++n) _Pragma("unroll") for (int k = 0; k < 2; ++k) dst[n][k] = *(const PG8_LAS bf16x8*)(lds + PG8_SB(b, h) + boff + n * 2048 + k * 1024); } while (0)
; #define PG8_MMA(ai, bj, At, Bt) do { __builtin_amdgcn_s_setprio(1); _Pragma("unroll") for (int m = 0; m < 4; ++m) _Pragma("unroll") for (int n = 0; n < 2; ++n) _Pragma("unroll") for (int k = 0; k < 2; ++k) \
;         acc[ai][bj][m][n] = __builtin_amdgcn_mfma_f32_16x16x32_bf16(Bt[n][k], At[m][k], acc[ai][bj][m][n], 0, 0, 0); __builtin_amdgcn_s_setprio(0); } while (0)
; #define PG8_WAIT_V(n) asm volatile("s_waitcnt vmcnt(" #n ")" ::: "memory")
; #define PG8_WAIT_L(n) asm volatile("s_waitcnt lgkmcnt(" #n ")" ::: "memory")
; #define PG8_BAR __builtin_amdgcn_s_barrier()
; #define PG8_SCHED __builtin_amdgcn_sched_barrier(0)
; template <class Epi, class Sched>
; __device__ __forceinline__ void gemm_phase(PG8_LAS unsigned char* lds, PG8_LAS unsigned char* xl, const Gemm g, const Sched& S, const Epi& E) {
;     ...
;             const char* a1 = cA + (size_t)(t + 1) * kstep;
;             const char* a2 = last ? nA : cA + (size_t)(t + 2) * kstep; const char* b2 = last ? nB : cB + (size_t)(t + 2) * kstep;
;             const char* a3 = a2 + kstep; const char* b3 = b2 + kstep;
;             PG8_LDB(B0, 0, 0); PG8_LDB(B1, 0, 1); PG8_SCHED; PG8_LDA(At, 0, 0); PG8_STAGE(PG8_SA(1, 1), a1 + hsA, voffA);
;             PG8_WAIT_V(8); PG8_WAIT_L(0); PG8_BAR; PG8_MMA(0, 0, At, B0); PG8_MMA(0, 1, At, B1); PG8_BAR; PG8_SCHED;
;             PG8_LDA(At, 0, 1); PG8_STAGE(PG8_SB(0, 0), b2, voffB); PG8_STAGE(PG8_SB(0, 1), b2 + hsB, voffB); PG8_STAGE(PG8_SA(0, 0), a2, voffA);
.LBB0_725:
	ds_read_b128 v[170:173], v157
	ds_read_b128 v[174:177], v157 offset:1024
	ds_read_b128 v[180:183], v157 offset:2048
	ds_read_b128 v[184:187], v157 offset:3072
	ds_read_b128 v[188:191], v158
	ds_read_b128 v[192:195], v158 offset:1024
	ds_read_b128 v[196:199], v158 offset:2048
	ds_read_b128 v[200:203], v158 offset:3072
	s_add_u32 s34, s30, 0xfffc0080
	s_addc_u32 s35, s31, -1
	s_cmp_eq_u32 s75, 12
	s_cselect_b32 s37, s33, s35
	s_cselect_b32 s36, s46, s34
	s_cselect_b32 s35, s47, s74
	s_cselect_b32 s34, s72, s73
	v_lshl_add_u64 v[144:145], s[30:31], 0, v[138:139]
	s_add_i32 m0, s57, 0xc000
	ds_read_b128 v[204:207], v159
	ds_read_b128 v[208:211], v159 offset:1024
	ds_read_b128 v[212:215], v159 offset:2048
	ds_read_b128 v[216:219], v159 offset:3072
	ds_read_b128 v[222:225], v159 offset:4096
	ds_read_b128 v[226:229], v159 offset:5120
	ds_read_b128 v[230:233], v159 offset:6144
	ds_read_b128 v[234:237], v159 offset:7168
	global_load_lds_dwordx4 v[144:145], off
	v_lshl_add_u64 v[144:145], s[30:31], 0, v[136:137]
	s_add_i32 m0, s57, 0xe000
	s_nop 0
	global_load_lds_dwordx4 v[144:145], off
	s_waitcnt vmcnt(8)
	s_waitcnt lgkmcnt(0)
	s_barrier
	s_setprio 1
	s_waitcnt lgkmcnt(0)
	v_mfma_f32_16x16x32_bf16 v[124:127], v[170:173], v[204:207], v[124:127]
	v_mfma_f32_16x16x32_bf16 v[120:123], v[180:183], v[204:207], v[120:123]
	v_mfma_f32_16x16x32_bf16 v[108:111], v[170:173], v[212:215], v[108:111]
	v_mfma_f32_16x16x32_bf16 v[104:107], v[180:183], v[212:215], v[104:107]
	v_mfma_f32_16x16x32_bf16 v[92:95], v[170:173], v[222:225], v[92:95]
	v_mfma_f32_16x16x32_bf16 v[88:91], v[180:183], v[222:225], v[88:91]
	v_mfma_f32_16x16x32_bf16 v[76:79], v[170:173], v[230:233], v[76:79]
	v_mfma_f32_16x16x32_bf16 v[72:75], v[180:183], v[230:233], v[72:75]
	v_mfma_f32_16x16x32_bf16 v[124:127], v[174:177], v[208:211], v[124:127]
	v_mfma_f32_16x16x32_bf16 v[120:123], v[184:187], v[208:211], v[120:123]
	v_mfma_f32_16x16x32_bf16 v[108:111], v[174:177], v[216:219], v[108:111]
	v_mfma_f32_16x16x32_bf16 v[104:107], v[184:187], v[216:219], v[104:107]
	v_mfma_f32_16x16x32_bf16 v[92:95], v[174:177], v[226:229], v[92:95]
	v_mfma_f32_16x16x32_bf16 v[88:91], v[184:187], v[226:229], v[88:91]
	v_mfma_f32_16x16x32_bf16 v[76:79], v[174:177], v[234:237], v[76:79]
	v_mfma_f32_16x16x32_bf16 v[72:75], v[184:187], v[234:237], v[72:75]
	s_setprio 0
	s_setprio 1
	v_mfma_f32_16x16x32_bf16 v[116:119], v[188:191], v[204:207], v[116:119]
	v_mfma_f32_16x16x32_bf16 v[112:115], v[196:199], v[204:207], v[112:115]
	v_mfma_f32_16x16x32_bf16 v[100:103], v[188:191], v[212:215], v[100:103]
	v_mfma_f32_16x16x32_bf16 v[96:99], v[196:199], v[212:215], v[96:99]
	v_mfma_f32_16x16x32_bf16 v[84:87], v[188:191], v[222:225], v[84:87]
	v_mfma_f32_16x16x32_bf16 v[80:83], v[196:199], v[222:225], v[80:83]
	v_mfma_f32_16x16x32_bf16 v[68:71], v[188:191], v[230:233], v[68:71]
	v_mfma_f32_16x16x32_bf16 v[64:67], v[196:199], v[230:233], v[64:67]
	v_mfma_f32_16x16x32_bf16 v[116:119], v[192:195], v[208:211], v[116:119]
	v_mfma_f32_16x16x32_bf16 v[112:115], v[200:203], v[208:211], v[112:115]
	v_mfma_f32_16x16x32_bf16 v[100:103], v[192:195], v[216:219], v[100:103]
	v_mfma_f32_16x16x32_bf16 v[96:99], v[200:203], v[216:219], v[96:99]
	v_mfma_f32_16x16x32_bf16 v[84:87], v[192:195], v[226:229], v[84:87]
	v_mfma_f32_16x16x32_bf16 v[80:83], v[200:203], v[226:229], v[80:83]
	v_mfma_f32_16x16x32_bf16 v[68:71], v[192:195], v[234:237], v[68:71]
	v_mfma_f32_16x16x32_bf16 v[64:67], v[200:203], v[234:237], v[64:67]
	s_setprio 0
	s_barrier
	s_add_i32 s68, s65, s56
	v_lshl_add_u64 v[144:145], s[34:35], 0, v[130:131]
	s_mov_b32 m0, s68
	ds_read_b128 v[204:207], v159 offset:16384
	ds_read_b128 v[208:211], v159 offset:17408
	ds_read_b128 v[212:215], v159 offset:18432
	ds_read_b128 v[216:219], v159 offset:19456
	ds_read_b128 v[222:225], v159 offset:20480
	ds_read_b128 v[226:229], v159 offset:21504
	ds_read_b128 v[230:233], v159 offset:22528
	ds_read_b128 v[234:237], v159 offset:23552
	global_load_lds_dwordx4 v[144:145], off
	s_add_i32 m0, s68, 0x2000
	s_add_u32 s76, s34, 0x40000
	v_lshl_add_u64 v[238:239], s[34:35], 0, v[134:135]
	s_addc_u32 s77, s35, 0
	s_add_i32 s68, s66, s56
	global_load_lds_dwordx4 v[238:239], off
	v_lshl_add_u64 v[240:241], s[76:77], 0, v[130:131]
	s_mov_b32 m0, s68
	v_lshl_add_u64 v[242:243], s[36:37], 0, v[132:133]
	global_load_lds_dwordx4 v[240:241], off
	v_lshl_add_u64 v[240:241], s[76:77], 0, v[134:135]
	s_add_i32 m0, s68, 0x2000
	s_nop 0
	global_load_lds_dwordx4 v[240:241], off
	v_lshl_add_u64 v[240:241], s[36:37], 0, v[128:129]
	s_mov_b32 m0, s57
	s_nop 0
	global_load_lds_dwordx4 v[240:241], off
	s_mov_b32 m0, s58
	s_nop 0
	global_load_lds_dwordx4 v[242:243], off
	s_waitcnt vmcnt(8)
	s_waitcnt lgkmcnt(0)
	s_barrier
; #define PG8_STAGE(bufoff, gbase, voff) do { _Pragma("unroll") for (int _i = 0; _i < 2; ++_i) \
;         __builtin_amdgcn_global_load_lds((const unsigned*)((const char*)(gbase) + (voff)[_i]), (PG8_LAS unsigned*)(lds + (bufoff) + ldsw + _i * 8192), 16, 0, 0); } while (0)
; #define PG8_LDA(dst, b, h) do { _Pragma("unroll") for (int m = 0; m < 4; ++m) _Pragma("unroll") for (int k = 0; k < 2; ++k) dst[m][k] = *(const PG8_LAS bf16x8*)(lds + PG8_SA(b, h) + aoff + m * 2048 + k * 1024); } while (0)
; #define PG8_LDB(dst, b, h) do { _Pragma("unroll") for (int n = 0; n < 2; ++n) _Pragma("unroll") for (int k = 0; k < 2; ++k) dst[n][k] = *(const PG8_LAS bf16x8*)(lds + PG8_SB(b, h) + boff + n * 2048 + k * 1024); } while (0)
; #define PG8_MMA(ai, bj, At, Bt) do { __builtin_amdgcn_s_setprio(1); _Pragma("unroll") for (int m = 0; m < 4; ++m) _Pragma("unroll") for (int n = 0; n < 2; ++n) _Pragma("unroll") for (int k = 0; k < 2; ++k) \
;         acc[ai][bj][m][n] = __builtin_amdgcn_mfma_f32_16x16x32_bf16(Bt[n][k], At[m][k], acc[ai][bj][m][n], 0, 0, 0); __builtin_amdgcn_s_setprio(0); } while (0)
; #define PG8_WAIT_V(n) asm volatile("s_waitcnt vmcnt(" #n ")" ::: "memory")
; #define PG8_WAIT_L(n) asm volatile("s_waitcnt lgkmcnt(" #n ")" ::: "memory")
; #define PG8_BAR __builtin_amdgcn_s_barrier()
; #define PG8_SCHED __builtin_amdgcn_sched_barrier(0)
; template <class Epi, class Sched>
; __device__ __forceinline__ void gemm_phase(PG8_LAS unsigned char* lds, PG8_LAS unsigned char* xl, const Gemm g, const Sched& S, const Epi& E) {
;     ...
;             PG8_WAIT_V(8); PG8_WAIT_L(0); PG8_BAR; PG8_MMA(1, 0, At, B0); PG8_MMA(1, 1, At, B1); PG8_BAR; PG8_SCHED;
;             PG8_LDB(B0, 1, 0); PG8_LDB(B1, 1, 1); PG8_SCHED; PG8_LDA(At, 1, 0); PG8_STAGE(PG8_SA(0, 1), a2 + hsA, voffA);
;             PG8_WAIT_V(8); PG8_WAIT_L(0); PG8_BAR; PG8_MMA(0, 0, At, B0); PG8_MMA(0, 1, At, B1); PG8_BAR; PG8_SCHED;
	s_setprio 1
	s_waitcnt lgkmcnt(0)
	v_mfma_f32_16x16x32_bf16 v[60:63], v[170:173], v[204:207], v[60:63]
	v_mfma_f32_16x16x32_bf16 v[56:59], v[180:183], v[204:207], v[56:59]
	v_mfma_f32_16x16x32_bf16 v[44:47], v[170:173], v[212:215], v[44:47]
	v_mfma_f32_16x16x32_bf16 v[40:43], v[180:183], v[212:215], v[40:43]
	v_mfma_f32_16x16x32_bf16 v[28:31], v[170:173], v[222:225], v[28:31]
	v_mfma_f32_16x16x32_bf16 v[24:27], v[180:183], v[222:225], v[24:27]
	v_mfma_f32_16x16x32_bf16 v[12:15], v[170:173], v[230:233], v[12:15]
	v_mfma_f32_16x16x32_bf16 v[8:11], v[180:183], v[230:233], v[8:11]
	v_mfma_f32_16x16x32_bf16 v[60:63], v[174:177], v[208:211], v[60:63]
	v_mfma_f32_16x16x32_bf16 v[56:59], v[184:187], v[208:211], v[56:59]
	v_mfma_f32_16x16x32_bf16 v[44:47], v[174:177], v[216:219], v[44:47]
	v_mfma_f32_16x16x32_bf16 v[40:43], v[184:187], v[216:219], v[40:43]
	v_mfma_f32_16x16x32_bf16 v[28:31], v[174:177], v[226:229], v[28:31]
	v_mfma_f32_16x16x32_bf16 v[24:27], v[184:187], v[226:229], v[24:27]
	v_mfma_f32_16x16x32_bf16 v[12:15], v[174:177], v[234:237], v[12:15]
	v_mfma_f32_16x16x32_bf16 v[8:11], v[184:187], v[234:237], v[8:11]
	s_setprio 0
	s_setprio 1
	v_mfma_f32_16x16x32_bf16 v[52:55], v[188:191], v[204:207], v[52:55]
	v_mfma_f32_16x16x32_bf16 v[48:51], v[196:199], v[204:207], v[48:51]
	v_mfma_f32_16x16x32_bf16 v[36:39], v[188:191], v[212:215], v[36:39]
	v_mfma_f32_16x16x32_bf16 v[32:35], v[196:199], v[212:215], v[32:35]
	v_mfma_f32_16x16x32_bf16 v[20:23], v[188:191], v[222:225], v[20:23]
	v_mfma_f32_16x16x32_bf16 v[16:19], v[196:199], v[222:225], v[16:19]
	v_mfma_f32_16x16x32_bf16 v[4:7], v[188:191], v[230:233], v[4:7]
	v_mfma_f32_16x16x32_bf16 v[0:3], v[196:199], v[230:233], v[0:3]
	v_mfma_f32_16x16x32_bf16 v[52:55], v[192:195], v[208:211], v[52:55]
	v_mfma_f32_16x16x32_bf16 v[48:51], v[200:203], v[208:211], v[48:51]
	v_mfma_f32_16x16x32_bf16 v[36:39], v[192:195], v[216:219], v[36:39]
	v_mfma_f32_16x16x32_bf16 v[32:35], v[200:203], v[216:219], v[32:35]
	v_mfma_f32_16x16x32_bf16 v[20:23], v[192:195], v[226:229], v[20:23]
	v_mfma_f32_16x16x32_bf16 v[16:19], v[200:203], v[226:229], v[16:19]
	v_mfma_f32_16x16x32_bf16 v[4:7], v[192:195], v[234:237], v[4:7]
	v_mfma_f32_16x16x32_bf16 v[0:3], v[200:203], v[234:237], v[0:3]
	s_setprio 0
	s_barrier
	s_add_i32 s68, 0, 0x18000
	v_add_u32_e32 v169, s68, v147
	s_add_i32 s76, 0, 0x1c000
	ds_read_b128 v[170:173], v169
	ds_read_b128 v[174:177], v169 offset:1024
	ds_read_b128 v[180:183], v169 offset:2048
	ds_read_b128 v[184:187], v169 offset:3072
	v_add_u32_e32 v169, s76, v147
	ds_read_b128 v[188:191], v169
	ds_read_b128 v[192:195], v169 offset:1024
	ds_read_b128 v[196:199], v169 offset:2048
	ds_read_b128 v[200:203], v169 offset:3072
	s_add_u32 s36, s36, 0x40000
	s_addc_u32 s37, s37, 0
	s_mov_b32 m0, s59
	v_lshl_add_u64 v[244:245], s[36:37], 0, v[128:129]
	ds_read_b128 v[204:207], v159 offset:32768
	ds_read_b128 v[208:211], v159 offset:33792
	ds_read_b128 v[212:215], v159 offset:34816
	ds_read_b128 v[216:219], v159 offset:35840
	ds_read_b128 v[222:225], v159 offset:36864
	ds_read_b128 v[226:229], v159 offset:37888
	ds_read_b128 v[230:233], v159 offset:38912
	ds_read_b128 v[234:237], v159 offset:39936
	global_load_lds_dwordx4 v[244:245], off
	v_lshl_add_u64 v[244:245], s[36:37], 0, v[132:133]
	s_mov_b32 m0, s60
	s_nop 0
	global_load_lds_dwordx4 v[244:245], off
	s_waitcnt vmcnt(8)
	s_waitcnt lgkmcnt(0)
	s_barrier
	s_setprio 1
	s_waitcnt lgkmcnt(0)
	v_mfma_f32_16x16x32_bf16 v[124:127], v[170:173], v[204:207], v[124:127]
	v_mfma_f32_16x16x32_bf16 v[120:123], v[180:183], v[204:207], v[120:123]
	v_mfma_f32_16x16x32_bf16 v[108:111], v[170:173], v[212:215], v[108:111]
	v_mfma_f32_16x16x32_bf16 v[104:107], v[180:183], v[212:215], v[104:107]
	v_mfma_f32_16x16x32_bf16 v[92:95], v[170:173], v[222:225], v[92:95]
	v_mfma_f32_16x16x32_bf16 v[88:91], v[180:183], v[222:225], v[88:91]
	v_mfma_f32_16x16x32_bf16 v[76:79], v[170:173], v[230:233], v[76:79]
	v_mfma_f32_16x16x32_bf16 v[72:75], v[180:183], v[230:233], v[72:75]
	v_mfma_f32_16x16x32_bf16 v[124:127], v[174:177], v[208:211], v[124:127]
	v_mfma_f32_16x16x32_bf16 v[120:123], v[184:187], v[208:211], v[120:123]
	v_mfma_f32_16x16x32_bf16 v[108:111], v[174:177], v[216:219], v[108:111]
	v_mfma_f32_16x16x32_bf16 v[104:107], v[184:187], v[216:219], v[104:107]
	v_mfma_f32_16x16x32_bf16 v[92:95], v[174:177], v[226:229], v[92:95]
	v_mfma_f32_16x16x32_bf16 v[88:91], v[184:187], v[226:229], v[88:91]
	v_mfma_f32_16x16x32_bf16 v[76:79], v[174:177], v[234:237], v[76:79]
	v_mfma_f32_16x16x32_bf16 v[72:75], v[184:187], v[234:237], v[72:75]
	s_setprio 0
	s_setprio 1
	v_mfma_f32_16x16x32_bf16 v[116:119], v[188:191], v[204:207], v[116:119]
	v_mfma_f32_16x16x32_bf16 v[112:115], v[196:199], v[204:207], v[112:115]
	v_mfma_f32_16x16x32_bf16 v[100:103], v[188:191], v[212:215], v[100:103]
	v_mfma_f32_16x16x32_bf16 v[96:99], v[196:199], v[212:215], v[96:99]
	v_mfma_f32_16x16x32_bf16 v[84:87], v[188:191], v[222:225], v[84:87]
	v_mfma_f32_16x16x32_bf16 v[80:83], v[196:199], v[222:225], v[80:83]
	v_mfma_f32_16x16x32_bf16 v[68:71], v[188:191], v[230:233], v[68:71]
	v_mfma_f32_16x16x32_bf16 v[64:67], v[196:199], v[230:233], v[64:67]
	v_mfma_f32_16x16x32_bf16 v[116:119], v[192:195], v[208:211], v[116:119]
	v_mfma_f32_16x16x32_bf16 v[112:115], v[200:203], v[208:211], v[112:115]
	v_mfma_f32_16x16x32_bf16 v[100:103], v[192:195], v[216:219], v[100:103]
	v_mfma_f32_16x16x32_bf16 v[96:99], v[200:203], v[216:219], v[96:99]
	v_mfma_f32_16x16x32_bf16 v[84:87], v[192:195], v[226:229], v[84:87]
	v_mfma_f32_16x16x32_bf16 v[80:83], v[200:203], v[226:229], v[80:83]
	v_mfma_f32_16x16x32_bf16 v[68:71], v[192:195], v[234:237], v[68:71]
	v_mfma_f32_16x16x32_bf16 v[64:67], v[200:203], v[234:237], v[64:67]
	s_setprio 0
	s_barrier
; #define PG8_STAGE(bufoff, gbase, voff) do { _Pragma("unroll") for (int _i = 0; _i < 2; ++_i) \
;         __builtin_amdgcn_global_load_lds((const unsigned*)((const char*)(gbase) + (voff)[_i]), (PG8_LAS unsigned*)(lds + (bufoff) + ldsw + _i * 8192), 16, 0, 0); } while (0)
; #define PG8_LDA(dst, b, h) do { _Pragma("unroll") for (int m = 0; m < 4; ++m) _Pragma("unroll") for (int k = 0; k < 2; ++k) dst[m][k] = *(const PG8_LAS bf16x8*)(lds + PG8_SA(b, h) + aoff + m * 2048 + k * 1024); } while (0)
; #define PG8_MMA(ai, bj, At, Bt) do { __builtin_amdgcn_s_setprio(1); _Pragma("unroll") for (int m = 0; m < 4; ++m) _Pragma("unroll") for (int n = 0; n < 2; ++n) _Pragma("unroll") for (int k = 0; k < 2; ++k) \
;         acc[ai][bj][m][n] = __builtin_amdgcn_mfma_f32_16x16x32_bf16(Bt[n][k], At[m][k], acc[ai][bj][m][n], 0, 0, 0); __builtin_amdgcn_s_setprio(0); } while (0)
; #define PG8_WAIT_V(n) asm volatile("s_waitcnt vmcnt(" #n ")" ::: "memory")
; #define PG8_WAIT_L(n) asm volatile("s_waitcnt lgkmcnt(" #n ")" ::: "memory")
; #define PG8_BAR __builtin_amdgcn_s_barrier()
; #define PG8_SCHED __builtin_amdgcn_sched_barrier(0)
;     __device__ __forceinline__ void operator()(Acc& acc, const Unit& u, int wr, int wc, int fr, int fq, PG8_LAS unsigned char* xl) const {
;     ...
;             for (int m = 0; m < 4; ++m) { const int rl = ai * HALF + wr * 64 + m * 16 + fr; const int row = u.r0 + rl; const size_t off = (size_t)row * DM + col; float s = 0.f;
; #pragma unroll
;                 for (int bj = 0; bj < 2; ++bj) {
;                     f32x4 b0, b1;
;                     if (BASE_BF16) unpack8(*(const u32x4*)((const bf16_t*)base + off + bj * HALF), b0, b1);
; template <class Epi, class Sched>
; __device__ __forceinline__ void gemm_phase(PG8_LAS unsigned char* lds, PG8_LAS unsigned char* xl, const Gemm g, const Sched& S, const Epi& E) {
;     ...
;             PG8_LDA(At, 1, 1); PG8_STAGE(PG8_SB(1, 0), b3, voffB); PG8_STAGE(PG8_SB(1, 1), b3 + hsB, voffB); PG8_STAGE(PG8_SA(1, 0), a3, voffA);
;             PG8_WAIT_V(8); PG8_WAIT_L(0); PG8_BAR; PG8_MMA(1, 0, At, B0); PG8_MMA(1, 1, At, B1); PG8_BAR; PG8_SCHED;
;         }
;         if (wr == 0) PG8_BAR;
;         E(acc, cur, wr, wc, fr, fq, xl);
	s_add_i32 s36, s68, s56
	v_lshl_add_u64 v[144:145], v[144:145], 0, s[16:17]
	s_mov_b32 m0, s36
	ds_read_b128 v[204:207], v159 offset:49152
	ds_read_b128 v[208:211], v159 offset:50176
	ds_read_b128 v[212:215], v159 offset:51200
	ds_read_b128 v[216:219], v159 offset:52224
	ds_read_b128 v[222:225], v159 offset:53248
	ds_read_b128 v[226:229], v159 offset:54272
	ds_read_b128 v[230:233], v159 offset:55296
	ds_read_b128 v[234:237], v159 offset:56320
	global_load_lds_dwordx4 v[144:145], off
	s_add_i32 m0, s36, 0x2000
	s_add_u32 s34, s34, 0x40080
	v_lshl_add_u64 v[144:145], v[238:239], 0, s[16:17]
	s_addc_u32 s35, s35, 0
	s_add_i32 s36, s76, s56
	global_load_lds_dwordx4 v[144:145], off
	v_lshl_add_u64 v[144:145], s[34:35], 0, v[130:131]
	s_mov_b32 m0, s36
	s_nop 0
	global_load_lds_dwordx4 v[144:145], off
	v_lshl_add_u64 v[144:145], s[34:35], 0, v[134:135]
	s_add_i32 m0, s36, 0x2000
	s_nop 0
	global_load_lds_dwordx4 v[144:145], off
	v_lshl_add_u64 v[144:145], v[240:241], 0, s[16:17]
	s_mov_b32 m0, s62
	s_nop 0
	global_load_lds_dwordx4 v[144:145], off
	v_lshl_add_u64 v[144:145], v[242:243], 0, s[16:17]
	s_mov_b32 m0, s63
	s_nop 0
	global_load_lds_dwordx4 v[144:145], off
	s_waitcnt vmcnt(8)
	s_waitcnt lgkmcnt(0)
	s_barrier
	s_setprio 1
	s_waitcnt lgkmcnt(0)
	v_mfma_f32_16x16x32_bf16 v[60:63], v[170:173], v[204:207], v[60:63]
	v_mfma_f32_16x16x32_bf16 v[56:59], v[180:183], v[204:207], v[56:59]
	v_mfma_f32_16x16x32_bf16 v[44:47], v[170:173], v[212:215], v[44:47]
	v_mfma_f32_16x16x32_bf16 v[40:43], v[180:183], v[212:215], v[40:43]
	v_mfma_f32_16x16x32_bf16 v[28:31], v[170:173], v[222:225], v[28:31]
	v_mfma_f32_16x16x32_bf16 v[24:27], v[180:183], v[222:225], v[24:27]
	v_mfma_f32_16x16x32_bf16 v[12:15], v[170:173], v[230:233], v[12:15]
	v_mfma_f32_16x16x32_bf16 v[8:11], v[180:183], v[230:233], v[8:11]
	v_mfma_f32_16x16x32_bf16 v[60:63], v[174:177], v[208:211], v[60:63]
	v_mfma_f32_16x16x32_bf16 v[56:59], v[184:187], v[208:211], v[56:59]
	v_mfma_f32_16x16x32_bf16 v[44:47], v[174:177], v[216:219], v[44:47]
	v_mfma_f32_16x16x32_bf16 v[40:43], v[184:187], v[216:219], v[40:43]
	v_mfma_f32_16x16x32_bf16 v[28:31], v[174:177], v[226:229], v[28:31]
	v_mfma_f32_16x16x32_bf16 v[24:27], v[184:187], v[226:229], v[24:27]
	v_mfma_f32_16x16x32_bf16 v[12:15], v[174:177], v[234:237], v[12:15]
	v_mfma_f32_16x16x32_bf16 v[8:11], v[184:187], v[234:237], v[8:11]
	s_setprio 0
	s_setprio 1
	v_mfma_f32_16x16x32_bf16 v[52:55], v[188:191], v[204:207], v[52:55]
	v_mfma_f32_16x16x32_bf16 v[48:51], v[196:199], v[204:207], v[48:51]
	v_mfma_f32_16x16x32_bf16 v[36:39], v[188:191], v[212:215], v[36:39]
	v_mfma_f32_16x16x32_bf16 v[32:35], v[196:199], v[212:215], v[32:35]
	v_mfma_f32_16x16x32_bf16 v[20:23], v[188:191], v[222:225], v[20:23]
	v_mfma_f32_16x16x32_bf16 v[16:19], v[196:199], v[222:225], v[16:19]
	v_mfma_f32_16x16x32_bf16 v[4:7], v[188:191], v[230:233], v[4:7]
	v_mfma_f32_16x16x32_bf16 v[0:3], v[196:199], v[230:233], v[0:3]
	v_mfma_f32_16x16x32_bf16 v[52:55], v[192:195], v[208:211], v[52:55]
	v_mfma_f32_16x16x32_bf16 v[48:51], v[200:203], v[208:211], v[48:51]
	v_mfma_f32_16x16x32_bf16 v[36:39], v[192:195], v[216:219], v[36:39]
	v_mfma_f32_16x16x32_bf16 v[32:35], v[200:203], v[216:219], v[32:35]
	v_mfma_f32_16x16x32_bf16 v[20:23], v[192:195], v[226:229], v[20:23]
	v_mfma_f32_16x16x32_bf16 v[16:19], v[200:203], v[226:229], v[16:19]
	v_mfma_f32_16x16x32_bf16 v[4:7], v[192:195], v[234:237], v[4:7]
	v_mfma_f32_16x16x32_bf16 v[0:3], v[200:203], v[234:237], v[0:3]
	s_setprio 0
	s_barrier
	s_add_i32 s75, s75, 2
	s_add_u32 s73, s73, 0x100
	s_addc_u32 s74, s74, 0
	s_add_u32 s30, s30, 0x100
	s_addc_u32 s31, s31, 0
	s_cmp_gt_u32 s75, 13
	s_cbranch_scc0 .LBB0_725
	v_add_u32_e32 v252, s53, v148
	v_ashrrev_i32_e32 v253, 31, v252
	v_add_u32_e32 v222, s55, v146
	v_ashrrev_i32_e32 v223, 31, v222
	v_lshlrev_b64 v[222:223], 10, v[222:223]
	v_lshl_add_u64 v[222:223], v[222:223], 0, v[252:253]
	v_lshl_add_u64 v[222:223], v[222:223], 1, s[10:11]
	global_load_dwordx4 v[184:187], v[222:223], off
	global_load_dwordx4 v[188:191], v[222:223], off offset:256
	v_add_u32_e32 v222, s55, v149
	v_ashrrev_i32_e32 v223, 31, v222
	v_lshlrev_b64 v[222:223], 10, v[222:223]
	v_lshl_add_u64 v[222:223], v[222:223], 0, v[252:253]
	v_lshl_add_u64 v[222:223], v[222:223], 1, s[10:11]
	global_load_dwordx4 v[192:195], v[222:223], off
	global_load_dwordx4 v[196:199], v[222:223], off offset:256
	v_add_u32_e32 v222, s55, v150
	v_ashrrev_i32_e32 v223, 31, v222
	v_lshlrev_b64 v[222:223], 10, v[222:223]
	v_lshl_add_u64 v[222:223], v[222:223], 0, v[252:253]
	v_lshl_add_u64 v[222:223], v[222:223], 1, s[10:11]
	global_load_dwordx4 v[200:203], v[222:223], off
	global_load_dwordx4 v[204:207], v[222:223], off offset:256
	v_add_u32_e32 v222, s55, v151
	v_ashrrev_i32_e32 v223, 31, v222
	v_lshlrev_b64 v[222:223], 10, v[222:223]
	v_lshl_add_u64 v[222:223], v[222:223], 0, v[252:253]
	v_lshl_add_u64 v[222:223], v[222:223], 1, s[10:11]
	global_load_dwordx4 v[208:211], v[222:223], off
	global_load_dwordx4 v[212:215], v[222:223], off offset:256
	v_add_u32_e32 v222, s55, v152
	v_ashrrev_i32_e32 v223, 31, v222
	v_lshlrev_b64 v[222:223], 10, v[222:223]
	v_lshl_add_u64 v[222:223], v[222:223], 0, v[252:253]
	v_lshl_add_u64 v[222:223], v[222:223], 1, s[10:11]
	global_load_dwordx4 v[216:219], v[222:223], off
	global_load_dwordx4 v[224:227], v[222:223], off offset:256
	v_add_u32_e32 v222, s55, v153
	v_ashrrev_i32_e32 v223, 31, v222
	v_lshlrev_b64 v[222:223], 10, v[222:223]
	v_lshl_add_u64 v[222:223], v[222:223], 0, v[252:253]
	v_lshl_add_u64 v[222:223], v[222:223], 1, s[10:11]
	global_load_dwordx4 v[228:231], v[222:223], off
	global_load_dwordx4 v[232:235], v[222:223], off offset:256
	v_add_u32_e32 v222, s55, v155
	v_ashrrev_i32_e32 v223, 31, v222
	v_lshlrev_b64 v[222:223], 10, v[222:223]
	v_lshl_add_u64 v[222:223], v[222:223], 0, v[252:253]
	v_lshl_add_u64 v[222:223], v[222:223], 1, s[10:11]
	global_load_dwordx4 v[236:239], v[222:223], off
	global_load_dwordx4 v[240:243], v[222:223], off offset:256
	v_add_u32_e32 v222, s55, v156
	v_ashrrev_i32_e32 v223, 31, v222
	v_lshlrev_b64 v[222:223], 10, v[222:223]
	v_lshl_add_u64 v[222:223], v[222:223], 0, v[252:253]
	v_lshl_add_u64 v[222:223], v[222:223], 1, s[10:11]
	global_load_dwordx4 v[244:247], v[222:223], off
	global_load_dwordx4 v[248:251], v[222:223], off offset:256
	s_and_b64 vcc, exec, s[18:19]
	s_cbranch_vccz .LBB0_728
	s_barrier
; __device__ __forceinline__ u32x4 pack8(f32x4 v0, f32x4 v1) { u32x4 w; w.x = cvt_pk_bf16(v0[0], v0[1]); w.y = cvt_pk_bf16(v0[2], v0[3]); w.z = cvt_pk_bf16(v1[0], v1[1]); w.w = cvt_pk_bf16(v1[2], v1[3]); return w; }
;     __device__ __forceinline__ void operator()(Acc& acc, const Unit& u, int wr, int wc, int fr, int fq, PG8_LAS unsigned char* xl) const {
;     ...
;             for (int m = 0; m < 4; ++m) { const int rl = ai * HALF + wr * 64 + m * 16 + fr; const int row = u.r0 + rl; const size_t off = (size_t)row * DM + col; float s = 0.f;
; #pragma unroll
;                 for (int bj = 0; bj < 2; ++bj) {
;                     f32x4 b0, b1;
;                     if (BASE_BF16) unpack8(*(const u32x4*)((const bf16_t*)base + off + bj * HALF), b0, b1);
;                     else { b0 = *(const f32x4*)((const float*)base + off + bj * HALF); b1 = *(const f32x4*)((const float*)base + off + bj * HALF + 4); }
;                     const u32x4 w = pack8(acc[ai][bj][m][0] + b0, acc[ai][bj][m][1] + b1);
;                     *(u32x4*)(outB + off + bj * HALF) = w;
;                     f32x4 v0, v1; unpack8(w, v0, v1);
;                     s += (v0[0] * v0[0] + v0[1] * v0[1]) + (v0[2] * v0[2] + v0[3] * v0[3]) + (v1[0] * v1[0] + v1[1] * v1[1]) + (v1[2] * v1[2] + v1[3] * v1[3]); }
;                 s += __shfl_xor(s, 16); s += __shfl_xor(s, 32);
;                 if (fq == 0) X[rl * 4 + wc] = s; }
.LBB0_728:
	v_add_u32_e32 v170, s55, v146
	v_add_u32_e32 v144, s53, v148
	v_ashrrev_i32_e32 v171, 31, v170
	v_ashrrev_i32_e32 v145, 31, v144
	v_lshlrev_b64 v[170:171], 10, v[170:171]
	v_lshl_add_u64 v[170:171], v[170:171], 0, v[144:145]
	v_lshlrev_b64 v[174:175], 1, v[170:171]
	v_lshl_add_u64 v[176:177], s[10:11], 0, v[174:175]
	s_nop 0
	v_lshl_add_u64 v[174:175], s[12:13], 0, v[174:175]
	s_waitcnt vmcnt(15) lgkmcnt(0)
	v_lshlrev_b32_e32 v180, 16, v184
	v_and_b32_e32 v181, 0xffff0000, v184
	v_lshlrev_b32_e32 v170, 16, v185
	v_and_b32_e32 v171, 0xffff0000, v185
	v_lshlrev_b32_e32 v182, 16, v186
	v_and_b32_e32 v183, 0xffff0000, v186
	v_lshlrev_b32_e32 v172, 16, v187
	v_and_b32_e32 v173, 0xffff0000, v187
	v_pk_add_f32 v[124:125], v[124:125], v[180:181]
	v_pk_add_f32 v[126:127], v[126:127], v[170:171]
	v_pk_add_f32 v[170:171], v[122:123], v[172:173]
	v_pk_add_f32 v[120:121], v[120:121], v[182:183]
	v_cvt_pk_bf16_f32 v122, v124, v125
	v_cvt_pk_bf16_f32 v123, v126, v127
	s_nop 0
	v_cvt_pk_bf16_f32 v124, v120, v121
	v_cvt_pk_bf16_f32 v125, v170, v171
	global_store_dwordx4 v[174:175], v[122:125], off
	s_nop 0
	v_lshlrev_b32_e32 v126, 16, v122
	v_and_b32_e32 v122, 0xffff0000, v122
	v_lshlrev_b32_e32 v127, 16, v123
	v_and_b32_e32 v123, 0xffff0000, v123
	v_lshlrev_b32_e32 v169, 16, v124
	v_and_b32_e32 v124, 0xffff0000, v124
	v_mul_f32_e32 v122, v122, v122
	v_mul_f32_e32 v123, v123, v123
	v_lshlrev_b32_e32 v176, 16, v125
	v_and_b32_e32 v125, 0xffff0000, v125
	v_mul_f32_e32 v124, v124, v124
	v_fmac_f32_e32 v122, v126, v126
	v_fmac_f32_e32 v123, v127, v127
	v_mul_f32_e32 v125, v125, v125
	v_fmac_f32_e32 v124, v169, v169
	v_add_f32_e32 v122, v122, v123
	v_fmac_f32_e32 v125, v176, v176
	v_add_f32_e32 v122, v122, v124
	v_add_f32_e32 v169, v122, v125
	v_and_b32_e32 v121, 64, v160
	v_xor_b32_e32 v120, 16, v160
	v_add_u32_e32 v121, 64, v121
	v_cmp_lt_i32_e32 vcc, v120, v121
	s_waitcnt vmcnt(15) lgkmcnt(0)
	v_lshlrev_b32_e32 v122, 16, v188
	v_and_b32_e32 v123, 0xffff0000, v188
	v_lshlrev_b32_e32 v124, 16, v189
	v_and_b32_e32 v125, 0xffff0000, v189
	v_lshlrev_b32_e32 v126, 16, v190
	v_and_b32_e32 v127, 0xffff0000, v190
	v_lshlrev_b32_e32 v170, 16, v191
	v_and_b32_e32 v171, 0xffff0000, v191
	v_pk_add_f32 v[118:119], v[118:119], v[124:125]
	v_pk_add_f32 v[116:117], v[116:117], v[122:123]
	v_pk_add_f32 v[114:115], v[114:115], v[170:171]
	v_pk_add_f32 v[112:113], v[112:113], v[126:127]
	v_cvt_pk_bf16_f32 v116, v116, v117
	v_cvt_pk_bf16_f32 v117, v118, v119
	v_cndmask_b32_e32 v120, v160, v120, vcc
	v_cvt_pk_bf16_f32 v118, v112, v113
	v_cvt_pk_bf16_f32 v119, v114, v115
	v_and_b32_e32 v113, 0xffff0000, v116
	v_and_b32_e32 v115, 0xffff0000, v117
	v_lshlrev_b32_e32 v112, 16, v116
	v_lshlrev_b32_e32 v114, 16, v117
	v_and_b32_e32 v123, 0xffff0000, v118
	v_mul_f32_e32 v113, v113, v113
	v_mul_f32_e32 v115, v115, v115
	v_lshlrev_b32_e32 v122, 16, v118
	v_and_b32_e32 v125, 0xffff0000, v119
	v_mul_f32_e32 v123, v123, v123
	v_fmac_f32_e32 v113, v112, v112
	v_fmac_f32_e32 v115, v114, v114
	v_lshlrev_b32_e32 v124, 16, v119
	v_mul_f32_e32 v125, v125, v125
	v_fmac_f32_e32 v123, v122, v122
	v_add_f32_e32 v112, v113, v115
	v_fmac_f32_e32 v125, v124, v124
	v_add_f32_e32 v112, v112, v123
	v_add_f32_e32 v112, v112, v125
	v_lshlrev_b32_e32 v120, 2, v120
	v_add_f32_e32 v112, v169, v112
	ds_bpermute_b32 v113, v120, v112
	v_xor_b32_e32 v114, 32, v160
	v_cmp_lt_i32_e32 vcc, v114, v121
	global_store_dwordx4 v[174:175], v[116:119], off offset:256
	s_waitcnt lgkmcnt(0)
	v_add_f32_e32 v113, v112, v113
	v_cndmask_b32_e32 v114, v160, v114, vcc
	v_lshlrev_b32_e32 v112, 2, v114
	ds_bpermute_b32 v114, v112, v113
	s_and_saveexec_b64 s[30:31], s[6:7]
	s_cbranch_execz .LBB0_730
	s_waitcnt lgkmcnt(0)
	v_add_f32_e32 v113, v113, v114
	ds_write_b32 v161, v113
.LBB0_730:
	s_or_b64 exec, exec, s[30:31]
	s_waitcnt lgkmcnt(0)
	v_add_u32_e32 v114, s55, v149
	v_ashrrev_i32_e32 v115, 31, v114
	v_lshlrev_b64 v[114:115], 10, v[114:115]
	v_lshl_add_u64 v[114:115], v[114:115], 0, v[144:145]
	v_lshlrev_b64 v[118:119], 1, v[114:115]
	v_lshl_add_u64 v[122:123], s[10:11], 0, v[118:119]
	s_nop 0
	v_lshl_add_u64 v[118:119], s[12:13], 0, v[118:119]
	s_waitcnt vmcnt(15) lgkmcnt(0)
	v_lshlrev_b32_e32 v124, 16, v192
	v_and_b32_e32 v125, 0xffff0000, v192
	v_lshlrev_b32_e32 v114, 16, v193
	v_and_b32_e32 v115, 0xffff0000, v193
	v_lshlrev_b32_e32 v126, 16, v194
	v_and_b32_e32 v127, 0xffff0000, v194
	v_lshlrev_b32_e32 v116, 16, v195
	v_and_b32_e32 v117, 0xffff0000, v195
	v_pk_add_f32 v[110:111], v[110:111], v[114:115]
	v_pk_add_f32 v[114:115], v[106:107], v[116:117]
	v_pk_add_f32 v[106:107], v[104:105], v[126:127]
	v_pk_add_f32 v[108:109], v[108:109], v[124:125]
	s_nop 0
	v_cvt_pk_bf16_f32 v104, v108, v109
	v_cvt_pk_bf16_f32 v105, v110, v111
	v_cvt_pk_bf16_f32 v106, v106, v107
	v_cvt_pk_bf16_f32 v107, v114, v115
	global_store_dwordx4 v[118:119], v[104:107], off
	s_nop 0
	v_lshlrev_b32_e32 v113, 16, v104
	v_and_b32_e32 v104, 0xffff0000, v104
	v_lshlrev_b32_e32 v114, 16, v105
	v_and_b32_e32 v105, 0xffff0000, v105
	v_lshlrev_b32_e32 v115, 16, v106
	v_and_b32_e32 v106, 0xffff0000, v106
	v_mul_f32_e32 v104, v104, v104
	v_mul_f32_e32 v105, v105, v105
	v_lshlrev_b32_e32 v116, 16, v107
	v_and_b32_e32 v107, 0xffff0000, v107
	v_mul_f32_e32 v106, v106, v106
	v_fmac_f32_e32 v104, v113, v113
	v_fmac_f32_e32 v105, v114, v114
	v_mul_f32_e32 v107, v107, v107
	v_fmac_f32_e32 v106, v115, v115
	v_add_f32_e32 v104, v104, v105
	v_fmac_f32_e32 v107, v116, v116
	v_add_f32_e32 v104, v104, v106
	v_add_f32_e32 v113, v104, v107
	s_waitcnt vmcnt(15) lgkmcnt(0)
; __device__ __forceinline__ u32x4 pack8(f32x4 v0, f32x4 v1) { u32x4 w; w.x = cvt_pk_bf16(v0[0], v0[1]); w.y = cvt_pk_bf16(v0[2], v0[3]); w.z = cvt_pk_bf16(v1[0], v1[1]); w.w = cvt_pk_bf16(v1[2], v1[3]); return w; }
;     __device__ __forceinline__ void operator()(Acc& acc, const Unit& u, int wr, int wc, int fr, int fq, PG8_LAS unsigned char* xl) const {
;     ...
;             for (int m = 0; m < 4; ++m) { const int rl = ai * HALF + wr * 64 + m * 16 + fr; const int row = u.r0 + rl; const size_t off = (size_t)row * DM + col; float s = 0.f;
; #pragma unroll
;                 for (int bj = 0; bj < 2; ++bj) {
;                     f32x4 b0, b1;
;                     if (BASE_BF16) unpack8(*(const u32x4*)((const bf16_t*)base + off + bj * HALF), b0, b1);
;                     else { b0 = *(const f32x4*)((const float*)base + off + bj * HALF); b1 = *(const f32x4*)((const float*)base + off + bj * HALF + 4); }
;                     const u32x4 w = pack8(acc[ai][bj][m][0] + b0, acc[ai][bj][m][1] + b1);
;                     *(u32x4*)(outB + off + bj * HALF) = w;
;                     f32x4 v0, v1; unpack8(w, v0, v1);
;                     s += (v0[0] * v0[0] + v0[1] * v0[1]) + (v0[2] * v0[2] + v0[3] * v0[3]) + (v1[0] * v1[0] + v1[1] * v1[1]) + (v1[2] * v1[2] + v1[3] * v1[3]); }
;                 s += __shfl_xor(s, 16); s += __shfl_xor(s, 32);
;                 if (fq == 0) X[rl * 4 + wc] = s; }
	v_lshlrev_b32_e32 v104, 16, v196
	v_and_b32_e32 v105, 0xffff0000, v196
	v_lshlrev_b32_e32 v106, 16, v197
	v_and_b32_e32 v107, 0xffff0000, v197
	v_lshlrev_b32_e32 v108, 16, v198
	v_and_b32_e32 v109, 0xffff0000, v198
	v_lshlrev_b32_e32 v110, 16, v199
	v_and_b32_e32 v111, 0xffff0000, v199
	v_pk_add_f32 v[102:103], v[102:103], v[106:107]
	v_pk_add_f32 v[100:101], v[100:101], v[104:105]
	v_pk_add_f32 v[96:97], v[96:97], v[108:109]
	v_pk_add_f32 v[104:105], v[98:99], v[110:111]
	v_cvt_pk_bf16_f32 v98, v100, v101
	v_cvt_pk_bf16_f32 v99, v102, v103
	v_cvt_pk_bf16_f32 v100, v96, v97
	s_nop 0
	v_and_b32_e32 v97, 0xffff0000, v98
	v_and_b32_e32 v103, 0xffff0000, v99
	v_cvt_pk_bf16_f32 v101, v104, v105
	v_lshlrev_b32_e32 v96, 16, v98
	v_lshlrev_b32_e32 v102, 16, v99
	v_and_b32_e32 v105, 0xffff0000, v100
	v_mul_f32_e32 v97, v97, v97
	v_mul_f32_e32 v103, v103, v103
	v_lshlrev_b32_e32 v104, 16, v100
	v_and_b32_e32 v107, 0xffff0000, v101
	v_mul_f32_e32 v105, v105, v105
	v_fmac_f32_e32 v97, v96, v96
	v_fmac_f32_e32 v103, v102, v102
	v_lshlrev_b32_e32 v106, 16, v101
	v_mul_f32_e32 v107, v107, v107
	v_fmac_f32_e32 v105, v104, v104
	v_add_f32_e32 v96, v97, v103
	v_add_f32_e32 v96, v96, v105
	v_fmac_f32_e32 v107, v106, v106
	v_add_f32_e32 v96, v96, v107
	v_add_f32_e32 v96, v113, v96
	ds_bpermute_b32 v97, v120, v96
	global_store_dwordx4 v[118:119], v[98:101], off offset:256
	s_waitcnt lgkmcnt(0)
	v_add_f32_e32 v96, v96, v97
	ds_bpermute_b32 v97, v112, v96
	s_and_saveexec_b64 s[30:31], s[6:7]
	s_cbranch_execz .LBB0_732
	s_waitcnt lgkmcnt(0)
	v_add_f32_e32 v96, v96, v97
	ds_write_b32 v162, v96
.LBB0_732:
	s_or_b64 exec, exec, s[30:31]
	v_add_u32_e32 v96, s55, v150
	s_waitcnt lgkmcnt(0)
	v_ashrrev_i32_e32 v97, 31, v96
	v_lshlrev_b64 v[96:97], 10, v[96:97]
	v_lshl_add_u64 v[96:97], v[96:97], 0, v[144:145]
	v_lshlrev_b64 v[100:101], 1, v[96:97]
	v_lshl_add_u64 v[102:103], s[10:11], 0, v[100:101]
	s_nop 0
	v_lshl_add_u64 v[100:101], s[12:13], 0, v[100:101]
	s_waitcnt vmcnt(15) lgkmcnt(0)
	v_lshlrev_b32_e32 v104, 16, v200
	v_and_b32_e32 v105, 0xffff0000, v200
	v_lshlrev_b32_e32 v96, 16, v201
	v_and_b32_e32 v97, 0xffff0000, v201
	v_lshlrev_b32_e32 v106, 16, v202
	v_and_b32_e32 v107, 0xffff0000, v202
	v_lshlrev_b32_e32 v98, 16, v203
	v_and_b32_e32 v99, 0xffff0000, v203
	v_pk_add_f32 v[94:95], v[94:95], v[96:97]
	v_pk_add_f32 v[96:97], v[90:91], v[98:99]
	v_pk_add_f32 v[90:91], v[88:89], v[106:107]
	v_pk_add_f32 v[92:93], v[92:93], v[104:105]
	s_nop 0
	v_cvt_pk_bf16_f32 v88, v92, v93
	v_cvt_pk_bf16_f32 v89, v94, v95
	v_cvt_pk_bf16_f32 v90, v90, v91
	v_cvt_pk_bf16_f32 v91, v96, v97
	global_store_dwordx4 v[100:101], v[88:91], off
	s_nop 0
	v_lshlrev_b32_e32 v96, 16, v88
	v_and_b32_e32 v88, 0xffff0000, v88
	v_lshlrev_b32_e32 v97, 16, v89
	v_and_b32_e32 v89, 0xffff0000, v89
	v_lshlrev_b32_e32 v98, 16, v90
	v_and_b32_e32 v90, 0xffff0000, v90
	v_mul_f32_e32 v88, v88, v88
	v_mul_f32_e32 v89, v89, v89
	v_lshlrev_b32_e32 v99, 16, v91
	v_and_b32_e32 v91, 0xffff0000, v91
	v_mul_f32_e32 v90, v90, v90
	v_fmac_f32_e32 v88, v96, v96
	v_fmac_f32_e32 v89, v97, v97
	v_mul_f32_e32 v91, v91, v91
	v_fmac_f32_e32 v90, v98, v98
	v_add_f32_e32 v88, v88, v89
	v_fmac_f32_e32 v91, v99, v99
	v_add_f32_e32 v88, v88, v90
	v_add_f32_e32 v96, v88, v91
	s_waitcnt vmcnt(15) lgkmcnt(0)
	v_lshlrev_b32_e32 v88, 16, v204
	v_and_b32_e32 v89, 0xffff0000, v204
	v_lshlrev_b32_e32 v90, 16, v205
	v_and_b32_e32 v91, 0xffff0000, v205
	v_lshlrev_b32_e32 v92, 16, v206
	v_and_b32_e32 v93, 0xffff0000, v206
	v_lshlrev_b32_e32 v94, 16, v207
	v_and_b32_e32 v95, 0xffff0000, v207
	v_pk_add_f32 v[86:87], v[86:87], v[90:91]
	v_pk_add_f32 v[84:85], v[84:85], v[88:89]
	v_pk_add_f32 v[80:81], v[80:81], v[92:93]
	v_pk_add_f32 v[88:89], v[82:83], v[94:95]
	v_cvt_pk_bf16_f32 v82, v84, v85
	v_cvt_pk_bf16_f32 v83, v86, v87
	v_cvt_pk_bf16_f32 v84, v80, v81
	s_nop 0
	v_and_b32_e32 v81, 0xffff0000, v82
	v_and_b32_e32 v87, 0xffff0000, v83
	v_cvt_pk_bf16_f32 v85, v88, v89
	v_lshlrev_b32_e32 v80, 16, v82
	v_lshlrev_b32_e32 v86, 16, v83
	v_and_b32_e32 v89, 0xffff0000, v84
	v_mul_f32_e32 v81, v81, v81
	v_mul_f32_e32 v87, v87, v87
	v_lshlrev_b32_e32 v88, 16, v84
	v_and_b32_e32 v91, 0xffff0000, v85
	v_mul_f32_e32 v89, v89, v89
	v_fmac_f32_e32 v81, v80, v80
	v_fmac_f32_e32 v87, v86, v86
	v_lshlrev_b32_e32 v90, 16, v85
	v_mul_f32_e32 v91, v91, v91
	v_fmac_f32_e32 v89, v88, v88
	v_add_f32_e32 v80, v81, v87
	v_add_f32_e32 v80, v80, v89
	v_fmac_f32_e32 v91, v90, v90
	v_add_f32_e32 v80, v80, v91
	v_add_f32_e32 v80, v96, v80
	ds_bpermute_b32 v81, v120, v80
	global_store_dwordx4 v[100:101], v[82:85], off offset:256
	s_waitcnt lgkmcnt(0)
	v_add_f32_e32 v80, v80, v81
	ds_bpermute_b32 v81, v112, v80
	s_and_saveexec_b64 s[30:31], s[6:7]
	s_cbranch_execz .LBB0_734
	s_waitcnt lgkmcnt(0)
	v_add_f32_e32 v80, v80, v81
	ds_write_b32 v163, v80
; __device__ __forceinline__ u32x4 pack8(f32x4 v0, f32x4 v1) { u32x4 w; w.x = cvt_pk_bf16(v0[0], v0[1]); w.y = cvt_pk_bf16(v0[2], v0[3]); w.z = cvt_pk_bf16(v1[0], v1[1]); w.w = cvt_pk_bf16(v1[2], v1[3]); return w; }
;     __device__ __forceinline__ void operator()(Acc& acc, const Unit& u, int wr, int wc, int fr, int fq, PG8_LAS unsigned char* xl) const {
;     ...
;             for (int m = 0; m < 4; ++m) { const int rl = ai * HALF + wr * 64 + m * 16 + fr; const int row = u.r0 + rl; const size_t off = (size_t)row * DM + col; float s = 0.f;
; #pragma unroll
;                 for (int bj = 0; bj < 2; ++bj) {
;                     f32x4 b0, b1;
;                     if (BASE_BF16) unpack8(*(const u32x4*)((const bf16_t*)base + off + bj * HALF), b0, b1);
;                     else { b0 = *(const f32x4*)((const float*)base + off + bj * HALF); b1 = *(const f32x4*)((const float*)base + off + bj * HALF + 4); }
;                     const u32x4 w = pack8(acc[ai][bj][m][0] + b0, acc[ai][bj][m][1] + b1);
;                     *(u32x4*)(outB + off + bj * HALF) = w;
;                     f32x4 v0, v1; unpack8(w, v0, v1);
;                     s += (v0[0] * v0[0] + v0[1] * v0[1]) + (v0[2] * v0[2] + v0[3] * v0[3]) + (v1[0] * v1[0] + v1[1] * v1[1]) + (v1[2] * v1[2] + v1[3] * v1[3]); }
;                 s += __shfl_xor(s, 16); s += __shfl_xor(s, 32);
;                 if (fq == 0) X[rl * 4 + wc] = s; }
.LBB0_734:
	s_or_b64 exec, exec, s[30:31]
	v_add_u32_e32 v80, s55, v151
	s_waitcnt lgkmcnt(0)
	v_ashrrev_i32_e32 v81, 31, v80
	v_lshlrev_b64 v[80:81], 10, v[80:81]
	v_lshl_add_u64 v[80:81], v[80:81], 0, v[144:145]
	v_lshlrev_b64 v[84:85], 1, v[80:81]
	v_lshl_add_u64 v[86:87], s[10:11], 0, v[84:85]
	s_nop 0
	v_lshl_add_u64 v[84:85], s[12:13], 0, v[84:85]
	s_waitcnt vmcnt(15) lgkmcnt(0)
	v_lshlrev_b32_e32 v88, 16, v208
	v_and_b32_e32 v89, 0xffff0000, v208
	v_lshlrev_b32_e32 v80, 16, v209
	v_and_b32_e32 v81, 0xffff0000, v209
	v_lshlrev_b32_e32 v90, 16, v210
	v_and_b32_e32 v91, 0xffff0000, v210
	v_lshlrev_b32_e32 v82, 16, v211
	v_and_b32_e32 v83, 0xffff0000, v211
	v_pk_add_f32 v[78:79], v[78:79], v[80:81]
	v_pk_add_f32 v[80:81], v[74:75], v[82:83]
	v_pk_add_f32 v[74:75], v[72:73], v[90:91]
	v_pk_add_f32 v[76:77], v[76:77], v[88:89]
	s_nop 0
	v_cvt_pk_bf16_f32 v72, v76, v77
	v_cvt_pk_bf16_f32 v73, v78, v79
	v_cvt_pk_bf16_f32 v74, v74, v75
	v_cvt_pk_bf16_f32 v75, v80, v81
	global_store_dwordx4 v[84:85], v[72:75], off
	s_nop 0
	v_lshlrev_b32_e32 v80, 16, v72
	v_and_b32_e32 v72, 0xffff0000, v72
	v_lshlrev_b32_e32 v81, 16, v73
	v_and_b32_e32 v73, 0xffff0000, v73
	v_lshlrev_b32_e32 v82, 16, v74
	v_and_b32_e32 v74, 0xffff0000, v74
	v_mul_f32_e32 v72, v72, v72
	v_mul_f32_e32 v73, v73, v73
	v_lshlrev_b32_e32 v83, 16, v75
	v_and_b32_e32 v75, 0xffff0000, v75
	v_mul_f32_e32 v74, v74, v74
	v_fmac_f32_e32 v72, v80, v80
	v_fmac_f32_e32 v73, v81, v81
	v_mul_f32_e32 v75, v75, v75
	v_fmac_f32_e32 v74, v82, v82
	v_add_f32_e32 v72, v72, v73
	v_fmac_f32_e32 v75, v83, v83
	v_add_f32_e32 v72, v72, v74
	v_add_f32_e32 v80, v72, v75
	s_waitcnt vmcnt(15) lgkmcnt(0)
	v_lshlrev_b32_e32 v72, 16, v212
	v_and_b32_e32 v73, 0xffff0000, v212
	v_lshlrev_b32_e32 v74, 16, v213
	v_and_b32_e32 v75, 0xffff0000, v213
	v_lshlrev_b32_e32 v76, 16, v214
	v_and_b32_e32 v77, 0xffff0000, v214
	v_lshlrev_b32_e32 v78, 16, v215
	v_and_b32_e32 v79, 0xffff0000, v215
	v_pk_add_f32 v[70:71], v[70:71], v[74:75]
	v_pk_add_f32 v[68:69], v[68:69], v[72:73]
	v_pk_add_f32 v[64:65], v[64:65], v[76:77]
	v_pk_add_f32 v[72:73], v[66:67], v[78:79]
	v_cvt_pk_bf16_f32 v66, v68, v69
	v_cvt_pk_bf16_f32 v67, v70, v71
	v_cvt_pk_bf16_f32 v68, v64, v65
	s_nop 0
	v_and_b32_e32 v65, 0xffff0000, v66
	v_and_b32_e32 v71, 0xffff0000, v67
	v_cvt_pk_bf16_f32 v69, v72, v73
	v_lshlrev_b32_e32 v64, 16, v66
	v_lshlrev_b32_e32 v70, 16, v67
	v_and_b32_e32 v73, 0xffff0000, v68
	v_mul_f32_e32 v65, v65, v65
	v_mul_f32_e32 v71, v71, v71
	v_lshlrev_b32_e32 v72, 16, v68
	v_and_b32_e32 v75, 0xffff0000, v69
	v_mul_f32_e32 v73, v73, v73
	v_fmac_f32_e32 v65, v64, v64
	v_fmac_f32_e32 v71, v70, v70
	v_lshlrev_b32_e32 v74, 16, v69
	v_mul_f32_e32 v75, v75, v75
	v_fmac_f32_e32 v73, v72, v72
	v_add_f32_e32 v64, v65, v71
	v_add_f32_e32 v64, v64, v73
	v_fmac_f32_e32 v75, v74, v74
	v_add_f32_e32 v64, v64, v75
	v_add_f32_e32 v64, v80, v64
	ds_bpermute_b32 v65, v120, v64
	global_store_dwordx4 v[84:85], v[66:69], off offset:256
	s_waitcnt lgkmcnt(0)
	v_add_f32_e32 v64, v64, v65
	ds_bpermute_b32 v65, v112, v64
	s_and_saveexec_b64 s[30:31], s[6:7]
	s_cbranch_execz .LBB0_736
	s_waitcnt lgkmcnt(0)
	v_add_f32_e32 v64, v64, v65
	ds_write_b32 v164, v64
.LBB0_736:
	s_or_b64 exec, exec, s[30:31]
	v_add_u32_e32 v64, s55, v152
	s_waitcnt lgkmcnt(0)
	v_ashrrev_i32_e32 v65, 31, v64
	v_lshlrev_b64 v[64:65], 10, v[64:65]
	v_lshl_add_u64 v[64:65], v[64:65], 0, v[144:145]
	v_lshlrev_b64 v[68:69], 1, v[64:65]
	v_lshl_add_u64 v[70:71], s[10:11], 0, v[68:69]
	s_nop 0
	v_lshl_add_u64 v[68:69], s[12:13], 0, v[68:69]
	s_waitcnt vmcnt(15) lgkmcnt(0)
	v_lshlrev_b32_e32 v72, 16, v216
	v_and_b32_e32 v73, 0xffff0000, v216
	v_lshlrev_b32_e32 v64, 16, v217
	v_and_b32_e32 v65, 0xffff0000, v217
	v_lshlrev_b32_e32 v74, 16, v218
	v_and_b32_e32 v75, 0xffff0000, v218
	v_lshlrev_b32_e32 v66, 16, v219
	v_and_b32_e32 v67, 0xffff0000, v219
	v_pk_add_f32 v[62:63], v[62:63], v[64:65]
	v_pk_add_f32 v[64:65], v[58:59], v[66:67]
	v_pk_add_f32 v[58:59], v[56:57], v[74:75]
	v_pk_add_f32 v[60:61], v[60:61], v[72:73]
	s_nop 0
	v_cvt_pk_bf16_f32 v56, v60, v61
	v_cvt_pk_bf16_f32 v57, v62, v63
	v_cvt_pk_bf16_f32 v58, v58, v59
	v_cvt_pk_bf16_f32 v59, v64, v65
	global_store_dwordx4 v[68:69], v[56:59], off
	s_nop 0
	v_lshlrev_b32_e32 v64, 16, v56
	v_and_b32_e32 v56, 0xffff0000, v56
	v_lshlrev_b32_e32 v65, 16, v57
	v_and_b32_e32 v57, 0xffff0000, v57
	v_lshlrev_b32_e32 v66, 16, v58
	v_and_b32_e32 v58, 0xffff0000, v58
	v_mul_f32_e32 v56, v56, v56
	v_mul_f32_e32 v57, v57, v57
	v_lshlrev_b32_e32 v67, 16, v59
	v_and_b32_e32 v59, 0xffff0000, v59
	v_mul_f32_e32 v58, v58, v58
	v_fmac_f32_e32 v56, v64, v64
	v_fmac_f32_e32 v57, v65, v65
	v_mul_f32_e32 v59, v59, v59
	v_fmac_f32_e32 v58, v66, v66
	v_add_f32_e32 v56, v56, v57
	v_fmac_f32_e32 v59, v67, v67
	v_add_f32_e32 v56, v56, v58
	v_add_f32_e32 v64, v56, v59
	s_waitcnt vmcnt(15) lgkmcnt(0)
	v_lshlrev_b32_e32 v56, 16, v224
	v_and_b32_e32 v57, 0xffff0000, v224
	v_lshlrev_b32_e32 v58, 16, v225
	v_and_b32_e32 v59, 0xffff0000, v225
	v_lshlrev_b32_e32 v60, 16, v226
	v_and_b32_e32 v61, 0xffff0000, v226
	v_lshlrev_b32_e32 v62, 16, v227
	v_and_b32_e32 v63, 0xffff0000, v227
	v_pk_add_f32 v[54:55], v[54:55], v[58:59]
	v_pk_add_f32 v[52:53], v[52:53], v[56:57]
	v_pk_add_f32 v[48:49], v[48:49], v[60:61]
	v_pk_add_f32 v[56:57], v[50:51], v[62:63]
	v_cvt_pk_bf16_f32 v50, v52, v53
	v_cvt_pk_bf16_f32 v51, v54, v55
	v_cvt_pk_bf16_f32 v52, v48, v49
	s_nop 0
	v_and_b32_e32 v49, 0xffff0000, v50
	v_and_b32_e32 v55, 0xffff0000, v51
	v_cvt_pk_bf16_f32 v53, v56, v57
	v_lshlrev_b32_e32 v48, 16, v50
	v_lshlrev_b32_e32 v54, 16, v51
	v_and_b32_e32 v57, 0xffff0000, v52
	v_mul_f32_e32 v49, v49, v49
	v_mul_f32_e32 v55, v55, v55
	v_lshlrev_b32_e32 v56, 16, v52
	v_and_b32_e32 v59, 0xffff0000, v53
	v_mul_f32_e32 v57, v57, v57
	v_fmac_f32_e32 v49, v48, v48
	v_fmac_f32_e32 v55, v54, v54
	v_lshlrev_b32_e32 v58, 16, v53
	v_mul_f32_e32 v59, v59, v59
	v_fmac_f32_e32 v57, v56, v56
	v_add_f32_e32 v48, v49, v55
	v_add_f32_e32 v48, v48, v57
	v_fmac_f32_e32 v59, v58, v58
	v_add_f32_e32 v48, v48, v59
	v_add_f32_e32 v48, v64, v48
	ds_bpermute_b32 v49, v120, v48
	global_store_dwordx4 v[68:69], v[50:53], off offset:256
	s_waitcnt lgkmcnt(0)
	v_add_f32_e32 v48, v48, v49
	ds_bpermute_b32 v49, v112, v48
	s_and_saveexec_b64 s[30:31], s[6:7]
	s_cbranch_execz .LBB0_738
	s_waitcnt lgkmcnt(0)
	v_add_f32_e32 v48, v48, v49
	ds_write_b32 v165, v48
; __device__ __forceinline__ u32x4 pack8(f32x4 v0, f32x4 v1) { u32x4 w; w.x = cvt_pk_bf16(v0[0], v0[1]); w.y = cvt_pk_bf16(v0[2], v0[3]); w.z = cvt_pk_bf16(v1[0], v1[1]); w.w = cvt_pk_bf16(v1[2], v1[3]); return w; }
;     __device__ __forceinline__ void operator()(Acc& acc, const Unit& u, int wr, int wc, int fr, int fq, PG8_LAS unsigned char* xl) const {
;     ...
;             for (int m = 0; m < 4; ++m) { const int rl = ai * HALF + wr * 64 + m * 16 + fr; const int row = u.r0 + rl; const size_t off = (size_t)row * DM + col; float s = 0.f;
; #pragma unroll
;                 for (int bj = 0; bj < 2; ++bj) {
;                     f32x4 b0, b1;
;                     if (BASE_BF16) unpack8(*(const u32x4*)((const bf16_t*)base + off + bj * HALF), b0, b1);
;                     else { b0 = *(const f32x4*)((const float*)base + off + bj * HALF); b1 = *(const f32x4*)((const float*)base + off + bj * HALF + 4); }
;                     const u32x4 w = pack8(acc[ai][bj][m][0] + b0, acc[ai][bj][m][1] + b1);
;                     *(u32x4*)(outB + off + bj * HALF) = w;
;                     f32x4 v0, v1; unpack8(w, v0, v1);
;                     s += (v0[0] * v0[0] + v0[1] * v0[1]) + (v0[2] * v0[2] + v0[3] * v0[3]) + (v1[0] * v1[0] + v1[1] * v1[1]) + (v1[2] * v1[2] + v1[3] * v1[3]); }
;                 s += __shfl_xor(s, 16); s += __shfl_xor(s, 32);
;                 if (fq == 0) X[rl * 4 + wc] = s; }
.LBB0_738:
	s_or_b64 exec, exec, s[30:31]
	v_add_u32_e32 v48, s55, v153
	s_waitcnt lgkmcnt(0)
	v_ashrrev_i32_e32 v49, 31, v48
	v_lshlrev_b64 v[48:49], 10, v[48:49]
	v_lshl_add_u64 v[48:49], v[48:49], 0, v[144:145]
	v_lshlrev_b64 v[52:53], 1, v[48:49]
	v_lshl_add_u64 v[54:55], s[10:11], 0, v[52:53]
	s_nop 0
	v_lshl_add_u64 v[52:53], s[12:13], 0, v[52:53]
	s_waitcnt vmcnt(15) lgkmcnt(0)
	v_lshlrev_b32_e32 v56, 16, v228
	v_and_b32_e32 v57, 0xffff0000, v228
	v_lshlrev_b32_e32 v48, 16, v229
	v_and_b32_e32 v49, 0xffff0000, v229
	v_lshlrev_b32_e32 v58, 16, v230
	v_and_b32_e32 v59, 0xffff0000, v230
	v_lshlrev_b32_e32 v50, 16, v231
	v_and_b32_e32 v51, 0xffff0000, v231
	v_pk_add_f32 v[46:47], v[46:47], v[48:49]
	v_pk_add_f32 v[48:49], v[42:43], v[50:51]
	v_pk_add_f32 v[42:43], v[40:41], v[58:59]
	v_pk_add_f32 v[44:45], v[44:45], v[56:57]
	s_nop 0
	v_cvt_pk_bf16_f32 v40, v44, v45
	v_cvt_pk_bf16_f32 v41, v46, v47
	v_cvt_pk_bf16_f32 v42, v42, v43
	v_cvt_pk_bf16_f32 v43, v48, v49
	global_store_dwordx4 v[52:53], v[40:43], off
	s_nop 0
	v_lshlrev_b32_e32 v48, 16, v40
	v_and_b32_e32 v40, 0xffff0000, v40
	v_lshlrev_b32_e32 v49, 16, v41
	v_and_b32_e32 v41, 0xffff0000, v41
	v_lshlrev_b32_e32 v50, 16, v42
	v_and_b32_e32 v42, 0xffff0000, v42
	v_mul_f32_e32 v40, v40, v40
	v_mul_f32_e32 v41, v41, v41
	v_lshlrev_b32_e32 v51, 16, v43
	v_and_b32_e32 v43, 0xffff0000, v43
	v_mul_f32_e32 v42, v42, v42
	v_fmac_f32_e32 v40, v48, v48
	v_fmac_f32_e32 v41, v49, v49
	v_mul_f32_e32 v43, v43, v43
	v_fmac_f32_e32 v42, v50, v50
	v_add_f32_e32 v40, v40, v41
	v_fmac_f32_e32 v43, v51, v51
	v_add_f32_e32 v40, v40, v42
	v_add_f32_e32 v48, v40, v43
	s_waitcnt vmcnt(15) lgkmcnt(0)
	v_lshlrev_b32_e32 v40, 16, v232
	v_and_b32_e32 v41, 0xffff0000, v232
	v_lshlrev_b32_e32 v42, 16, v233
	v_and_b32_e32 v43, 0xffff0000, v233
	v_lshlrev_b32_e32 v44, 16, v234
	v_and_b32_e32 v45, 0xffff0000, v234
	v_lshlrev_b32_e32 v46, 16, v235
	v_and_b32_e32 v47, 0xffff0000, v235
	v_pk_add_f32 v[38:39], v[38:39], v[42:43]
	v_pk_add_f32 v[36:37], v[36:37], v[40:41]
	v_pk_add_f32 v[32:33], v[32:33], v[44:45]
	v_pk_add_f32 v[40:41], v[34:35], v[46:47]
	v_cvt_pk_bf16_f32 v34, v36, v37
	v_cvt_pk_bf16_f32 v35, v38, v39
	v_cvt_pk_bf16_f32 v36, v32, v33
	s_nop 0
	v_and_b32_e32 v33, 0xffff0000, v34
	v_and_b32_e32 v39, 0xffff0000, v35
	v_cvt_pk_bf16_f32 v37, v40, v41
	v_lshlrev_b32_e32 v32, 16, v34
	v_lshlrev_b32_e32 v38, 16, v35
	v_and_b32_e32 v41, 0xffff0000, v36
	v_mul_f32_e32 v33, v33, v33
	v_mul_f32_e32 v39, v39, v39
	v_lshlrev_b32_e32 v40, 16, v36
	v_and_b32_e32 v43, 0xffff0000, v37
	v_mul_f32_e32 v41, v41, v41
	v_fmac_f32_e32 v33, v32, v32
	v_fmac_f32_e32 v39, v38, v38
	v_lshlrev_b32_e32 v42, 16, v37
	v_mul_f32_e32 v43, v43, v43
	v_fmac_f32_e32 v41, v40, v40
	v_add_f32_e32 v32, v33, v39
	v_add_f32_e32 v32, v32, v41
	v_fmac_f32_e32 v43, v42, v42
	v_add_f32_e32 v32, v32, v43
	v_add_f32_e32 v32, v48, v32
	ds_bpermute_b32 v33, v120, v32
	global_store_dwordx4 v[52:53], v[34:37], off offset:256
	s_waitcnt lgkmcnt(0)
	v_add_f32_e32 v32, v32, v33
	ds_bpermute_b32 v33, v112, v32
	s_and_saveexec_b64 s[30:31], s[6:7]
	s_cbranch_execz .LBB0_740
	s_waitcnt lgkmcnt(0)
	v_add_f32_e32 v32, v32, v33
	ds_write_b32 v166, v32
; __device__ __forceinline__ u32x4 pack8(f32x4 v0, f32x4 v1) { u32x4 w; w.x = cvt_pk_bf16(v0[0], v0[1]); w.y = cvt_pk_bf16(v0[2], v0[3]); w.z = cvt_pk_bf16(v1[0], v1[1]); w.w = cvt_pk_bf16(v1[2], v1[3]); return w; }
;     __device__ __forceinline__ void operator()(Acc& acc, const Unit& u, int wr, int wc, int fr, int fq, PG8_LAS unsigned char* xl) const {
;     ...
;             for (int m = 0; m < 4; ++m) { const int rl = ai * HALF + wr * 64 + m * 16 + fr; const int row = u.r0 + rl; const size_t off = (size_t)row * DM + col; float s = 0.f;
; #pragma unroll
;                 for (int bj = 0; bj < 2; ++bj) {
;                     f32x4 b0, b1;
;                     if (BASE_BF16) unpack8(*(const u32x4*)((const bf16_t*)base + off + bj * HALF), b0, b1);
;                     else { b0 = *(const f32x4*)((const float*)base + off + bj * HALF); b1 = *(const f32x4*)((const float*)base + off + bj * HALF + 4); }
;                     const u32x4 w = pack8(acc[ai][bj][m][0] + b0, acc[ai][bj][m][1] + b1);
;                     *(u32x4*)(outB + off + bj * HALF) = w;
;                     f32x4 v0, v1; unpack8(w, v0, v1);
;                     s += (v0[0] * v0[0] + v0[1] * v0[1]) + (v0[2] * v0[2] + v0[3] * v0[3]) + (v1[0] * v1[0] + v1[1] * v1[1]) + (v1[2] * v1[2] + v1[3] * v1[3]); }
;                 s += __shfl_xor(s, 16); s += __shfl_xor(s, 32);
;                 if (fq == 0) X[rl * 4 + wc] = s; }
.LBB0_740:
	s_or_b64 exec, exec, s[30:31]
	v_add_u32_e32 v32, s55, v155
	s_waitcnt lgkmcnt(0)
	v_ashrrev_i32_e32 v33, 31, v32
	v_lshlrev_b64 v[32:33], 10, v[32:33]
	v_lshl_add_u64 v[32:33], v[32:33], 0, v[144:145]
	v_lshlrev_b64 v[36:37], 1, v[32:33]
	v_lshl_add_u64 v[38:39], s[10:11], 0, v[36:37]
	s_nop 0
	v_lshl_add_u64 v[36:37], s[12:13], 0, v[36:37]
	s_waitcnt vmcnt(15) lgkmcnt(0)
	v_lshlrev_b32_e32 v40, 16, v236
	v_and_b32_e32 v41, 0xffff0000, v236
	v_lshlrev_b32_e32 v32, 16, v237
	v_and_b32_e32 v33, 0xffff0000, v237
	v_lshlrev_b32_e32 v42, 16, v238
	v_and_b32_e32 v43, 0xffff0000, v238
	v_lshlrev_b32_e32 v34, 16, v239
	v_and_b32_e32 v35, 0xffff0000, v239
	v_pk_add_f32 v[30:31], v[30:31], v[32:33]
	v_pk_add_f32 v[32:33], v[26:27], v[34:35]
	v_pk_add_f32 v[26:27], v[24:25], v[42:43]
	v_pk_add_f32 v[28:29], v[28:29], v[40:41]
	s_nop 0
	v_cvt_pk_bf16_f32 v24, v28, v29
	v_cvt_pk_bf16_f32 v25, v30, v31
	v_cvt_pk_bf16_f32 v26, v26, v27
	v_cvt_pk_bf16_f32 v27, v32, v33
	global_store_dwordx4 v[36:37], v[24:27], off
	s_nop 0
	v_lshlrev_b32_e32 v32, 16, v24
	v_and_b32_e32 v24, 0xffff0000, v24
	v_lshlrev_b32_e32 v33, 16, v25
	v_and_b32_e32 v25, 0xffff0000, v25
	v_lshlrev_b32_e32 v34, 16, v26
	v_and_b32_e32 v26, 0xffff0000, v26
	v_mul_f32_e32 v24, v24, v24
	v_mul_f32_e32 v25, v25, v25
	v_lshlrev_b32_e32 v35, 16, v27
	v_and_b32_e32 v27, 0xffff0000, v27
	v_mul_f32_e32 v26, v26, v26
	v_fmac_f32_e32 v24, v32, v32
	v_fmac_f32_e32 v25, v33, v33
	v_mul_f32_e32 v27, v27, v27
	v_fmac_f32_e32 v26, v34, v34
	v_add_f32_e32 v24, v24, v25
	v_fmac_f32_e32 v27, v35, v35
	v_add_f32_e32 v24, v24, v26
	v_add_f32_e32 v32, v24, v27
	s_waitcnt vmcnt(15) lgkmcnt(0)
	v_lshlrev_b32_e32 v24, 16, v240
	v_and_b32_e32 v25, 0xffff0000, v240
	v_lshlrev_b32_e32 v26, 16, v241
	v_and_b32_e32 v27, 0xffff0000, v241
	v_lshlrev_b32_e32 v28, 16, v242
	v_and_b32_e32 v29, 0xffff0000, v242
	v_lshlrev_b32_e32 v30, 16, v243
	v_and_b32_e32 v31, 0xffff0000, v243
	v_pk_add_f32 v[22:23], v[22:23], v[26:27]
	v_pk_add_f32 v[20:21], v[20:21], v[24:25]
	v_pk_add_f32 v[16:17], v[16:17], v[28:29]
	v_pk_add_f32 v[24:25], v[18:19], v[30:31]
	v_cvt_pk_bf16_f32 v18, v20, v21
	v_cvt_pk_bf16_f32 v19, v22, v23
	v_cvt_pk_bf16_f32 v20, v16, v17
	s_nop 0
	v_and_b32_e32 v17, 0xffff0000, v18
	v_and_b32_e32 v23, 0xffff0000, v19
	v_cvt_pk_bf16_f32 v21, v24, v25
	v_lshlrev_b32_e32 v16, 16, v18
	v_lshlrev_b32_e32 v22, 16, v19
	v_and_b32_e32 v25, 0xffff0000, v20
	v_mul_f32_e32 v17, v17, v17
	v_mul_f32_e32 v23, v23, v23
	v_lshlrev_b32_e32 v24, 16, v20
	v_and_b32_e32 v27, 0xffff0000, v21
	v_mul_f32_e32 v25, v25, v25
	v_fmac_f32_e32 v17, v16, v16
	v_fmac_f32_e32 v23, v22, v22
	v_lshlrev_b32_e32 v26, 16, v21
	v_mul_f32_e32 v27, v27, v27
	v_fmac_f32_e32 v25, v24, v24
	v_add_f32_e32 v16, v17, v23
	v_add_f32_e32 v16, v16, v25
	v_fmac_f32_e32 v27, v26, v26
	v_add_f32_e32 v16, v16, v27
	v_add_f32_e32 v16, v32, v16
	ds_bpermute_b32 v17, v120, v16
	global_store_dwordx4 v[36:37], v[18:21], off offset:256
	s_waitcnt lgkmcnt(0)
	v_add_f32_e32 v16, v16, v17
	ds_bpermute_b32 v17, v112, v16
	s_and_saveexec_b64 s[30:31], s[6:7]
	s_cbranch_execz .LBB0_742
	s_waitcnt lgkmcnt(0)
	v_add_f32_e32 v16, v16, v17
	ds_write_b32 v167, v16
.LBB0_742:
	s_or_b64 exec, exec, s[30:31]
	v_add_u32_e32 v16, s55, v156
	s_waitcnt lgkmcnt(0)
	v_ashrrev_i32_e32 v17, 31, v16
	v_lshlrev_b64 v[16:17], 10, v[16:17]
	v_lshl_add_u64 v[16:17], v[16:17], 0, v[144:145]
	v_lshlrev_b64 v[20:21], 1, v[16:17]
	v_lshl_add_u64 v[22:23], s[10:11], 0, v[20:21]
	s_nop 0
	v_lshl_add_u64 v[20:21], s[12:13], 0, v[20:21]
	s_waitcnt vmcnt(15) lgkmcnt(0)
	v_lshlrev_b32_e32 v24, 16, v244
	v_and_b32_e32 v25, 0xffff0000, v244
	v_lshlrev_b32_e32 v16, 16, v245
	v_and_b32_e32 v17, 0xffff0000, v245
	v_lshlrev_b32_e32 v26, 16, v246
	v_and_b32_e32 v27, 0xffff0000, v246
	v_lshlrev_b32_e32 v18, 16, v247
	v_and_b32_e32 v19, 0xffff0000, v247
	v_pk_add_f32 v[14:15], v[14:15], v[16:17]
	v_pk_add_f32 v[16:17], v[10:11], v[18:19]
	v_pk_add_f32 v[10:11], v[8:9], v[26:27]
	v_pk_add_f32 v[12:13], v[12:13], v[24:25]
	s_nop 0
	v_cvt_pk_bf16_f32 v8, v12, v13
	v_cvt_pk_bf16_f32 v9, v14, v15
	v_cvt_pk_bf16_f32 v10, v10, v11
	v_cvt_pk_bf16_f32 v11, v16, v17
	global_store_dwordx4 v[20:21], v[8:11], off
	s_nop 0
	v_lshlrev_b32_e32 v16, 16, v8
	v_and_b32_e32 v8, 0xffff0000, v8
	v_lshlrev_b32_e32 v17, 16, v9
	v_and_b32_e32 v9, 0xffff0000, v9
	v_lshlrev_b32_e32 v18, 16, v10
	v_and_b32_e32 v10, 0xffff0000, v10
	v_mul_f32_e32 v8, v8, v8
	v_mul_f32_e32 v9, v9, v9
	v_lshlrev_b32_e32 v19, 16, v11
	v_and_b32_e32 v11, 0xffff0000, v11
	v_mul_f32_e32 v10, v10, v10
	v_fmac_f32_e32 v8, v16, v16
	v_fmac_f32_e32 v9, v17, v17
	v_mul_f32_e32 v11, v11, v11
	v_fmac_f32_e32 v10, v18, v18
	v_add_f32_e32 v8, v8, v9
	v_fmac_f32_e32 v11, v19, v19
	v_add_f32_e32 v8, v8, v10
	v_add_f32_e32 v16, v8, v11
	s_waitcnt vmcnt(15) lgkmcnt(0)
	v_lshlrev_b32_e32 v8, 16, v248
	v_and_b32_e32 v9, 0xffff0000, v248
	v_lshlrev_b32_e32 v10, 16, v249
	v_and_b32_e32 v11, 0xffff0000, v249
	v_lshlrev_b32_e32 v12, 16, v250
	v_and_b32_e32 v13, 0xffff0000, v250
	v_lshlrev_b32_e32 v14, 16, v251
	v_and_b32_e32 v15, 0xffff0000, v251
	v_pk_add_f32 v[6:7], v[6:7], v[10:11]
	v_pk_add_f32 v[4:5], v[4:5], v[8:9]
	v_pk_add_f32 v[0:1], v[0:1], v[12:13]
	v_pk_add_f32 v[8:9], v[2:3], v[14:15]
	v_cvt_pk_bf16_f32 v2, v4, v5
	v_cvt_pk_bf16_f32 v3, v6, v7
	v_cvt_pk_bf16_f32 v4, v0, v1
	s_nop 0
	v_and_b32_e32 v1, 0xffff0000, v2
	v_and_b32_e32 v7, 0xffff0000, v3
	v_cvt_pk_bf16_f32 v5, v8, v9
	v_lshlrev_b32_e32 v0, 16, v2
	v_lshlrev_b32_e32 v6, 16, v3
	v_and_b32_e32 v9, 0xffff0000, v4
	v_mul_f32_e32 v1, v1, v1
	v_mul_f32_e32 v7, v7, v7
	v_lshlrev_b32_e32 v8, 16, v4
	v_and_b32_e32 v11, 0xffff0000, v5
	v_mul_f32_e32 v9, v9, v9
	v_fmac_f32_e32 v1, v0, v0
	v_fmac_f32_e32 v7, v6, v6
	v_lshlrev_b32_e32 v10, 16, v5
	v_mul_f32_e32 v11, v11, v11
	v_fmac_f32_e32 v9, v8, v8
	v_add_f32_e32 v0, v1, v7
	v_add_f32_e32 v0, v0, v9
	v_fmac_f32_e32 v11, v10, v10
	v_add_f32_e32 v0, v0, v11
	v_add_f32_e32 v0, v16, v0
	ds_bpermute_b32 v1, v120, v0
	global_store_dwordx4 v[20:21], v[2:5], off offset:256
	s_waitcnt lgkmcnt(0)
	v_add_f32_e32 v0, v0, v1
	ds_bpermute_b32 v1, v112, v0
	s_and_saveexec_b64 s[30:31], s[6:7]
	s_cbranch_execz .LBB0_744
	s_waitcnt lgkmcnt(0)
	v_add_f32_e32 v0, v0, v1
	ds_write_b32 v168, v0

; #define PG8_STAGE(bufoff, gbase, voff) do { _Pragma("unroll") for (int _i = 0; _i < 2; ++_i) \
;         __builtin_amdgcn_global_load_lds((const unsigned*)((const char*)(gbase) + (voff)[_i]), (PG8_LAS unsigned*)(lds + (bufoff) + ldsw + _i * 8192), 16, 0, 0); } while (0)
; #define PG8_LDA(dst, b, h) do { _Pragma("unroll") for (int m = 0; m < 4; ++m) _Pragma("unroll") for (int k = 0; k < 2; ++k) dst[m][k] = *(const PG8_LAS bf16x8*)(lds + PG8_SA(b, h) + aoff + m * 2048 + k * 1024); } while (0)
; #define PG8_LDB(dst, b, h) do { _Pragma("unroll") for (int n = 0; n < 2; ++n) _Pragma("unroll") for (int k = 0; k < 2; ++k) dst[n][k] = *(const PG8_LAS bf16x8*)(lds + PG8_SB(b, h) + boff + n * 2048 + k * 1024); } while (0)
; #define PG8_MMA(ai, bj, At, Bt) do { __builtin_amdgcn_s_setprio(1); _Pragma("unroll") for (int m = 0; m < 4; ++m) _Pragma("unroll") for (int n = 0; n < 2; ++n) _Pragma("unroll") for (int k = 0; k < 2; ++k) \
;         acc[ai][bj][m][n] = __builtin_amdgcn_mfma_f32_16x16x32_bf16(Bt[n][k], At[m][k], acc[ai][bj][m][n], 0, 0, 0); __builtin_amdgcn_s_setprio(0); } while (0)
; #define PG8_WAIT_V(n) asm volatile("s_waitcnt vmcnt(" #n ")" ::: "memory")
; #define PG8_WAIT_L(n) asm volatile("s_waitcnt lgkmcnt(" #n ")" ::: "memory")
; #define PG8_BAR __builtin_amdgcn_s_barrier()
; #define PG8_SCHED __builtin_amdgcn_sched_barrier(0)
; template <class Epi, class Sched>
; __device__ __forceinline__ void gemm_phase(PG8_LAS unsigned char* lds, PG8_LAS unsigned char* xl, const Gemm g, const Sched& S, const Epi& E) {
;     ...
;             const char* a1 = cA + (size_t)(t + 1) * kstep;
;             const char* a2 = last ? nA : cA + (size_t)(t + 2) * kstep; const char* b2 = last ? nB : cB + (size_t)(t + 2) * kstep;
;             const char* a3 = a2 + kstep; const char* b3 = b2 + kstep;
;             PG8_LDB(B0, 0, 0); PG8_LDB(B1, 0, 1); PG8_SCHED; PG8_LDA(At, 0, 0); PG8_STAGE(PG8_SA(1, 1), a1 + hsA, voffA);
;             PG8_WAIT_V(8); PG8_WAIT_L(0); PG8_BAR; PG8_MMA(0, 0, At, B0); PG8_MMA(0, 1, At, B1); PG8_BAR; PG8_SCHED;
;             PG8_LDA(At, 0, 1); PG8_STAGE(PG8_SB(0, 0), b2, voffB); PG8_STAGE(PG8_SB(0, 1), b2 + hsB, voffB); PG8_STAGE(PG8_SA(0, 0), a2, voffA);
.LBB0_942:
	ds_read_b128 v[144:147], v199
	ds_read_b128 v[148:151], v199 offset:1024
	ds_read_b128 v[152:155], v199 offset:2048
	ds_read_b128 v[156:159], v199 offset:3072
	ds_read_b128 v[160:163], v200
	ds_read_b128 v[164:167], v200 offset:1024
	ds_read_b128 v[168:171], v200 offset:2048
	ds_read_b128 v[172:175], v200 offset:3072
	s_add_u32 s48, s2, 0x100
	s_addc_u32 s49, s3, 0
	s_cmp_eq_u32 s80, 40
	s_cselect_b32 s53, s33, s49
	s_cselect_b32 s52, s46, s48
	s_cselect_b32 s51, s47, s79
	s_cselect_b32 s50, s77, s78
	v_lshl_add_u64 v[176:177], s[2:3], 0, v[138:139]
	s_add_i32 m0, s43, 0xc000
	ds_read_b128 v[214:217], v201
	ds_read_b128 v[222:225], v201 offset:1024
	ds_read_b128 v[226:229], v201 offset:2048
	ds_read_b128 v[230:233], v201 offset:3072
	ds_read_b128 v[234:237], v201 offset:4096
	ds_read_b128 v[238:241], v201 offset:5120
	ds_read_b128 v[242:245], v201 offset:6144
	ds_read_b128 v[246:249], v201 offset:7168
	global_load_lds_dwordx4 v[176:177], off
	v_lshl_add_u64 v[176:177], s[2:3], 0, v[136:137]
	s_add_i32 m0, s43, 0xe000
	s_nop 0
	global_load_lds_dwordx4 v[176:177], off
	s_waitcnt vmcnt(8)
	s_waitcnt lgkmcnt(0)
	s_barrier
	s_setprio 1
	s_waitcnt lgkmcnt(0)
	v_mfma_f32_16x16x32_bf16 v[124:127], v[144:147], v[214:217], v[124:127]
	v_mfma_f32_16x16x32_bf16 v[120:123], v[152:155], v[214:217], v[120:123]
	v_mfma_f32_16x16x32_bf16 v[108:111], v[144:147], v[226:229], v[108:111]
	v_mfma_f32_16x16x32_bf16 v[104:107], v[152:155], v[226:229], v[104:107]
	v_mfma_f32_16x16x32_bf16 v[92:95], v[144:147], v[234:237], v[92:95]
	v_mfma_f32_16x16x32_bf16 v[88:91], v[152:155], v[234:237], v[88:91]
	v_mfma_f32_16x16x32_bf16 v[76:79], v[144:147], v[242:245], v[76:79]
	v_mfma_f32_16x16x32_bf16 v[72:75], v[152:155], v[242:245], v[72:75]
	v_mfma_f32_16x16x32_bf16 v[124:127], v[148:151], v[222:225], v[124:127]
	v_mfma_f32_16x16x32_bf16 v[120:123], v[156:159], v[222:225], v[120:123]
	v_mfma_f32_16x16x32_bf16 v[108:111], v[148:151], v[230:233], v[108:111]
	v_mfma_f32_16x16x32_bf16 v[104:107], v[156:159], v[230:233], v[104:107]
	v_mfma_f32_16x16x32_bf16 v[92:95], v[148:151], v[238:241], v[92:95]
	v_mfma_f32_16x16x32_bf16 v[88:91], v[156:159], v[238:241], v[88:91]
	v_mfma_f32_16x16x32_bf16 v[76:79], v[148:151], v[246:249], v[76:79]
	v_mfma_f32_16x16x32_bf16 v[72:75], v[156:159], v[246:249], v[72:75]
	s_setprio 0
	s_setprio 1
	v_mfma_f32_16x16x32_bf16 v[116:119], v[160:163], v[214:217], v[116:119]
	v_mfma_f32_16x16x32_bf16 v[112:115], v[168:171], v[214:217], v[112:115]
	v_mfma_f32_16x16x32_bf16 v[100:103], v[160:163], v[226:229], v[100:103]
	v_mfma_f32_16x16x32_bf16 v[96:99], v[168:171], v[226:229], v[96:99]
	v_mfma_f32_16x16x32_bf16 v[84:87], v[160:163], v[234:237], v[84:87]
	v_mfma_f32_16x16x32_bf16 v[80:83], v[168:171], v[234:237], v[80:83]
	v_mfma_f32_16x16x32_bf16 v[68:71], v[160:163], v[242:245], v[68:71]
	v_mfma_f32_16x16x32_bf16 v[64:67], v[168:171], v[242:245], v[64:67]
	v_mfma_f32_16x16x32_bf16 v[116:119], v[164:167], v[222:225], v[116:119]
	v_mfma_f32_16x16x32_bf16 v[112:115], v[172:175], v[222:225], v[112:115]
	v_mfma_f32_16x16x32_bf16 v[100:103], v[164:167], v[230:233], v[100:103]
	v_mfma_f32_16x16x32_bf16 v[96:99], v[172:175], v[230:233], v[96:99]
	v_mfma_f32_16x16x32_bf16 v[84:87], v[164:167], v[238:241], v[84:87]
	v_mfma_f32_16x16x32_bf16 v[80:83], v[172:175], v[238:241], v[80:83]
	v_mfma_f32_16x16x32_bf16 v[68:71], v[164:167], v[246:249], v[68:71]
	v_mfma_f32_16x16x32_bf16 v[64:67], v[172:175], v[246:249], v[64:67]
	s_setprio 0
	s_barrier
	s_add_i32 s2, s70, s42
	v_lshl_add_u64 v[176:177], s[50:51], 0, v[130:131]
	s_mov_b32 m0, s2
	ds_read_b128 v[214:217], v201 offset:16384
	ds_read_b128 v[222:225], v201 offset:17408
	ds_read_b128 v[226:229], v201 offset:18432
	ds_read_b128 v[230:233], v201 offset:19456
	ds_read_b128 v[234:237], v201 offset:20480
	ds_read_b128 v[238:241], v201 offset:21504
	ds_read_b128 v[242:245], v201 offset:22528
	ds_read_b128 v[246:249], v201 offset:23552
	global_load_lds_dwordx4 v[176:177], off
	s_add_i32 m0, s2, 0x2000
	s_add_u32 s2, s50, 0xb0000
	v_lshl_add_u64 v[218:219], s[50:51], 0, v[134:135]
	s_addc_u32 s3, s51, 0
	s_add_i32 s68, s71, s42
	global_load_lds_dwordx4 v[218:219], off
	v_lshl_add_u64 v[250:251], s[2:3], 0, v[130:131]
	s_mov_b32 m0, s68
	v_lshl_add_u64 v[252:253], s[52:53], 0, v[132:133]
	global_load_lds_dwordx4 v[250:251], off
	v_lshl_add_u64 v[250:251], s[2:3], 0, v[134:135]
	s_add_i32 m0, s68, 0x2000
	s_nop 0
	global_load_lds_dwordx4 v[250:251], off
	v_lshl_add_u64 v[250:251], s[52:53], 0, v[128:129]
	s_mov_b32 m0, s43
	s_nop 0
	global_load_lds_dwordx4 v[250:251], off
	s_mov_b32 m0, s59
	s_nop 0
	global_load_lds_dwordx4 v[252:253], off
	s_waitcnt vmcnt(8)
	s_waitcnt lgkmcnt(0)
	s_barrier
; #define PG8_STAGE(bufoff, gbase, voff) do { _Pragma("unroll") for (int _i = 0; _i < 2; ++_i) \
;         __builtin_amdgcn_global_load_lds((const unsigned*)((const char*)(gbase) + (voff)[_i]), (PG8_LAS unsigned*)(lds + (bufoff) + ldsw + _i * 8192), 16, 0, 0); } while (0)
; #define PG8_LDA(dst, b, h) do { _Pragma("unroll") for (int m = 0; m < 4; ++m) _Pragma("unroll") for (int k = 0; k < 2; ++k) dst[m][k] = *(const PG8_LAS bf16x8*)(lds + PG8_SA(b, h) + aoff + m * 2048 + k * 1024); } while (0)
; #define PG8_LDB(dst, b, h) do { _Pragma("unroll") for (int n = 0; n < 2; ++n) _Pragma("unroll") for (int k = 0; k < 2; ++k) dst[n][k] = *(const PG8_LAS bf16x8*)(lds + PG8_SB(b, h) + boff + n * 2048 + k * 1024); } while (0)
; #define PG8_MMA(ai, bj, At, Bt) do { __builtin_amdgcn_s_setprio(1); _Pragma("unroll") for (int m = 0; m < 4; ++m) _Pragma("unroll") for (int n = 0; n < 2; ++n) _Pragma("unroll") for (int k = 0; k < 2; ++k) \
;         acc[ai][bj][m][n] = __builtin_amdgcn_mfma_f32_16x16x32_bf16(Bt[n][k], At[m][k], acc[ai][bj][m][n], 0, 0, 0); __builtin_amdgcn_s_setprio(0); } while (0)
; #define PG8_WAIT_V(n) asm volatile("s_waitcnt vmcnt(" #n ")" ::: "memory")
; #define PG8_WAIT_L(n) asm volatile("s_waitcnt lgkmcnt(" #n ")" ::: "memory")
; #define PG8_BAR __builtin_amdgcn_s_barrier()
; #define PG8_SCHED __builtin_amdgcn_sched_barrier(0)
; template <class Epi, class Sched>
; __device__ __forceinline__ void gemm_phase(PG8_LAS unsigned char* lds, PG8_LAS unsigned char* xl, const Gemm g, const Sched& S, const Epi& E) {
;     ...
;             PG8_WAIT_V(8); PG8_WAIT_L(0); PG8_BAR; PG8_MMA(1, 0, At, B0); PG8_MMA(1, 1, At, B1); PG8_BAR; PG8_SCHED;
;             PG8_LDB(B0, 1, 0); PG8_LDB(B1, 1, 1); PG8_SCHED; PG8_LDA(At, 1, 0); PG8_STAGE(PG8_SA(0, 1), a2 + hsA, voffA);
;             PG8_WAIT_V(8); PG8_WAIT_L(0); PG8_BAR; PG8_MMA(0, 0, At, B0); PG8_MMA(0, 1, At, B1); PG8_BAR; PG8_SCHED;
	s_setprio 1
	s_waitcnt lgkmcnt(0)
	v_mfma_f32_16x16x32_bf16 v[60:63], v[144:147], v[214:217], v[60:63]
	v_mfma_f32_16x16x32_bf16 v[56:59], v[152:155], v[214:217], v[56:59]
	v_mfma_f32_16x16x32_bf16 v[44:47], v[144:147], v[226:229], v[44:47]
	v_mfma_f32_16x16x32_bf16 v[40:43], v[152:155], v[226:229], v[40:43]
	v_mfma_f32_16x16x32_bf16 v[28:31], v[144:147], v[234:237], v[28:31]
	v_mfma_f32_16x16x32_bf16 v[24:27], v[152:155], v[234:237], v[24:27]
	v_mfma_f32_16x16x32_bf16 v[12:15], v[144:147], v[242:245], v[12:15]
	v_mfma_f32_16x16x32_bf16 v[8:11], v[152:155], v[242:245], v[8:11]
	v_mfma_f32_16x16x32_bf16 v[60:63], v[148:151], v[222:225], v[60:63]
	v_mfma_f32_16x16x32_bf16 v[56:59], v[156:159], v[222:225], v[56:59]
	v_mfma_f32_16x16x32_bf16 v[44:47], v[148:151], v[230:233], v[44:47]
	v_mfma_f32_16x16x32_bf16 v[40:43], v[156:159], v[230:233], v[40:43]
	v_mfma_f32_16x16x32_bf16 v[28:31], v[148:151], v[238:241], v[28:31]
	v_mfma_f32_16x16x32_bf16 v[24:27], v[156:159], v[238:241], v[24:27]
	v_mfma_f32_16x16x32_bf16 v[12:15], v[148:151], v[246:249], v[12:15]
	v_mfma_f32_16x16x32_bf16 v[8:11], v[156:159], v[246:249], v[8:11]
	s_setprio 0
	s_setprio 1
	v_mfma_f32_16x16x32_bf16 v[52:55], v[160:163], v[214:217], v[52:55]
	v_mfma_f32_16x16x32_bf16 v[48:51], v[168:171], v[214:217], v[48:51]
	v_mfma_f32_16x16x32_bf16 v[36:39], v[160:163], v[226:229], v[36:39]
	v_mfma_f32_16x16x32_bf16 v[32:35], v[168:171], v[226:229], v[32:35]
	v_mfma_f32_16x16x32_bf16 v[20:23], v[160:163], v[234:237], v[20:23]
	v_mfma_f32_16x16x32_bf16 v[16:19], v[168:171], v[234:237], v[16:19]
	v_mfma_f32_16x16x32_bf16 v[4:7], v[160:163], v[242:245], v[4:7]
	v_mfma_f32_16x16x32_bf16 v[0:3], v[168:171], v[242:245], v[0:3]
	v_mfma_f32_16x16x32_bf16 v[52:55], v[164:167], v[222:225], v[52:55]
	v_mfma_f32_16x16x32_bf16 v[48:51], v[172:175], v[222:225], v[48:51]
	v_mfma_f32_16x16x32_bf16 v[36:39], v[164:167], v[230:233], v[36:39]
	v_mfma_f32_16x16x32_bf16 v[32:35], v[172:175], v[230:233], v[32:35]
	v_mfma_f32_16x16x32_bf16 v[20:23], v[164:167], v[238:241], v[20:23]
	v_mfma_f32_16x16x32_bf16 v[16:19], v[172:175], v[238:241], v[16:19]
	v_mfma_f32_16x16x32_bf16 v[4:7], v[164:167], v[246:249], v[4:7]
	v_mfma_f32_16x16x32_bf16 v[0:3], v[172:175], v[246:249], v[0:3]
	s_setprio 0
	s_barrier
	s_add_i32 s68, 0, 0x18000
	s_add_i32 s81, 0, 0x1c000
	v_add_u32_e32 v156, s68, v181
	v_add_u32_e32 v172, s81, v181
	ds_read_b128 v[144:147], v156
	ds_read_b128 v[148:151], v156 offset:1024
	ds_read_b128 v[152:155], v156 offset:2048
	ds_read_b128 v[156:159], v156 offset:3072
	ds_read_b128 v[160:163], v172
	ds_read_b128 v[164:167], v172 offset:1024
	ds_read_b128 v[168:171], v172 offset:2048
	ds_read_b128 v[172:175], v172 offset:3072
	s_add_u32 s2, s52, 0xb0000
	s_addc_u32 s3, s53, 0
	s_mov_b32 m0, s60
	v_lshl_add_u64 v[212:213], s[2:3], 0, v[128:129]
	ds_read_b128 v[214:217], v201 offset:32768
	ds_read_b128 v[222:225], v201 offset:33792
	ds_read_b128 v[226:229], v201 offset:34816
	ds_read_b128 v[230:233], v201 offset:35840
	ds_read_b128 v[234:237], v201 offset:36864
	ds_read_b128 v[238:241], v201 offset:37888
	ds_read_b128 v[242:245], v201 offset:38912
	ds_read_b128 v[246:249], v201 offset:39936
	global_load_lds_dwordx4 v[212:213], off
	v_lshl_add_u64 v[212:213], s[2:3], 0, v[132:133]
	s_mov_b32 m0, s61
	s_nop 0
	global_load_lds_dwordx4 v[212:213], off
	s_waitcnt vmcnt(8)
	s_waitcnt lgkmcnt(0)
	s_barrier
	s_setprio 1
	s_waitcnt lgkmcnt(0)
	v_mfma_f32_16x16x32_bf16 v[124:127], v[144:147], v[214:217], v[124:127]
	v_mfma_f32_16x16x32_bf16 v[120:123], v[152:155], v[214:217], v[120:123]
	v_mfma_f32_16x16x32_bf16 v[108:111], v[144:147], v[226:229], v[108:111]
	v_mfma_f32_16x16x32_bf16 v[104:107], v[152:155], v[226:229], v[104:107]
	v_mfma_f32_16x16x32_bf16 v[92:95], v[144:147], v[234:237], v[92:95]
	v_mfma_f32_16x16x32_bf16 v[88:91], v[152:155], v[234:237], v[88:91]
	v_mfma_f32_16x16x32_bf16 v[76:79], v[144:147], v[242:245], v[76:79]
	v_mfma_f32_16x16x32_bf16 v[72:75], v[152:155], v[242:245], v[72:75]
	v_mfma_f32_16x16x32_bf16 v[124:127], v[148:151], v[222:225], v[124:127]
	v_mfma_f32_16x16x32_bf16 v[120:123], v[156:159], v[222:225], v[120:123]
	v_mfma_f32_16x16x32_bf16 v[108:111], v[148:151], v[230:233], v[108:111]
	v_mfma_f32_16x16x32_bf16 v[104:107], v[156:159], v[230:233], v[104:107]
	v_mfma_f32_16x16x32_bf16 v[92:95], v[148:151], v[238:241], v[92:95]
	v_mfma_f32_16x16x32_bf16 v[88:91], v[156:159], v[238:241], v[88:91]
	v_mfma_f32_16x16x32_bf16 v[76:79], v[148:151], v[246:249], v[76:79]
	v_mfma_f32_16x16x32_bf16 v[72:75], v[156:159], v[246:249], v[72:75]
	s_setprio 0
	s_setprio 1
	v_mfma_f32_16x16x32_bf16 v[116:119], v[160:163], v[214:217], v[116:119]
	v_mfma_f32_16x16x32_bf16 v[112:115], v[168:171], v[214:217], v[112:115]
	v_mfma_f32_16x16x32_bf16 v[100:103], v[160:163], v[226:229], v[100:103]
	v_mfma_f32_16x16x32_bf16 v[96:99], v[168:171], v[226:229], v[96:99]
	v_mfma_f32_16x16x32_bf16 v[84:87], v[160:163], v[234:237], v[84:87]
	v_mfma_f32_16x16x32_bf16 v[80:83], v[168:171], v[234:237], v[80:83]
	v_mfma_f32_16x16x32_bf16 v[68:71], v[160:163], v[242:245], v[68:71]
	v_mfma_f32_16x16x32_bf16 v[64:67], v[168:171], v[242:245], v[64:67]
	v_mfma_f32_16x16x32_bf16 v[116:119], v[164:167], v[222:225], v[116:119]
	v_mfma_f32_16x16x32_bf16 v[112:115], v[172:175], v[222:225], v[112:115]
	v_mfma_f32_16x16x32_bf16 v[100:103], v[164:167], v[230:233], v[100:103]
	v_mfma_f32_16x16x32_bf16 v[96:99], v[172:175], v[230:233], v[96:99]
	v_mfma_f32_16x16x32_bf16 v[84:87], v[164:167], v[238:241], v[84:87]
	v_mfma_f32_16x16x32_bf16 v[80:83], v[172:175], v[238:241], v[80:83]
	v_mfma_f32_16x16x32_bf16 v[68:71], v[164:167], v[246:249], v[68:71]
	v_mfma_f32_16x16x32_bf16 v[64:67], v[172:175], v[246:249], v[64:67]
	s_setprio 0
	s_barrier
; #define PG8_STAGE(bufoff, gbase, voff) do { _Pragma("unroll") for (int _i = 0; _i < 2; ++_i) \
;         __builtin_amdgcn_global_load_lds((const unsigned*)((const char*)(gbase) + (voff)[_i]), (PG8_LAS unsigned*)(lds + (bufoff) + ldsw + _i * 8192), 16, 0, 0); } while (0)
; #define PG8_LDA(dst, b, h) do { _Pragma("unroll") for (int m = 0; m < 4; ++m) _Pragma("unroll") for (int k = 0; k < 2; ++k) dst[m][k] = *(const PG8_LAS bf16x8*)(lds + PG8_SA(b, h) + aoff + m * 2048 + k * 1024); } while (0)
; #define PG8_MMA(ai, bj, At, Bt) do { __builtin_amdgcn_s_setprio(1); _Pragma("unroll") for (int m = 0; m < 4; ++m) _Pragma("unroll") for (int n = 0; n < 2; ++n) _Pragma("unroll") for (int k = 0; k < 2; ++k) \
;         acc[ai][bj][m][n] = __builtin_amdgcn_mfma_f32_16x16x32_bf16(Bt[n][k], At[m][k], acc[ai][bj][m][n], 0, 0, 0); __builtin_amdgcn_s_setprio(0); } while (0)
; #define PG8_WAIT_V(n) asm volatile("s_waitcnt vmcnt(" #n ")" ::: "memory")
; #define PG8_WAIT_L(n) asm volatile("s_waitcnt lgkmcnt(" #n ")" ::: "memory")
; #define PG8_BAR __builtin_amdgcn_s_barrier()
; #define PG8_SCHED __builtin_amdgcn_sched_barrier(0)
;     __device__ __forceinline__ void operator()(Acc& acc, const Unit& u, int wr, int wc, int fr, int fq, PG8_LAS unsigned char* xl) const {
;     ...
;             for (int m = 0; m < 4; ++m) { const int rl = ai * HALF + wr * 64 + m * 16 + fr; const size_t off = (size_t)(u.r0 + rl) * DM + col; float s = 0.f;
; #pragma unroll
;                 for (int bj = 0; bj < 2; ++bj) {
;                     f32x4 b0, b1; unpack8(*(const u32x4*)(base + off + bj * HALF), b0, b1);
; template <class Epi, class Sched>
; __device__ __forceinline__ void gemm_phase(PG8_LAS unsigned char* lds, PG8_LAS unsigned char* xl, const Gemm g, const Sched& S, const Epi& E) {
;     ...
;             PG8_LDA(At, 1, 1); PG8_STAGE(PG8_SB(1, 0), b3, voffB); PG8_STAGE(PG8_SB(1, 1), b3 + hsB, voffB); PG8_STAGE(PG8_SA(1, 0), a3, voffA);
;             PG8_WAIT_V(8); PG8_WAIT_L(0); PG8_BAR; PG8_MMA(1, 0, At, B0); PG8_MMA(1, 1, At, B1); PG8_BAR; PG8_SCHED;
;         }
;         if (wr == 0) PG8_BAR;
;         E(acc, cur, wr, wc, fr, fq, xl);
	s_add_i32 s2, s68, s42
	v_lshl_add_u64 v[176:177], v[176:177], 0, s[22:23]
	s_mov_b32 m0, s2
	ds_read_b128 v[214:217], v201 offset:49152
	ds_read_b128 v[222:225], v201 offset:50176
	ds_read_b128 v[226:229], v201 offset:51200
	ds_read_b128 v[230:233], v201 offset:52224
	ds_read_b128 v[234:237], v201 offset:53248
	ds_read_b128 v[238:241], v201 offset:54272
	ds_read_b128 v[242:245], v201 offset:55296
	ds_read_b128 v[246:249], v201 offset:56320
	global_load_lds_dwordx4 v[176:177], off
	s_add_i32 m0, s2, 0x2000
	s_add_u32 s2, s50, 0xb0080
	v_lshl_add_u64 v[176:177], v[218:219], 0, s[22:23]
	s_addc_u32 s3, s51, 0
	s_add_i32 s50, s81, s42
	global_load_lds_dwordx4 v[176:177], off
	v_lshl_add_u64 v[176:177], s[2:3], 0, v[130:131]
	s_mov_b32 m0, s50
	s_nop 0
	global_load_lds_dwordx4 v[176:177], off
	v_lshl_add_u64 v[176:177], s[2:3], 0, v[134:135]
	s_add_i32 m0, s50, 0x2000
	s_nop 0
	global_load_lds_dwordx4 v[176:177], off
	v_lshl_add_u64 v[176:177], v[250:251], 0, s[22:23]
	s_mov_b32 m0, s65
	s_nop 0
	global_load_lds_dwordx4 v[176:177], off
	v_lshl_add_u64 v[176:177], v[252:253], 0, s[22:23]
	s_mov_b32 m0, s66
	s_nop 0
	global_load_lds_dwordx4 v[176:177], off
	s_waitcnt vmcnt(8)
	s_waitcnt lgkmcnt(0)
	s_barrier
	s_setprio 1
	s_waitcnt lgkmcnt(0)
	v_mfma_f32_16x16x32_bf16 v[60:63], v[144:147], v[214:217], v[60:63]
	v_mfma_f32_16x16x32_bf16 v[56:59], v[152:155], v[214:217], v[56:59]
	v_mfma_f32_16x16x32_bf16 v[44:47], v[144:147], v[226:229], v[44:47]
	v_mfma_f32_16x16x32_bf16 v[40:43], v[152:155], v[226:229], v[40:43]
	v_mfma_f32_16x16x32_bf16 v[28:31], v[144:147], v[234:237], v[28:31]
	v_mfma_f32_16x16x32_bf16 v[24:27], v[152:155], v[234:237], v[24:27]
	v_mfma_f32_16x16x32_bf16 v[12:15], v[144:147], v[242:245], v[12:15]
	v_mfma_f32_16x16x32_bf16 v[8:11], v[152:155], v[242:245], v[8:11]
	v_mfma_f32_16x16x32_bf16 v[60:63], v[148:151], v[222:225], v[60:63]
	v_mfma_f32_16x16x32_bf16 v[56:59], v[156:159], v[222:225], v[56:59]
	v_mfma_f32_16x16x32_bf16 v[44:47], v[148:151], v[230:233], v[44:47]
	v_mfma_f32_16x16x32_bf16 v[40:43], v[156:159], v[230:233], v[40:43]
	v_mfma_f32_16x16x32_bf16 v[28:31], v[148:151], v[238:241], v[28:31]
	v_mfma_f32_16x16x32_bf16 v[24:27], v[156:159], v[238:241], v[24:27]
	v_mfma_f32_16x16x32_bf16 v[12:15], v[148:151], v[246:249], v[12:15]
	v_mfma_f32_16x16x32_bf16 v[8:11], v[156:159], v[246:249], v[8:11]
	s_setprio 0
	s_setprio 1
	v_mfma_f32_16x16x32_bf16 v[52:55], v[160:163], v[214:217], v[52:55]
	v_mfma_f32_16x16x32_bf16 v[48:51], v[168:171], v[214:217], v[48:51]
	v_mfma_f32_16x16x32_bf16 v[36:39], v[160:163], v[226:229], v[36:39]
	v_mfma_f32_16x16x32_bf16 v[32:35], v[168:171], v[226:229], v[32:35]
	v_mfma_f32_16x16x32_bf16 v[20:23], v[160:163], v[234:237], v[20:23]
	v_mfma_f32_16x16x32_bf16 v[16:19], v[168:171], v[234:237], v[16:19]
	v_mfma_f32_16x16x32_bf16 v[4:7], v[160:163], v[242:245], v[4:7]
	v_mfma_f32_16x16x32_bf16 v[0:3], v[168:171], v[242:245], v[0:3]
	v_mfma_f32_16x16x32_bf16 v[52:55], v[164:167], v[222:225], v[52:55]
	v_mfma_f32_16x16x32_bf16 v[48:51], v[172:175], v[222:225], v[48:51]
	v_mfma_f32_16x16x32_bf16 v[36:39], v[164:167], v[230:233], v[36:39]
	v_mfma_f32_16x16x32_bf16 v[32:35], v[172:175], v[230:233], v[32:35]
	v_mfma_f32_16x16x32_bf16 v[20:23], v[164:167], v[238:241], v[20:23]
	v_mfma_f32_16x16x32_bf16 v[16:19], v[172:175], v[238:241], v[16:19]
	v_mfma_f32_16x16x32_bf16 v[4:7], v[164:167], v[246:249], v[4:7]
	v_mfma_f32_16x16x32_bf16 v[0:3], v[172:175], v[246:249], v[0:3]
	s_setprio 0
	s_barrier
	s_add_i32 s80, s80, 2
	s_add_u32 s78, s78, 0x100
	s_addc_u32 s79, s79, 0
	s_cmp_gt_u32 s80, 41
	s_mov_b64 s[2:3], s[48:49]
	s_cbranch_scc0 .LBB0_942
	v_add_u32_e32 v252, s76, v183
	v_ashrrev_i32_e32 v253, 31, v252
	v_add_u32_e32 v248, s75, v180
	v_ashrrev_i32_e32 v249, 31, v248
	v_lshlrev_b64 v[248:249], 10, v[248:249]
	v_lshl_add_u64 v[248:249], v[248:249], 0, v[252:253]
	v_lshl_add_u64 v[248:249], v[248:249], 1, s[18:19]
	global_load_dwordx4 v[224:227], v[248:249], off
	global_load_dwordx4 v[228:231], v[248:249], off offset:256
	v_add_u32_e32 v248, s75, v184
	v_ashrrev_i32_e32 v249, 31, v248
	v_lshlrev_b64 v[248:249], 10, v[248:249]
	v_lshl_add_u64 v[248:249], v[248:249], 0, v[252:253]
	v_lshl_add_u64 v[248:249], v[248:249], 1, s[18:19]
	global_load_dwordx4 v[232:235], v[248:249], off
	global_load_dwordx4 v[236:239], v[248:249], off offset:256
	v_add_u32_e32 v248, s75, v185
	v_ashrrev_i32_e32 v249, 31, v248
	v_lshlrev_b64 v[248:249], 10, v[248:249]
	v_lshl_add_u64 v[248:249], v[248:249], 0, v[252:253]
	v_lshl_add_u64 v[248:249], v[248:249], 1, s[18:19]
	global_load_dwordx4 v[240:243], v[248:249], off
	global_load_dwordx4 v[244:247], v[248:249], off offset:256
	s_and_b64 vcc, exec, s[26:27]
	s_cbranch_vccz .LBB0_945
	s_barrier
;     __device__ __forceinline__ void operator()(Acc& acc, const Unit& u, int wr, int wc, int fr, int fq, PG8_LAS unsigned char* xl) const {
;     ...
;             for (int m = 0; m < 4; ++m) { const int rl = ai * HALF + wr * 64 + m * 16 + fr; const size_t off = (size_t)(u.r0 + rl) * DM + col; float s = 0.f;
; #pragma unroll
;                 for (int bj = 0; bj < 2; ++bj) {
;                     f32x4 b0, b1; unpack8(*(const u32x4*)(base + off + bj * HALF), b0, b1);
;                     const f32x4 v0 = acc[ai][bj][m][0] + b0, v1 = acc[ai][bj][m][1] + b1;
;                     acc[ai][bj][m][0] = v0; acc[ai][bj][m][1] = v1;
;                     s += (v0[0] * v0[0] + v0[1] * v0[1]) + (v0[2] * v0[2] + v0[3] * v0[3]) + (v1[0] * v1[0] + v1[1] * v1[1]) + (v1[2] * v1[2] + v1[3] * v1[3]); }
;                 s += __shfl_xor(s, 16); s += __shfl_xor(s, 32);
;                 if (fq == 0) X[rl * 4 + wc] = s; }
.LBB0_945:
	v_add_u32_e32 v144, s75, v180
	v_ashrrev_i32_e32 v145, 31, v144
	v_add_u32_e32 v146, s76, v183
	v_lshlrev_b64 v[148:149], 11, v[144:145]
	v_ashrrev_i32_e32 v147, 31, v146
	v_lshl_add_u64 v[148:149], s[18:19], 0, v[148:149]
	v_lshl_add_u64 v[152:153], v[146:147], 1, v[148:149]
	s_nop 0
	s_nop 0
	s_nop 0
	v_and_b32_e32 v157, 64, v202
	v_xor_b32_e32 v156, 16, v202
	v_add_u32_e32 v164, 64, v157
	v_cmp_lt_i32_e32 vcc, v156, v164
	s_waitcnt vmcnt(4) lgkmcnt(0)
	v_and_b32_e32 v157, 0xffff0000, v224
	v_cndmask_b32_e32 v156, v202, v156, vcc
	v_lshlrev_b32_e32 v213, 2, v156
	v_lshlrev_b32_e32 v156, 16, v224
	v_lshlrev_b32_e32 v148, 16, v225
	v_and_b32_e32 v149, 0xffff0000, v225
	v_lshlrev_b32_e32 v160, 16, v228
	v_and_b32_e32 v161, 0xffff0000, v228
	v_lshlrev_b32_e32 v152, 16, v229
	v_and_b32_e32 v153, 0xffff0000, v229
	v_lshlrev_b32_e32 v158, 16, v226
	v_and_b32_e32 v159, 0xffff0000, v226
	v_lshlrev_b32_e32 v162, 16, v230
	v_and_b32_e32 v163, 0xffff0000, v230
	v_pk_add_f32 v[126:127], v[126:127], v[148:149]
	v_pk_add_f32 v[124:125], v[124:125], v[156:157]
	v_pk_add_f32 v[118:119], v[118:119], v[152:153]
	v_pk_add_f32 v[116:117], v[116:117], v[160:161]
	v_lshlrev_b32_e32 v150, 16, v227
	v_and_b32_e32 v151, 0xffff0000, v227
	v_lshlrev_b32_e32 v154, 16, v231
	v_and_b32_e32 v155, 0xffff0000, v231
	v_add_u32_e32 v248, s75, v186
	v_ashrrev_i32_e32 v249, 31, v248
	v_lshlrev_b64 v[248:249], 10, v[248:249]
	v_lshl_add_u64 v[248:249], v[248:249], 0, v[252:253]
	v_lshl_add_u64 v[248:249], v[248:249], 1, s[18:19]
	global_load_dwordx4 v[224:227], v[248:249], off
	global_load_dwordx4 v[228:231], v[248:249], off offset:256
	v_pk_add_f32 v[120:121], v[120:121], v[158:159]
	v_pk_add_f32 v[112:113], v[112:113], v[162:163]
	v_mul_f32_e32 v148, v125, v125
	v_mul_f32_e32 v149, v127, v127
	v_mul_f32_e32 v152, v117, v117
	v_mul_f32_e32 v153, v119, v119
	v_pk_add_f32 v[122:123], v[122:123], v[150:151]
	v_pk_add_f32 v[114:115], v[114:115], v[154:155]
	v_mul_f32_e32 v150, v121, v121
	v_mul_f32_e32 v154, v113, v113
	v_fmac_f32_e32 v148, v124, v124
	v_fmac_f32_e32 v149, v126, v126
	v_fmac_f32_e32 v152, v116, v116
	v_fmac_f32_e32 v153, v118, v118
	v_mul_f32_e32 v151, v123, v123
	v_mul_f32_e32 v155, v115, v115
	v_fmac_f32_e32 v150, v120, v120
	v_fmac_f32_e32 v154, v112, v112
	v_add_f32_e32 v148, v148, v149
	v_add_f32_e32 v149, v152, v153
	v_fmac_f32_e32 v151, v122, v122
	v_fmac_f32_e32 v155, v114, v114
	v_add_f32_e32 v148, v150, v148
	v_add_f32_e32 v149, v154, v149
	v_add_f32_e32 v148, v151, v148
	v_add_f32_e32 v149, v155, v149
	v_add_f32_e32 v148, v148, v149
	ds_bpermute_b32 v149, v213, v148
	v_xor_b32_e32 v150, 32, v202
	v_cmp_lt_i32_e32 vcc, v150, v164
	s_waitcnt lgkmcnt(0)
	v_add_f32_e32 v148, v148, v149
	v_cndmask_b32_e32 v150, v202, v150, vcc
	v_lshlrev_b32_e32 v214, 2, v150
	ds_bpermute_b32 v149, v214, v148
	s_and_saveexec_b64 s[2:3], s[8:9]
	s_cbranch_execz .LBB0_947
	s_waitcnt lgkmcnt(0)
	v_add_f32_e32 v148, v148, v149
	ds_write_b32 v203, v148
.LBB0_947:
	s_or_b64 exec, exec, s[2:3]
	v_add_u32_e32 v148, s75, v184
	s_waitcnt lgkmcnt(0)
	v_ashrrev_i32_e32 v149, 31, v148
	v_lshlrev_b64 v[150:151], 11, v[148:149]
	v_lshl_add_u64 v[150:151], s[18:19], 0, v[150:151]
	v_lshl_add_u64 v[154:155], v[146:147], 1, v[150:151]
	s_nop 0
	s_nop 0
	s_nop 0
	s_waitcnt vmcnt(4) lgkmcnt(0)
	v_lshlrev_b32_e32 v158, 16, v232
	v_and_b32_e32 v159, 0xffff0000, v232
	v_lshlrev_b32_e32 v150, 16, v233
	v_and_b32_e32 v151, 0xffff0000, v233
	v_lshlrev_b32_e32 v162, 16, v236
	v_and_b32_e32 v163, 0xffff0000, v236
	v_lshlrev_b32_e32 v154, 16, v237
	v_and_b32_e32 v155, 0xffff0000, v237
	v_lshlrev_b32_e32 v160, 16, v234
	v_and_b32_e32 v161, 0xffff0000, v234
	v_lshlrev_b32_e32 v164, 16, v238
	v_and_b32_e32 v165, 0xffff0000, v238
	v_pk_add_f32 v[110:111], v[110:111], v[150:151]
	v_pk_add_f32 v[108:109], v[108:109], v[158:159]
	v_pk_add_f32 v[102:103], v[102:103], v[154:155]
	v_pk_add_f32 v[100:101], v[100:101], v[162:163]
	v_lshlrev_b32_e32 v152, 16, v235
	v_and_b32_e32 v153, 0xffff0000, v235
	v_lshlrev_b32_e32 v156, 16, v239
	v_and_b32_e32 v157, 0xffff0000, v239
	v_add_u32_e32 v248, s75, v187
	v_ashrrev_i32_e32 v249, 31, v248
	v_lshlrev_b64 v[248:249], 10, v[248:249]
	v_lshl_add_u64 v[248:249], v[248:249], 0, v[252:253]
	v_lshl_add_u64 v[248:249], v[248:249], 1, s[18:19]
	global_load_dwordx4 v[232:235], v[248:249], off
	global_load_dwordx4 v[236:239], v[248:249], off offset:256
	v_pk_add_f32 v[104:105], v[104:105], v[160:161]
	v_pk_add_f32 v[96:97], v[96:97], v[164:165]
	v_mul_f32_e32 v150, v109, v109
	v_mul_f32_e32 v151, v111, v111
	v_mul_f32_e32 v154, v101, v101
	v_mul_f32_e32 v155, v103, v103
	v_pk_add_f32 v[106:107], v[106:107], v[152:153]
	v_pk_add_f32 v[98:99], v[98:99], v[156:157]
	v_mul_f32_e32 v152, v105, v105
	v_mul_f32_e32 v156, v97, v97
	v_fmac_f32_e32 v150, v108, v108
	v_fmac_f32_e32 v151, v110, v110
	v_fmac_f32_e32 v154, v100, v100
	v_fmac_f32_e32 v155, v102, v102
	v_mul_f32_e32 v153, v107, v107
	v_mul_f32_e32 v157, v99, v99
	v_fmac_f32_e32 v152, v104, v104
	v_fmac_f32_e32 v156, v96, v96
	v_add_f32_e32 v150, v150, v151
	v_add_f32_e32 v151, v154, v155
	v_fmac_f32_e32 v153, v106, v106
	v_fmac_f32_e32 v157, v98, v98
	v_add_f32_e32 v150, v152, v150
	v_add_f32_e32 v151, v156, v151
	v_add_f32_e32 v150, v153, v150
	v_add_f32_e32 v151, v157, v151
	v_add_f32_e32 v150, v150, v151
	ds_bpermute_b32 v151, v213, v150
	s_waitcnt lgkmcnt(0)
	v_add_f32_e32 v150, v150, v151
	ds_bpermute_b32 v151, v214, v150
	s_and_saveexec_b64 s[2:3], s[8:9]
	s_cbranch_execz .LBB0_949
	s_waitcnt lgkmcnt(0)
	v_add_f32_e32 v150, v150, v151
	ds_write_b32 v204, v150
;     __device__ __forceinline__ void operator()(Acc& acc, const Unit& u, int wr, int wc, int fr, int fq, PG8_LAS unsigned char* xl) const {
;     ...
;             for (int m = 0; m < 4; ++m) { const int rl = ai * HALF + wr * 64 + m * 16 + fr; const size_t off = (size_t)(u.r0 + rl) * DM + col; float s = 0.f;
; #pragma unroll
;                 for (int bj = 0; bj < 2; ++bj) {
;                     f32x4 b0, b1; unpack8(*(const u32x4*)(base + off + bj * HALF), b0, b1);
;                     const f32x4 v0 = acc[ai][bj][m][0] + b0, v1 = acc[ai][bj][m][1] + b1;
;                     acc[ai][bj][m][0] = v0; acc[ai][bj][m][1] = v1;
;                     s += (v0[0] * v0[0] + v0[1] * v0[1]) + (v0[2] * v0[2] + v0[3] * v0[3]) + (v1[0] * v1[0] + v1[1] * v1[1]) + (v1[2] * v1[2] + v1[3] * v1[3]); }
;                 s += __shfl_xor(s, 16); s += __shfl_xor(s, 32);
;                 if (fq == 0) X[rl * 4 + wc] = s; }
.LBB0_949:
	s_or_b64 exec, exec, s[2:3]
	v_add_u32_e32 v150, s75, v185
	s_waitcnt lgkmcnt(0)
	v_ashrrev_i32_e32 v151, 31, v150
	v_lshlrev_b64 v[152:153], 11, v[150:151]
	v_lshl_add_u64 v[152:153], s[18:19], 0, v[152:153]
	v_lshl_add_u64 v[156:157], v[146:147], 1, v[152:153]
	s_nop 0
	s_nop 0
	s_nop 0
	s_waitcnt vmcnt(4) lgkmcnt(0)
	v_lshlrev_b32_e32 v160, 16, v240
	v_and_b32_e32 v161, 0xffff0000, v240
	v_lshlrev_b32_e32 v152, 16, v241
	v_and_b32_e32 v153, 0xffff0000, v241
	v_lshlrev_b32_e32 v164, 16, v244
	v_and_b32_e32 v165, 0xffff0000, v244
	v_lshlrev_b32_e32 v156, 16, v245
	v_and_b32_e32 v157, 0xffff0000, v245
	v_lshlrev_b32_e32 v162, 16, v242
	v_and_b32_e32 v163, 0xffff0000, v242
	v_lshlrev_b32_e32 v166, 16, v246
	v_and_b32_e32 v167, 0xffff0000, v246
	v_pk_add_f32 v[94:95], v[94:95], v[152:153]
	v_pk_add_f32 v[92:93], v[92:93], v[160:161]
	v_pk_add_f32 v[86:87], v[86:87], v[156:157]
	v_pk_add_f32 v[84:85], v[84:85], v[164:165]
	v_lshlrev_b32_e32 v154, 16, v243
	v_and_b32_e32 v155, 0xffff0000, v243
	v_lshlrev_b32_e32 v158, 16, v247
	v_and_b32_e32 v159, 0xffff0000, v247
	v_add_u32_e32 v248, s75, v188
	v_ashrrev_i32_e32 v249, 31, v248
	v_lshlrev_b64 v[248:249], 10, v[248:249]
	v_lshl_add_u64 v[248:249], v[248:249], 0, v[252:253]
	v_lshl_add_u64 v[248:249], v[248:249], 1, s[18:19]
	global_load_dwordx4 v[240:243], v[248:249], off
	global_load_dwordx4 v[244:247], v[248:249], off offset:256
	v_pk_add_f32 v[88:89], v[88:89], v[162:163]
	v_pk_add_f32 v[80:81], v[80:81], v[166:167]
	v_mul_f32_e32 v152, v93, v93
	v_mul_f32_e32 v153, v95, v95
	v_mul_f32_e32 v156, v85, v85
	v_mul_f32_e32 v157, v87, v87
	v_pk_add_f32 v[90:91], v[90:91], v[154:155]
	v_pk_add_f32 v[82:83], v[82:83], v[158:159]
	v_mul_f32_e32 v154, v89, v89
	v_mul_f32_e32 v158, v81, v81
	v_fmac_f32_e32 v152, v92, v92
	v_fmac_f32_e32 v153, v94, v94
	v_fmac_f32_e32 v156, v84, v84
	v_fmac_f32_e32 v157, v86, v86
	v_mul_f32_e32 v155, v91, v91
	v_mul_f32_e32 v159, v83, v83
	v_fmac_f32_e32 v154, v88, v88
	v_fmac_f32_e32 v158, v80, v80
	v_add_f32_e32 v152, v152, v153
	v_add_f32_e32 v153, v156, v157
	v_fmac_f32_e32 v155, v90, v90
	v_fmac_f32_e32 v159, v82, v82
	v_add_f32_e32 v152, v154, v152
	v_add_f32_e32 v153, v158, v153
	v_add_f32_e32 v152, v155, v152
	v_add_f32_e32 v153, v159, v153
	v_add_f32_e32 v152, v152, v153
	ds_bpermute_b32 v153, v213, v152
	s_waitcnt lgkmcnt(0)
	v_add_f32_e32 v152, v152, v153
	ds_bpermute_b32 v153, v214, v152
	s_and_saveexec_b64 s[2:3], s[8:9]
	s_cbranch_execz .LBB0_951
	s_waitcnt lgkmcnt(0)
	v_add_f32_e32 v152, v152, v153
	ds_write_b32 v205, v152
.LBB0_951:
	s_or_b64 exec, exec, s[2:3]
	v_add_u32_e32 v152, s75, v186
	s_waitcnt lgkmcnt(0)
	v_ashrrev_i32_e32 v153, 31, v152
	v_lshlrev_b64 v[154:155], 11, v[152:153]
	v_lshl_add_u64 v[154:155], s[18:19], 0, v[154:155]
	v_lshl_add_u64 v[158:159], v[146:147], 1, v[154:155]
	s_nop 0
	s_nop 0
	s_nop 0
	s_waitcnt vmcnt(4) lgkmcnt(0)
	v_lshlrev_b32_e32 v162, 16, v224
	v_and_b32_e32 v163, 0xffff0000, v224
	v_lshlrev_b32_e32 v154, 16, v225
	v_and_b32_e32 v155, 0xffff0000, v225
	v_lshlrev_b32_e32 v166, 16, v228
	v_and_b32_e32 v167, 0xffff0000, v228
	v_lshlrev_b32_e32 v158, 16, v229
	v_and_b32_e32 v159, 0xffff0000, v229
	v_lshlrev_b32_e32 v164, 16, v226
	v_and_b32_e32 v165, 0xffff0000, v226
	v_lshlrev_b32_e32 v168, 16, v230
	v_and_b32_e32 v169, 0xffff0000, v230
	v_pk_add_f32 v[78:79], v[78:79], v[154:155]
	v_pk_add_f32 v[76:77], v[76:77], v[162:163]
	v_pk_add_f32 v[70:71], v[70:71], v[158:159]
	v_pk_add_f32 v[68:69], v[68:69], v[166:167]
	v_lshlrev_b32_e32 v156, 16, v227
	v_and_b32_e32 v157, 0xffff0000, v227
	v_lshlrev_b32_e32 v160, 16, v231
	v_and_b32_e32 v161, 0xffff0000, v231
	v_add_u32_e32 v248, s75, v189
	v_ashrrev_i32_e32 v249, 31, v248
	v_lshlrev_b64 v[248:249], 10, v[248:249]
	v_lshl_add_u64 v[248:249], v[248:249], 0, v[252:253]
	v_lshl_add_u64 v[248:249], v[248:249], 1, s[18:19]
	global_load_dwordx4 v[224:227], v[248:249], off
	global_load_dwordx4 v[228:231], v[248:249], off offset:256
	v_pk_add_f32 v[72:73], v[72:73], v[164:165]
	v_pk_add_f32 v[64:65], v[64:65], v[168:169]
	v_mul_f32_e32 v154, v77, v77
	v_mul_f32_e32 v155, v79, v79
	v_mul_f32_e32 v158, v69, v69
	v_mul_f32_e32 v159, v71, v71
	v_pk_add_f32 v[74:75], v[74:75], v[156:157]
	v_pk_add_f32 v[66:67], v[66:67], v[160:161]
	v_mul_f32_e32 v156, v73, v73
	v_mul_f32_e32 v160, v65, v65
	v_fmac_f32_e32 v154, v76, v76
	v_fmac_f32_e32 v155, v78, v78
	v_fmac_f32_e32 v158, v68, v68
	v_fmac_f32_e32 v159, v70, v70
	v_mul_f32_e32 v157, v75, v75
	v_mul_f32_e32 v161, v67, v67
	v_fmac_f32_e32 v156, v72, v72
	v_fmac_f32_e32 v160, v64, v64
	v_add_f32_e32 v154, v154, v155
	v_add_f32_e32 v155, v158, v159
	v_fmac_f32_e32 v157, v74, v74
	v_fmac_f32_e32 v161, v66, v66
	v_add_f32_e32 v154, v156, v154
	v_add_f32_e32 v155, v160, v155
	v_add_f32_e32 v154, v157, v154
	v_add_f32_e32 v155, v161, v155
	v_add_f32_e32 v154, v154, v155
	ds_bpermute_b32 v155, v213, v154
	s_waitcnt lgkmcnt(0)
	v_add_f32_e32 v154, v154, v155
	ds_bpermute_b32 v155, v214, v154
	s_and_saveexec_b64 s[2:3], s[8:9]
	s_cbranch_execz .LBB0_953
	s_waitcnt lgkmcnt(0)
	v_add_f32_e32 v154, v154, v155
	ds_write_b32 v206, v154
;     __device__ __forceinline__ void operator()(Acc& acc, const Unit& u, int wr, int wc, int fr, int fq, PG8_LAS unsigned char* xl) const {
;     ...
;             for (int m = 0; m < 4; ++m) { const int rl = ai * HALF + wr * 64 + m * 16 + fr; const size_t off = (size_t)(u.r0 + rl) * DM + col; float s = 0.f;
; #pragma unroll
;                 for (int bj = 0; bj < 2; ++bj) {
;                     f32x4 b0, b1; unpack8(*(const u32x4*)(base + off + bj * HALF), b0, b1);
;                     const f32x4 v0 = acc[ai][bj][m][0] + b0, v1 = acc[ai][bj][m][1] + b1;
;                     acc[ai][bj][m][0] = v0; acc[ai][bj][m][1] = v1;
;                     s += (v0[0] * v0[0] + v0[1] * v0[1]) + (v0[2] * v0[2] + v0[3] * v0[3]) + (v1[0] * v1[0] + v1[1] * v1[1]) + (v1[2] * v1[2] + v1[3] * v1[3]); }
;                 s += __shfl_xor(s, 16); s += __shfl_xor(s, 32);
;                 if (fq == 0) X[rl * 4 + wc] = s; }
.LBB0_953:
	s_or_b64 exec, exec, s[2:3]
	v_add_u32_e32 v154, s75, v187
	s_waitcnt lgkmcnt(0)
	v_ashrrev_i32_e32 v155, 31, v154
	v_lshlrev_b64 v[156:157], 11, v[154:155]
	v_lshl_add_u64 v[156:157], s[18:19], 0, v[156:157]
	v_lshl_add_u64 v[160:161], v[146:147], 1, v[156:157]
	s_nop 0
	s_nop 0
	s_nop 0
	s_waitcnt vmcnt(4) lgkmcnt(0)
	v_lshlrev_b32_e32 v164, 16, v232
	v_and_b32_e32 v165, 0xffff0000, v232
	v_lshlrev_b32_e32 v156, 16, v233
	v_and_b32_e32 v157, 0xffff0000, v233
	v_lshlrev_b32_e32 v168, 16, v236
	v_and_b32_e32 v169, 0xffff0000, v236
	v_lshlrev_b32_e32 v160, 16, v237
	v_and_b32_e32 v161, 0xffff0000, v237
	v_lshlrev_b32_e32 v166, 16, v234
	v_and_b32_e32 v167, 0xffff0000, v234
	v_lshlrev_b32_e32 v170, 16, v238
	v_and_b32_e32 v171, 0xffff0000, v238
	v_pk_add_f32 v[62:63], v[62:63], v[156:157]
	v_pk_add_f32 v[60:61], v[60:61], v[164:165]
	v_pk_add_f32 v[54:55], v[54:55], v[160:161]
	v_pk_add_f32 v[52:53], v[52:53], v[168:169]
	v_lshlrev_b32_e32 v158, 16, v235
	v_and_b32_e32 v159, 0xffff0000, v235
	v_lshlrev_b32_e32 v162, 16, v239
	v_and_b32_e32 v163, 0xffff0000, v239
	v_add_u32_e32 v248, s75, v190
	v_ashrrev_i32_e32 v249, 31, v248
	v_lshlrev_b64 v[248:249], 10, v[248:249]
	v_lshl_add_u64 v[248:249], v[248:249], 0, v[252:253]
	v_lshl_add_u64 v[248:249], v[248:249], 1, s[18:19]
	global_load_dwordx4 v[232:235], v[248:249], off
	global_load_dwordx4 v[236:239], v[248:249], off offset:256
	v_pk_add_f32 v[56:57], v[56:57], v[166:167]
	v_pk_add_f32 v[48:49], v[48:49], v[170:171]
	v_mul_f32_e32 v156, v61, v61
	v_mul_f32_e32 v157, v63, v63
	v_mul_f32_e32 v160, v53, v53
	v_mul_f32_e32 v161, v55, v55
	v_pk_add_f32 v[58:59], v[58:59], v[158:159]
	v_pk_add_f32 v[50:51], v[50:51], v[162:163]
	v_mul_f32_e32 v158, v57, v57
	v_mul_f32_e32 v162, v49, v49
	v_fmac_f32_e32 v156, v60, v60
	v_fmac_f32_e32 v157, v62, v62
	v_fmac_f32_e32 v160, v52, v52
	v_fmac_f32_e32 v161, v54, v54
	v_mul_f32_e32 v159, v59, v59
	v_mul_f32_e32 v163, v51, v51
	v_fmac_f32_e32 v158, v56, v56
	v_fmac_f32_e32 v162, v48, v48
	v_add_f32_e32 v156, v156, v157
	v_add_f32_e32 v157, v160, v161
	v_fmac_f32_e32 v159, v58, v58
	v_fmac_f32_e32 v163, v50, v50
	v_add_f32_e32 v156, v158, v156
	v_add_f32_e32 v157, v162, v157
	v_add_f32_e32 v156, v159, v156
	v_add_f32_e32 v157, v163, v157
	v_add_f32_e32 v156, v156, v157
	ds_bpermute_b32 v157, v213, v156
	s_waitcnt lgkmcnt(0)
	v_add_f32_e32 v156, v156, v157
	ds_bpermute_b32 v157, v214, v156
	s_and_saveexec_b64 s[2:3], s[8:9]
	s_cbranch_execz .LBB0_955
	s_waitcnt lgkmcnt(0)
	v_add_f32_e32 v156, v156, v157
	ds_write_b32 v207, v156
.LBB0_955:
	s_or_b64 exec, exec, s[2:3]
	v_add_u32_e32 v156, s75, v188
	s_waitcnt lgkmcnt(0)
	v_ashrrev_i32_e32 v157, 31, v156
	v_lshlrev_b64 v[158:159], 11, v[156:157]
	v_lshl_add_u64 v[158:159], s[18:19], 0, v[158:159]
	v_lshl_add_u64 v[162:163], v[146:147], 1, v[158:159]
	s_nop 0
	s_nop 0
	s_nop 0
	s_waitcnt vmcnt(4) lgkmcnt(0)
	v_lshlrev_b32_e32 v166, 16, v240
	v_and_b32_e32 v167, 0xffff0000, v240
	v_lshlrev_b32_e32 v158, 16, v241
	v_and_b32_e32 v159, 0xffff0000, v241
	v_lshlrev_b32_e32 v170, 16, v244
	v_and_b32_e32 v171, 0xffff0000, v244
	v_lshlrev_b32_e32 v162, 16, v245
	v_and_b32_e32 v163, 0xffff0000, v245
	v_lshlrev_b32_e32 v168, 16, v242
	v_and_b32_e32 v169, 0xffff0000, v242
	v_lshlrev_b32_e32 v172, 16, v246
	v_and_b32_e32 v173, 0xffff0000, v246
	v_pk_add_f32 v[46:47], v[46:47], v[158:159]
	v_pk_add_f32 v[44:45], v[44:45], v[166:167]
	v_pk_add_f32 v[38:39], v[38:39], v[162:163]
	v_pk_add_f32 v[36:37], v[36:37], v[170:171]
	v_lshlrev_b32_e32 v160, 16, v243
	v_and_b32_e32 v161, 0xffff0000, v243
	v_lshlrev_b32_e32 v164, 16, v247
	v_and_b32_e32 v165, 0xffff0000, v247
	v_pk_add_f32 v[40:41], v[40:41], v[168:169]
	v_pk_add_f32 v[32:33], v[32:33], v[172:173]
	v_mul_f32_e32 v158, v45, v45
	v_mul_f32_e32 v159, v47, v47
	v_mul_f32_e32 v162, v37, v37
	v_mul_f32_e32 v163, v39, v39
	v_pk_add_f32 v[42:43], v[42:43], v[160:161]
	v_pk_add_f32 v[34:35], v[34:35], v[164:165]
	v_mul_f32_e32 v160, v41, v41
	v_mul_f32_e32 v164, v33, v33
	v_fmac_f32_e32 v158, v44, v44
	v_fmac_f32_e32 v159, v46, v46
	v_fmac_f32_e32 v162, v36, v36
	v_fmac_f32_e32 v163, v38, v38
	v_mul_f32_e32 v161, v43, v43
	v_mul_f32_e32 v165, v35, v35
	v_fmac_f32_e32 v160, v40, v40
	v_fmac_f32_e32 v164, v32, v32
	v_add_f32_e32 v158, v158, v159
	v_add_f32_e32 v159, v162, v163
	v_fmac_f32_e32 v161, v42, v42
	v_fmac_f32_e32 v165, v34, v34
	v_add_f32_e32 v158, v160, v158
	v_add_f32_e32 v159, v164, v159
	v_add_f32_e32 v158, v161, v158
	v_add_f32_e32 v159, v165, v159
	v_add_f32_e32 v158, v158, v159
	ds_bpermute_b32 v159, v213, v158
	s_waitcnt lgkmcnt(0)
	v_add_f32_e32 v158, v158, v159
	ds_bpermute_b32 v159, v214, v158
	s_and_saveexec_b64 s[2:3], s[8:9]
	s_cbranch_execz .LBB0_957
	s_waitcnt lgkmcnt(0)
	v_add_f32_e32 v158, v158, v159
	ds_write_b32 v208, v158
;     __device__ __forceinline__ void operator()(Acc& acc, const Unit& u, int wr, int wc, int fr, int fq, PG8_LAS unsigned char* xl) const {
;     ...
;             for (int m = 0; m < 4; ++m) { const int rl = ai * HALF + wr * 64 + m * 16 + fr; const size_t off = (size_t)(u.r0 + rl) * DM + col; float s = 0.f;
; #pragma unroll
;                 for (int bj = 0; bj < 2; ++bj) {
;                     f32x4 b0, b1; unpack8(*(const u32x4*)(base + off + bj * HALF), b0, b1);
;                     const f32x4 v0 = acc[ai][bj][m][0] + b0, v1 = acc[ai][bj][m][1] + b1;
;                     acc[ai][bj][m][0] = v0; acc[ai][bj][m][1] = v1;
;                     s += (v0[0] * v0[0] + v0[1] * v0[1]) + (v0[2] * v0[2] + v0[3] * v0[3]) + (v1[0] * v1[0] + v1[1] * v1[1]) + (v1[2] * v1[2] + v1[3] * v1[3]); }
;                 s += __shfl_xor(s, 16); s += __shfl_xor(s, 32);
;                 if (fq == 0) X[rl * 4 + wc] = s; }
.LBB0_957:
	s_or_b64 exec, exec, s[2:3]
	v_add_u32_e32 v158, s75, v189
	s_waitcnt lgkmcnt(0)
	v_ashrrev_i32_e32 v159, 31, v158
	v_lshlrev_b64 v[160:161], 11, v[158:159]
	v_lshl_add_u64 v[160:161], s[18:19], 0, v[160:161]
	v_lshl_add_u64 v[164:165], v[146:147], 1, v[160:161]
	s_nop 0
	s_nop 0
	s_nop 0
	s_waitcnt vmcnt(2) lgkmcnt(0)
	v_lshlrev_b32_e32 v168, 16, v224
	v_and_b32_e32 v169, 0xffff0000, v224
	v_lshlrev_b32_e32 v160, 16, v225
	v_and_b32_e32 v161, 0xffff0000, v225
	v_lshlrev_b32_e32 v172, 16, v228
	v_and_b32_e32 v173, 0xffff0000, v228
	v_lshlrev_b32_e32 v164, 16, v229
	v_and_b32_e32 v165, 0xffff0000, v229
	v_lshlrev_b32_e32 v170, 16, v226
	v_and_b32_e32 v171, 0xffff0000, v226
	v_lshlrev_b32_e32 v174, 16, v230
	v_and_b32_e32 v175, 0xffff0000, v230
	v_pk_add_f32 v[30:31], v[30:31], v[160:161]
	v_pk_add_f32 v[28:29], v[28:29], v[168:169]
	v_pk_add_f32 v[22:23], v[22:23], v[164:165]
	v_pk_add_f32 v[20:21], v[20:21], v[172:173]
	v_lshlrev_b32_e32 v162, 16, v227
	v_and_b32_e32 v163, 0xffff0000, v227
	v_lshlrev_b32_e32 v166, 16, v231
	v_and_b32_e32 v167, 0xffff0000, v231
	v_pk_add_f32 v[24:25], v[24:25], v[170:171]
	v_pk_add_f32 v[16:17], v[16:17], v[174:175]
	v_mul_f32_e32 v160, v29, v29
	v_mul_f32_e32 v161, v31, v31
	v_mul_f32_e32 v164, v21, v21
	v_mul_f32_e32 v165, v23, v23
	v_pk_add_f32 v[26:27], v[26:27], v[162:163]
	v_pk_add_f32 v[18:19], v[18:19], v[166:167]
	v_mul_f32_e32 v162, v25, v25
	v_mul_f32_e32 v166, v17, v17
	v_fmac_f32_e32 v160, v28, v28
	v_fmac_f32_e32 v161, v30, v30
	v_fmac_f32_e32 v164, v20, v20
	v_fmac_f32_e32 v165, v22, v22
	v_mul_f32_e32 v163, v27, v27
	v_mul_f32_e32 v167, v19, v19
	v_fmac_f32_e32 v162, v24, v24
	v_fmac_f32_e32 v166, v16, v16
	v_add_f32_e32 v160, v160, v161
	v_add_f32_e32 v161, v164, v165
	v_fmac_f32_e32 v163, v26, v26
	v_fmac_f32_e32 v167, v18, v18
	v_add_f32_e32 v160, v162, v160
	v_add_f32_e32 v161, v166, v161
	v_add_f32_e32 v160, v163, v160
	v_add_f32_e32 v161, v167, v161
	v_add_f32_e32 v160, v160, v161
	ds_bpermute_b32 v161, v213, v160
	s_waitcnt lgkmcnt(0)
	v_add_f32_e32 v160, v160, v161
	ds_bpermute_b32 v161, v214, v160
	s_and_saveexec_b64 s[2:3], s[8:9]
	s_cbranch_execz .LBB0_959
	s_waitcnt lgkmcnt(0)
	v_add_f32_e32 v160, v160, v161
	ds_write_b32 v209, v160
.LBB0_959:
	s_or_b64 exec, exec, s[2:3]
	v_add_u32_e32 v160, s75, v190
	s_waitcnt lgkmcnt(0)
	v_ashrrev_i32_e32 v161, 31, v160
	v_lshlrev_b64 v[162:163], 11, v[160:161]
	v_lshl_add_u64 v[162:163], s[18:19], 0, v[162:163]
	v_lshl_add_u64 v[166:167], v[146:147], 1, v[162:163]
	s_nop 0
	s_nop 0
	s_nop 0
	s_waitcnt vmcnt(0) lgkmcnt(0)
	v_lshlrev_b32_e32 v170, 16, v232
	v_and_b32_e32 v171, 0xffff0000, v232
	v_lshlrev_b32_e32 v162, 16, v233
	v_and_b32_e32 v163, 0xffff0000, v233
	v_lshlrev_b32_e32 v216, 16, v236
	v_and_b32_e32 v217, 0xffff0000, v236
	v_lshlrev_b32_e32 v166, 16, v237
	v_and_b32_e32 v167, 0xffff0000, v237
	v_lshlrev_b32_e32 v172, 16, v234
	v_and_b32_e32 v173, 0xffff0000, v234
	v_lshlrev_b32_e32 v164, 16, v235
	v_and_b32_e32 v165, 0xffff0000, v235
	v_lshlrev_b32_e32 v218, 16, v238
	v_and_b32_e32 v219, 0xffff0000, v238
	v_lshlrev_b32_e32 v222, 16, v239
	v_and_b32_e32 v223, 0xffff0000, v239
	v_pk_add_f32 v[174:175], v[14:15], v[162:163]
	v_pk_add_f32 v[176:177], v[12:13], v[170:171]
	v_pk_add_f32 v[166:167], v[6:7], v[166:167]
	v_pk_add_f32 v[168:169], v[4:5], v[216:217]
	v_pk_add_f32 v[170:171], v[10:11], v[164:165]
	v_pk_add_f32 v[172:173], v[8:9], v[172:173]
	v_pk_add_f32 v[164:165], v[0:1], v[218:219]
	v_mul_f32_e32 v0, v177, v177
	v_mul_f32_e32 v1, v175, v175
	v_mul_f32_e32 v4, v169, v169
	v_mul_f32_e32 v5, v167, v167
	v_pk_add_f32 v[162:163], v[2:3], v[222:223]
	v_mul_f32_e32 v2, v173, v173
	v_mul_f32_e32 v6, v165, v165
	v_fmac_f32_e32 v0, v176, v176
	v_fmac_f32_e32 v1, v174, v174
	v_fmac_f32_e32 v4, v168, v168
	v_fmac_f32_e32 v5, v166, v166
	v_mul_f32_e32 v3, v171, v171
	v_mul_f32_e32 v7, v163, v163
	v_fmac_f32_e32 v2, v172, v172
	v_fmac_f32_e32 v6, v164, v164
	v_add_f32_e32 v0, v0, v1
	v_add_f32_e32 v1, v4, v5
	v_fmac_f32_e32 v3, v170, v170
	v_fmac_f32_e32 v7, v162, v162
	v_add_f32_e32 v0, v2, v0
	v_add_f32_e32 v1, v6, v1
	v_add_f32_e32 v0, v3, v0
	v_add_f32_e32 v1, v7, v1
	v_add_f32_e32 v0, v0, v1
	ds_bpermute_b32 v1, v213, v0
	s_waitcnt lgkmcnt(0)
	v_add_f32_e32 v0, v0, v1
	ds_bpermute_b32 v1, v214, v0
	s_and_saveexec_b64 s[2:3], s[8:9]
	s_cbranch_execz .LBB0_961
	s_waitcnt lgkmcnt(0)
	v_add_f32_e32 v0, v0, v1
	ds_write_b32 v210, v0
